# GEMM K-loops: 64 LDS-DMA loads use SGPR base + 32-bit lane offset (saddr form), their 64-bit VALU address adds removed from the load segments
# baseline (speedup 1.0000x reference)
.LBB0_61:
	s_waitcnt lgkmcnt(0)
	s_add_u32 s12, s12, 0x5720000
	s_addc_u32 s13, s13, 0
	s_lshl_b32 s16, s16, 5
	s_and_b32 s29, s16, 0x60
	s_add_i32 m0, s27, 0x18000
	v_lshl_add_u64 v[6:7], v[6:7], 0, s[8:9]
	s_lshl_b32 s28, s15, 13
	s_lshl_b32 s30, s29, 7
	s_waitcnt vmcnt(2)
	s_barrier
	global_load_lds_dwordx4 v[6:7], off
	v_lshl_add_u64 v[4:5], v[4:5], 0, s[8:9]
	s_add_i32 m0, s27, 0x1a000
	s_add_i32 s48, s27, 0x8000
	s_add_i32 s49, s27, 0xa000
	global_load_lds_dwordx4 v[4:5], off
	v_lshl_add_u64 v[0:1], v[0:1], 0, s[8:9]
	s_mov_b32 m0, s48
	s_add_u32 s16, s4, 0x40080
	global_load_lds_dwordx4 v[0:1], off
	v_lshl_add_u64 v[0:1], v[2:3], 0, s[8:9]
	s_mov_b32 m0, s49
	s_addc_u32 s17, s5, 0
	global_load_lds_dwordx4 v[0:1], off
	s_add_i32 m0, s27, 0x1c000
	s_nop 0
	global_load_lds_dwordx4 v192, s[16:17]
	s_add_i32 m0, s27, 0x1e000
	s_cmpk_lt_u32 s14, 0x100
	global_load_lds_dwordx4 v128, s[16:17]
	v_lshrrev_b32_e32 v1, 1, v8
	v_and_b32_e32 v1, 24, v1
	v_and_b32_e32 v0, 15, v8
	v_lshlrev_b32_e32 v2, 1, v1
	v_lshl_or_b32 v140, s15, 6, v0
	v_lshl_or_b32 v0, v0, 6, v2
	v_lshlrev_b32_e32 v2, 2, v8
	v_and_b32_e32 v2, 32, v2
	v_bitop3_b32 v3, v0, s28, v2 bitop3:0xde
	v_bitop3_b32 v141, v0, s30, v2 bitop3:0xde
	v_lshlrev_b32_e32 v0, 14, v13
	v_and_b32_e32 v0, 0xffff8000, v0
	v_or_b32_e32 v142, s29, v1
	v_lshl_add_u32 v0, v12, 11, v0
	v_and_b32_e32 v1, 1, v13
	v_lshl_or_b32 v0, v1, 6, v0
	v_lshl_add_u32 v134, v14, 1, v0
	v_lshlrev_b32_e32 v0, 14, v9
	v_and_b32_e32 v0, 0xffff8000, v0
	s_waitcnt vmcnt(6)
	v_lshl_add_u32 v0, v10, 11, v0
	v_and_b32_e32 v1, 1, v9
	v_lshl_or_b32 v0, v1, 6, v0
	s_sext_i32_i16 s50, s2
	s_cselect_b64 s[14:15], -1, 0
	v_mov_b32_e32 v135, v193
	v_lshl_add_u32 v136, v11, 1, v0
	v_mov_b32_e32 v137, v193
	s_mov_b32 s2, 0
	v_add_u32_e32 v143, 0, v3
	s_barrier
	s_branch .LBB0_64

.LBB0_67:
	s_add_u32 s4, s36, 0xfffc0080
	s_addc_u32 s5, s37, -1
	s_add_i32 s58, 0, 0x10000
	s_cmp_eq_u32 s55, 12
	s_cselect_b32 s41, s29, s5
	s_cselect_b32 s40, s51, s4
	v_add_u32_e32 v138, s58, v141
	s_cselect_b32 s5, s17, s54
	s_cselect_b32 s4, s52, s53
	s_add_i32 s60, 0, 0x14000
	ds_read_b128 v[144:147], v138
	ds_read_b128 v[148:151], v138 offset:1024
	ds_read_b128 v[152:155], v138 offset:2048
	ds_read_b128 v[156:159], v138 offset:3072
	v_add_u32_e32 v138, s60, v141
	ds_read_b128 v[160:163], v138
	ds_read_b128 v[164:167], v138 offset:1024
	ds_read_b128 v[168:171], v138 offset:2048
	ds_read_b128 v[172:175], v138 offset:3072
	s_add_i32 m0, s27, 0xc000
	ds_read_b128 v[176:179], v143
	ds_read_b128 v[180:183], v143 offset:1024
	ds_read_b128 v[184:187], v143 offset:2048
	ds_read_b128 v[188:191], v143 offset:3072
	ds_read_b128 v[208:211], v143 offset:4096
	ds_read_b128 v[212:215], v143 offset:5120
	ds_read_b128 v[216:219], v143 offset:6144
	ds_read_b128 v[220:223], v143 offset:7168
	global_load_lds_dwordx4 v134, s[36:37]
	s_add_i32 m0, s27, 0xe000
	s_nop 0
	global_load_lds_dwordx4 v136, s[36:37]
	s_waitcnt vmcnt(8)
	s_waitcnt lgkmcnt(0)
	s_barrier
	s_setprio 1
	s_waitcnt lgkmcnt(0)
	v_mfma_f32_16x16x32_bf16 v[124:127], v[144:147], v[176:179], v[124:127]
	v_mfma_f32_16x16x32_bf16 v[120:123], v[152:155], v[176:179], v[120:123]
	v_mfma_f32_16x16x32_bf16 v[108:111], v[144:147], v[184:187], v[108:111]
	v_mfma_f32_16x16x32_bf16 v[104:107], v[152:155], v[184:187], v[104:107]
	v_mfma_f32_16x16x32_bf16 v[92:95], v[144:147], v[208:211], v[92:95]
	v_mfma_f32_16x16x32_bf16 v[88:91], v[152:155], v[208:211], v[88:91]
	v_mfma_f32_16x16x32_bf16 v[76:79], v[144:147], v[216:219], v[76:79]
	v_mfma_f32_16x16x32_bf16 v[72:75], v[152:155], v[216:219], v[72:75]
	v_mfma_f32_16x16x32_bf16 v[124:127], v[148:151], v[180:183], v[124:127]
	v_mfma_f32_16x16x32_bf16 v[120:123], v[156:159], v[180:183], v[120:123]
	v_mfma_f32_16x16x32_bf16 v[108:111], v[148:151], v[188:191], v[108:111]
	v_mfma_f32_16x16x32_bf16 v[104:107], v[156:159], v[188:191], v[104:107]
	v_mfma_f32_16x16x32_bf16 v[92:95], v[148:151], v[212:215], v[92:95]
	v_mfma_f32_16x16x32_bf16 v[88:91], v[156:159], v[212:215], v[88:91]
	v_mfma_f32_16x16x32_bf16 v[76:79], v[148:151], v[220:223], v[76:79]
	v_mfma_f32_16x16x32_bf16 v[72:75], v[156:159], v[220:223], v[72:75]
	s_setprio 0
	s_setprio 1
	v_mfma_f32_16x16x32_bf16 v[116:119], v[160:163], v[176:179], v[116:119]
	v_mfma_f32_16x16x32_bf16 v[112:115], v[168:171], v[176:179], v[112:115]
	v_mfma_f32_16x16x32_bf16 v[100:103], v[160:163], v[184:187], v[100:103]
	v_mfma_f32_16x16x32_bf16 v[96:99], v[168:171], v[184:187], v[96:99]
	v_mfma_f32_16x16x32_bf16 v[84:87], v[160:163], v[208:211], v[84:87]
	v_mfma_f32_16x16x32_bf16 v[80:83], v[168:171], v[208:211], v[80:83]
	v_mfma_f32_16x16x32_bf16 v[68:71], v[160:163], v[216:219], v[68:71]
	v_mfma_f32_16x16x32_bf16 v[64:67], v[168:171], v[216:219], v[64:67]
	v_mfma_f32_16x16x32_bf16 v[116:119], v[164:167], v[180:183], v[116:119]
	v_mfma_f32_16x16x32_bf16 v[112:115], v[172:175], v[180:183], v[112:115]
	v_mfma_f32_16x16x32_bf16 v[100:103], v[164:167], v[188:191], v[100:103]
	v_mfma_f32_16x16x32_bf16 v[96:99], v[172:175], v[188:191], v[96:99]
	v_mfma_f32_16x16x32_bf16 v[84:87], v[164:167], v[212:215], v[84:87]
	v_mfma_f32_16x16x32_bf16 v[80:83], v[172:175], v[212:215], v[80:83]
	v_mfma_f32_16x16x32_bf16 v[68:71], v[164:167], v[220:223], v[68:71]
	v_mfma_f32_16x16x32_bf16 v[64:67], v[172:175], v[220:223], v[64:67]
	s_setprio 0
	s_barrier
	s_add_i32 s58, s58, s44
	v_lshl_add_u64 v[138:139], s[4:5], 0, v[192:193]
	s_mov_b32 m0, s58
	ds_read_b128 v[176:179], v143 offset:16384
	ds_read_b128 v[180:183], v143 offset:17408
	ds_read_b128 v[184:187], v143 offset:18432
	ds_read_b128 v[188:191], v143 offset:19456
	ds_read_b128 v[208:211], v143 offset:20480
	ds_read_b128 v[212:215], v143 offset:21504
	ds_read_b128 v[216:219], v143 offset:22528
	ds_read_b128 v[220:223], v143 offset:23552
	global_load_lds_dwordx4 v[138:139], off
	s_add_i32 m0, s58, 0x2000
	s_add_u32 s58, s4, 0x40000
	v_lshl_add_u64 v[224:225], s[4:5], 0, v[128:129]
	s_addc_u32 s59, s5, 0
	s_add_i32 s60, s60, s44
	global_load_lds_dwordx4 v[224:225], off
	s_mov_b32 m0, s60
	v_lshl_add_u64 v[228:229], s[40:41], 0, v[130:131]
	global_load_lds_dwordx4 v192, s[58:59]
	s_add_i32 m0, s60, 0x2000
	s_nop 0
	global_load_lds_dwordx4 v128, s[58:59]
	v_lshl_add_u64 v[226:227], s[40:41], 0, v[132:133]
	s_mov_b32 m0, s27
	s_nop 0
	global_load_lds_dwordx4 v[226:227], off
	s_mov_b32 m0, s45
	s_nop 0
	global_load_lds_dwordx4 v[228:229], off
	s_waitcnt vmcnt(8)
	s_waitcnt lgkmcnt(0)
	s_barrier
	s_setprio 1
	s_waitcnt lgkmcnt(0)
	v_mfma_f32_16x16x32_bf16 v[60:63], v[144:147], v[176:179], v[60:63]
	v_mfma_f32_16x16x32_bf16 v[56:59], v[152:155], v[176:179], v[56:59]
	v_mfma_f32_16x16x32_bf16 v[44:47], v[144:147], v[184:187], v[44:47]
	v_mfma_f32_16x16x32_bf16 v[40:43], v[152:155], v[184:187], v[40:43]
	v_mfma_f32_16x16x32_bf16 v[28:31], v[144:147], v[208:211], v[28:31]
	v_mfma_f32_16x16x32_bf16 v[24:27], v[152:155], v[208:211], v[24:27]
	v_mfma_f32_16x16x32_bf16 v[12:15], v[144:147], v[216:219], v[12:15]
	v_mfma_f32_16x16x32_bf16 v[8:11], v[152:155], v[216:219], v[8:11]
	v_mfma_f32_16x16x32_bf16 v[60:63], v[148:151], v[180:183], v[60:63]
	v_mfma_f32_16x16x32_bf16 v[56:59], v[156:159], v[180:183], v[56:59]
	v_mfma_f32_16x16x32_bf16 v[44:47], v[148:151], v[188:191], v[44:47]
	v_mfma_f32_16x16x32_bf16 v[40:43], v[156:159], v[188:191], v[40:43]
	v_mfma_f32_16x16x32_bf16 v[28:31], v[148:151], v[212:215], v[28:31]
	v_mfma_f32_16x16x32_bf16 v[24:27], v[156:159], v[212:215], v[24:27]
	v_mfma_f32_16x16x32_bf16 v[12:15], v[148:151], v[220:223], v[12:15]
	v_mfma_f32_16x16x32_bf16 v[8:11], v[156:159], v[220:223], v[8:11]
	s_setprio 0
	s_setprio 1
	v_mfma_f32_16x16x32_bf16 v[52:55], v[160:163], v[176:179], v[52:55]
	v_mfma_f32_16x16x32_bf16 v[48:51], v[168:171], v[176:179], v[48:51]
	v_mfma_f32_16x16x32_bf16 v[36:39], v[160:163], v[184:187], v[36:39]
	v_mfma_f32_16x16x32_bf16 v[32:35], v[168:171], v[184:187], v[32:35]
	v_mfma_f32_16x16x32_bf16 v[20:23], v[160:163], v[208:211], v[20:23]
	v_mfma_f32_16x16x32_bf16 v[16:19], v[168:171], v[208:211], v[16:19]
	v_mfma_f32_16x16x32_bf16 v[4:7], v[160:163], v[216:219], v[4:7]
	v_mfma_f32_16x16x32_bf16 v[0:3], v[168:171], v[216:219], v[0:3]
	v_mfma_f32_16x16x32_bf16 v[52:55], v[164:167], v[180:183], v[52:55]
	v_mfma_f32_16x16x32_bf16 v[48:51], v[172:175], v[180:183], v[48:51]
	v_mfma_f32_16x16x32_bf16 v[36:39], v[164:167], v[188:191], v[36:39]
	v_mfma_f32_16x16x32_bf16 v[32:35], v[172:175], v[188:191], v[32:35]
	v_mfma_f32_16x16x32_bf16 v[20:23], v[164:167], v[212:215], v[20:23]
	v_mfma_f32_16x16x32_bf16 v[16:19], v[172:175], v[212:215], v[16:19]
	v_mfma_f32_16x16x32_bf16 v[4:7], v[164:167], v[220:223], v[4:7]
	v_mfma_f32_16x16x32_bf16 v[0:3], v[172:175], v[220:223], v[0:3]
	s_setprio 0
	s_barrier
	s_add_i32 s58, 0, 0x18000
	s_add_i32 s59, 0, 0x1c000
	v_add_u32_e32 v156, s58, v141
	v_add_u32_e32 v172, s59, v141
	ds_read_b128 v[144:147], v156
	ds_read_b128 v[148:151], v156 offset:1024
	ds_read_b128 v[152:155], v156 offset:2048
	ds_read_b128 v[156:159], v156 offset:3072
	ds_read_b128 v[160:163], v172
	ds_read_b128 v[164:167], v172 offset:1024
	ds_read_b128 v[168:171], v172 offset:2048
	ds_read_b128 v[172:175], v172 offset:3072
	s_add_u32 s40, s40, 0x40000
	s_addc_u32 s41, s41, 0
	s_mov_b32 m0, s46
	ds_read_b128 v[176:179], v143 offset:32768
	ds_read_b128 v[180:183], v143 offset:33792
	ds_read_b128 v[184:187], v143 offset:34816
	ds_read_b128 v[188:191], v143 offset:35840
	ds_read_b128 v[208:211], v143 offset:36864
	ds_read_b128 v[212:215], v143 offset:37888
	ds_read_b128 v[216:219], v143 offset:38912
	ds_read_b128 v[220:223], v143 offset:39936
	global_load_lds_dwordx4 v132, s[40:41]
	v_lshl_add_u64 v[230:231], s[40:41], 0, v[130:131]
	s_mov_b32 m0, s47
	s_nop 0
	global_load_lds_dwordx4 v[230:231], off
	s_waitcnt vmcnt(8)
	s_waitcnt lgkmcnt(0)
	s_barrier
	s_setprio 1
	s_waitcnt lgkmcnt(0)
	v_mfma_f32_16x16x32_bf16 v[124:127], v[144:147], v[176:179], v[124:127]
	v_mfma_f32_16x16x32_bf16 v[120:123], v[152:155], v[176:179], v[120:123]
	v_mfma_f32_16x16x32_bf16 v[108:111], v[144:147], v[184:187], v[108:111]
	v_mfma_f32_16x16x32_bf16 v[104:107], v[152:155], v[184:187], v[104:107]
	v_mfma_f32_16x16x32_bf16 v[92:95], v[144:147], v[208:211], v[92:95]
	v_mfma_f32_16x16x32_bf16 v[88:91], v[152:155], v[208:211], v[88:91]
	v_mfma_f32_16x16x32_bf16 v[76:79], v[144:147], v[216:219], v[76:79]
	v_mfma_f32_16x16x32_bf16 v[72:75], v[152:155], v[216:219], v[72:75]
	v_mfma_f32_16x16x32_bf16 v[124:127], v[148:151], v[180:183], v[124:127]
	v_mfma_f32_16x16x32_bf16 v[120:123], v[156:159], v[180:183], v[120:123]
	v_mfma_f32_16x16x32_bf16 v[108:111], v[148:151], v[188:191], v[108:111]
	v_mfma_f32_16x16x32_bf16 v[104:107], v[156:159], v[188:191], v[104:107]
	v_mfma_f32_16x16x32_bf16 v[92:95], v[148:151], v[212:215], v[92:95]
	v_mfma_f32_16x16x32_bf16 v[88:91], v[156:159], v[212:215], v[88:91]
	v_mfma_f32_16x16x32_bf16 v[76:79], v[148:151], v[220:223], v[76:79]
	v_mfma_f32_16x16x32_bf16 v[72:75], v[156:159], v[220:223], v[72:75]
	s_setprio 0
	s_setprio 1
	v_mfma_f32_16x16x32_bf16 v[116:119], v[160:163], v[176:179], v[116:119]
	v_mfma_f32_16x16x32_bf16 v[112:115], v[168:171], v[176:179], v[112:115]
	v_mfma_f32_16x16x32_bf16 v[100:103], v[160:163], v[184:187], v[100:103]
	v_mfma_f32_16x16x32_bf16 v[96:99], v[168:171], v[184:187], v[96:99]
	v_mfma_f32_16x16x32_bf16 v[84:87], v[160:163], v[208:211], v[84:87]
	v_mfma_f32_16x16x32_bf16 v[80:83], v[168:171], v[208:211], v[80:83]
	v_mfma_f32_16x16x32_bf16 v[68:71], v[160:163], v[216:219], v[68:71]
	v_mfma_f32_16x16x32_bf16 v[64:67], v[168:171], v[216:219], v[64:67]
	v_mfma_f32_16x16x32_bf16 v[116:119], v[164:167], v[180:183], v[116:119]
	v_mfma_f32_16x16x32_bf16 v[112:115], v[172:175], v[180:183], v[112:115]
	v_mfma_f32_16x16x32_bf16 v[100:103], v[164:167], v[188:191], v[100:103]
	v_mfma_f32_16x16x32_bf16 v[96:99], v[172:175], v[188:191], v[96:99]
	v_mfma_f32_16x16x32_bf16 v[84:87], v[164:167], v[212:215], v[84:87]
	v_mfma_f32_16x16x32_bf16 v[80:83], v[172:175], v[212:215], v[80:83]
	v_mfma_f32_16x16x32_bf16 v[68:71], v[164:167], v[220:223], v[68:71]
	v_mfma_f32_16x16x32_bf16 v[64:67], v[172:175], v[220:223], v[64:67]
	s_setprio 0
	s_barrier
	s_add_i32 s40, s58, s44
	v_lshl_add_u64 v[138:139], v[138:139], 0, s[8:9]
	s_mov_b32 m0, s40
	ds_read_b128 v[176:179], v143 offset:49152
	ds_read_b128 v[180:183], v143 offset:50176
	ds_read_b128 v[184:187], v143 offset:51200
	ds_read_b128 v[188:191], v143 offset:52224
	ds_read_b128 v[208:211], v143 offset:53248
	ds_read_b128 v[212:215], v143 offset:54272
	ds_read_b128 v[216:219], v143 offset:55296
	ds_read_b128 v[220:223], v143 offset:56320
	global_load_lds_dwordx4 v[138:139], off
	s_add_i32 m0, s40, 0x2000
	s_add_u32 s4, s4, 0x40080
	v_lshl_add_u64 v[138:139], v[224:225], 0, s[8:9]
	s_addc_u32 s5, s5, 0
	s_add_i32 s40, s59, s44
	global_load_lds_dwordx4 v[138:139], off
	s_mov_b32 m0, s40
	s_nop 0
	global_load_lds_dwordx4 v192, s[4:5]
	s_add_i32 m0, s40, 0x2000
	s_nop 0
	global_load_lds_dwordx4 v128, s[4:5]
	v_lshl_add_u64 v[138:139], v[226:227], 0, s[8:9]
	s_mov_b32 m0, s48
	s_nop 0
	global_load_lds_dwordx4 v[138:139], off
	v_lshl_add_u64 v[138:139], v[228:229], 0, s[8:9]
	s_mov_b32 m0, s49
	s_nop 0
	global_load_lds_dwordx4 v[138:139], off
	s_waitcnt vmcnt(8)
	s_waitcnt lgkmcnt(0)
	s_barrier
	s_setprio 1
	s_waitcnt lgkmcnt(0)
	v_mfma_f32_16x16x32_bf16 v[60:63], v[144:147], v[176:179], v[60:63]
	v_mfma_f32_16x16x32_bf16 v[56:59], v[152:155], v[176:179], v[56:59]
	v_mfma_f32_16x16x32_bf16 v[44:47], v[144:147], v[184:187], v[44:47]
	v_mfma_f32_16x16x32_bf16 v[40:43], v[152:155], v[184:187], v[40:43]
	v_mfma_f32_16x16x32_bf16 v[28:31], v[144:147], v[208:211], v[28:31]
	v_mfma_f32_16x16x32_bf16 v[24:27], v[152:155], v[208:211], v[24:27]
	v_mfma_f32_16x16x32_bf16 v[12:15], v[144:147], v[216:219], v[12:15]
	v_mfma_f32_16x16x32_bf16 v[8:11], v[152:155], v[216:219], v[8:11]
	v_mfma_f32_16x16x32_bf16 v[60:63], v[148:151], v[180:183], v[60:63]
	v_mfma_f32_16x16x32_bf16 v[56:59], v[156:159], v[180:183], v[56:59]
	v_mfma_f32_16x16x32_bf16 v[44:47], v[148:151], v[188:191], v[44:47]
	v_mfma_f32_16x16x32_bf16 v[40:43], v[156:159], v[188:191], v[40:43]
	v_mfma_f32_16x16x32_bf16 v[28:31], v[148:151], v[212:215], v[28:31]
	v_mfma_f32_16x16x32_bf16 v[24:27], v[156:159], v[212:215], v[24:27]
	v_mfma_f32_16x16x32_bf16 v[12:15], v[148:151], v[220:223], v[12:15]
	v_mfma_f32_16x16x32_bf16 v[8:11], v[156:159], v[220:223], v[8:11]
	s_setprio 0
	s_setprio 1
	v_mfma_f32_16x16x32_bf16 v[52:55], v[160:163], v[176:179], v[52:55]
	v_mfma_f32_16x16x32_bf16 v[48:51], v[168:171], v[176:179], v[48:51]
	v_mfma_f32_16x16x32_bf16 v[36:39], v[160:163], v[184:187], v[36:39]
	v_mfma_f32_16x16x32_bf16 v[32:35], v[168:171], v[184:187], v[32:35]
	v_mfma_f32_16x16x32_bf16 v[20:23], v[160:163], v[208:211], v[20:23]
	v_mfma_f32_16x16x32_bf16 v[16:19], v[168:171], v[208:211], v[16:19]
	v_mfma_f32_16x16x32_bf16 v[4:7], v[160:163], v[216:219], v[4:7]
	v_mfma_f32_16x16x32_bf16 v[0:3], v[168:171], v[216:219], v[0:3]
	v_mfma_f32_16x16x32_bf16 v[52:55], v[164:167], v[180:183], v[52:55]
	v_mfma_f32_16x16x32_bf16 v[48:51], v[172:175], v[180:183], v[48:51]
	v_mfma_f32_16x16x32_bf16 v[36:39], v[164:167], v[188:191], v[36:39]
	v_mfma_f32_16x16x32_bf16 v[32:35], v[172:175], v[188:191], v[32:35]
	v_mfma_f32_16x16x32_bf16 v[20:23], v[164:167], v[212:215], v[20:23]
	v_mfma_f32_16x16x32_bf16 v[16:19], v[172:175], v[212:215], v[16:19]
	v_mfma_f32_16x16x32_bf16 v[4:7], v[164:167], v[220:223], v[4:7]
	v_mfma_f32_16x16x32_bf16 v[0:3], v[172:175], v[220:223], v[0:3]
	s_setprio 0
	s_barrier
	s_add_i32 s55, s55, 2
	s_add_u32 s36, s36, 0x100
	s_addc_u32 s37, s37, 0
	s_add_u32 s53, s53, 0x100
	s_addc_u32 s54, s54, 0
	s_cmp_gt_u32 s55, 13
	s_cbranch_scc0 .LBB0_67
	s_and_b64 vcc, exec, s[14:15]
	s_cbranch_vccz .LBB0_70
	s_barrier

.LBB0_208:
	v_lshl_add_u64 v[8:9], s[4:5], 0, v[192:193]
	v_mov_b32_e32 v129, v193
	v_and_b32_e32 v220, 15, v138
	v_and_b32_e32 v16, 48, v138
	v_lshlrev_b32_e32 v17, 2, v138
	v_lshl_add_u64 v[10:11], s[4:5], 0, v[128:129]
	s_and_b32 s59, s53, 3
	s_lshl_b32 s11, s0, 13
	v_lshl_or_b32 v16, v220, 6, v16
	v_and_b32_e32 v17, 32, v17
	s_add_i32 m0, s44, 0x18000
	v_lshl_add_u64 v[8:9], v[8:9], 0, s[8:9]
	s_lshr_b32 s10, s30, 3
	v_lshl_add_u64 v[12:13], s[26:27], 0, v[192:193]
	s_lshl_b32 s54, s0, 6
	v_bitop3_b32 v18, v16, s11, v17 bitop3:0xde
	s_lshl_b32 s11, s59, 12
	s_waitcnt vmcnt(2)
	s_barrier
	global_load_lds_dwordx4 v[8:9], off
	v_lshl_add_u64 v[8:9], v[10:11], 0, s[8:9]
	s_add_i32 m0, s44, 0x1a000
	s_add_i32 s58, s44, 0x8000
	s_add_i32 s55, s44, 0xa000
	v_lshl_add_u64 v[14:15], s[26:27], 0, v[128:129]
	global_load_lds_dwordx4 v[8:9], off
	v_lshl_add_u64 v[8:9], v[12:13], 0, s[8:9]
	s_mov_b32 m0, s58
	s_add_u32 s28, s4, 0xb0080
	global_load_lds_dwordx4 v[8:9], off
	v_lshl_add_u64 v[8:9], v[14:15], 0, s[8:9]
	s_mov_b32 m0, s55
	s_addc_u32 s29, s5, 0
	global_load_lds_dwordx4 v[8:9], off
	s_add_i32 m0, s44, 0x1c000
	s_nop 0
	global_load_lds_dwordx4 v192, s[28:29]
	s_add_i32 m0, s44, 0x1e000
	v_bitop3_b32 v139, v16, s11, v17 bitop3:0xde
	global_load_lds_dwordx4 v128, s[28:29]
	s_movk_i32 s11, 0xb00
	v_lshrrev_b32_e32 v5, 1, v5
	v_mul_lo_u32 v4, v4, s11
	s_mov_b32 s30, 0xb000
	v_mad_u64_u32 v[4:5], s[28:29], v5, s30, v[4:5]
	v_or_b32_e32 v4, v4, v6
	v_add_lshl_u32 v130, v4, v7, 1
	v_lshrrev_b32_e32 v4, 1, v0
	v_mul_lo_u32 v0, v1, s11
	v_mad_u64_u32 v[0:1], s[28:29], v4, s30, v[0:1]
	v_or_b32_e32 v0, v0, v2
	s_waitcnt vmcnt(6)
	v_add_lshl_u32 v132, v0, v3, 1
	v_mov_b32_e32 v2, v193
	v_mov_b32_e32 v3, v193
	v_mov_b32_e32 v0, v193
	v_mov_b32_e32 v1, v193
	v_add_u32_e32 v140, 0, v18
	v_mov_b64_e32 v[6:7], v[2:3]
	v_mov_b64_e32 v[18:19], v[2:3]
	v_mov_b64_e32 v[22:23], v[2:3]
	v_mov_b64_e32 v[34:35], v[2:3]
	v_mov_b64_e32 v[38:39], v[2:3]
	v_mov_b64_e32 v[50:51], v[2:3]
	v_mov_b64_e32 v[54:55], v[2:3]
	v_mov_b64_e32 v[10:11], v[2:3]
	v_mov_b64_e32 v[14:15], v[2:3]
	v_mov_b64_e32 v[26:27], v[2:3]
	v_mov_b64_e32 v[30:31], v[2:3]
	v_mov_b64_e32 v[42:43], v[2:3]
	v_mov_b64_e32 v[46:47], v[2:3]
	v_mov_b64_e32 v[58:59], v[2:3]
	v_mov_b64_e32 v[62:63], v[2:3]
	v_mov_b64_e32 v[66:67], v[2:3]
	v_mov_b64_e32 v[70:71], v[2:3]
	v_mov_b64_e32 v[82:83], v[2:3]
	v_mov_b64_e32 v[86:87], v[2:3]
	v_mov_b64_e32 v[118:119], v[2:3]
	v_mov_b64_e32 v[122:123], v[2:3]
	v_mov_b64_e32 v[106:107], v[2:3]
	v_mov_b64_e32 v[102:103], v[2:3]
	v_mov_b64_e32 v[74:75], v[2:3]
	v_mov_b64_e32 v[78:79], v[2:3]
	v_mov_b64_e32 v[94:95], v[2:3]
	v_mov_b64_e32 v[114:115], v[2:3]
	v_mov_b64_e32 v[126:127], v[2:3]
	v_mov_b64_e32 v[110:111], v[2:3]
	v_mov_b64_e32 v[98:99], v[2:3]
	v_mov_b64_e32 v[90:91], v[2:3]
	v_or_b32_e32 v212, s54, v220
	s_sext_i32_i8 s10, s10
	v_mov_b32_e32 v131, v193
	v_mov_b32_e32 v133, v193
	s_mov_b32 s11, 0
	v_mov_b64_e32 v[4:5], v[0:1]
	v_mov_b64_e32 v[16:17], v[0:1]
	v_mov_b64_e32 v[20:21], v[0:1]
	v_mov_b64_e32 v[32:33], v[0:1]
	v_mov_b64_e32 v[36:37], v[0:1]
	v_mov_b64_e32 v[48:49], v[0:1]
	v_mov_b64_e32 v[52:53], v[0:1]
	v_mov_b64_e32 v[8:9], v[0:1]
	v_mov_b64_e32 v[12:13], v[0:1]
	v_mov_b64_e32 v[24:25], v[0:1]
	v_mov_b64_e32 v[28:29], v[0:1]
	v_mov_b64_e32 v[40:41], v[0:1]
	v_mov_b64_e32 v[44:45], v[0:1]
	v_mov_b64_e32 v[56:57], v[0:1]
	v_mov_b64_e32 v[60:61], v[0:1]
	v_mov_b64_e32 v[64:65], v[0:1]
	v_mov_b64_e32 v[68:69], v[0:1]
	v_mov_b64_e32 v[80:81], v[0:1]
	v_mov_b64_e32 v[84:85], v[0:1]
	v_mov_b64_e32 v[116:117], v[0:1]
	v_mov_b64_e32 v[120:121], v[0:1]
	v_mov_b64_e32 v[104:105], v[0:1]
	v_mov_b64_e32 v[100:101], v[0:1]
	v_mov_b64_e32 v[72:73], v[0:1]
	v_mov_b64_e32 v[76:77], v[0:1]
	v_mov_b64_e32 v[92:93], v[0:1]
	v_mov_b64_e32 v[112:113], v[0:1]
	v_mov_b64_e32 v[124:125], v[0:1]
	v_mov_b64_e32 v[108:109], v[0:1]
	v_mov_b64_e32 v[96:97], v[0:1]
	v_mov_b64_e32 v[88:89], v[0:1]
	s_barrier

.LBB0_220:
	s_add_u32 s34, s26, s4
	s_addc_u32 s35, s27, s5
	s_add_u32 s34, s34, 0x100
	s_addc_u32 s35, s35, 0
	s_add_u32 s66, s42, s4
	s_addc_u32 s67, s43, s5
	s_add_i32 s70, 0, 0x10000
	s_cmpk_eq_i32 s4, 0x1500
	s_cselect_b32 s37, s31, s35
	s_cselect_b32 s36, s30, s34
	v_add_u32_e32 v141, s70, v139
	s_cselect_b32 s35, s29, s67
	s_cselect_b32 s34, s28, s66
	s_add_i32 s71, 0, 0x14000
	ds_read_b128 v[142:145], v141
	ds_read_b128 v[146:149], v141 offset:1024
	ds_read_b128 v[150:153], v141 offset:2048
	ds_read_b128 v[154:157], v141 offset:3072
	v_add_u32_e32 v141, s71, v139
	ds_read_b128 v[158:161], v141
	ds_read_b128 v[162:165], v141 offset:1024
	ds_read_b128 v[166:169], v141 offset:2048
	ds_read_b128 v[170:173], v141 offset:3072
	s_add_i32 s66, s44, 0xc000
	v_lshl_add_u64 v[190:191], v[134:135], 0, s[4:5]
	s_mov_b32 m0, s66
	s_add_i32 s67, s44, 0xe000
	ds_read_b128 v[174:177], v140
	ds_read_b128 v[178:181], v140 offset:1024
	ds_read_b128 v[182:185], v140 offset:2048
	ds_read_b128 v[186:189], v140 offset:3072
	ds_read_b128 v[208:211], v140 offset:4096
	ds_read_b128 v[214:217], v140 offset:5120
	ds_read_b128 v[222:225], v140 offset:6144
	ds_read_b128 v[226:229], v140 offset:7168
	global_load_lds_dwordx4 v[190:191], off
	v_lshl_add_u64 v[190:191], v[136:137], 0, s[4:5]
	s_mov_b32 m0, s67
	s_nop 0
	global_load_lds_dwordx4 v[190:191], off
	s_waitcnt vmcnt(8)
	s_waitcnt lgkmcnt(0)
	s_barrier
	s_setprio 1
	s_waitcnt lgkmcnt(0)
	v_mfma_f32_16x16x32_bf16 v[88:91], v[142:145], v[174:177], v[88:91]
	v_mfma_f32_16x16x32_bf16 v[96:99], v[150:153], v[174:177], v[96:99]
	v_mfma_f32_16x16x32_bf16 v[108:111], v[142:145], v[182:185], v[108:111]
	v_mfma_f32_16x16x32_bf16 v[124:127], v[150:153], v[182:185], v[124:127]
	v_mfma_f32_16x16x32_bf16 v[112:115], v[142:145], v[208:211], v[112:115]
	v_mfma_f32_16x16x32_bf16 v[92:95], v[150:153], v[208:211], v[92:95]
	v_mfma_f32_16x16x32_bf16 v[76:79], v[142:145], v[222:225], v[76:79]
	v_mfma_f32_16x16x32_bf16 v[72:75], v[150:153], v[222:225], v[72:75]
	v_mfma_f32_16x16x32_bf16 v[88:91], v[146:149], v[178:181], v[88:91]
	v_mfma_f32_16x16x32_bf16 v[96:99], v[154:157], v[178:181], v[96:99]
	v_mfma_f32_16x16x32_bf16 v[108:111], v[146:149], v[186:189], v[108:111]
	v_mfma_f32_16x16x32_bf16 v[124:127], v[154:157], v[186:189], v[124:127]
	v_mfma_f32_16x16x32_bf16 v[112:115], v[146:149], v[214:217], v[112:115]
	v_mfma_f32_16x16x32_bf16 v[92:95], v[154:157], v[214:217], v[92:95]
	v_mfma_f32_16x16x32_bf16 v[76:79], v[146:149], v[226:229], v[76:79]
	v_mfma_f32_16x16x32_bf16 v[72:75], v[154:157], v[226:229], v[72:75]
	s_setprio 0
	s_setprio 1
	v_mfma_f32_16x16x32_bf16 v[100:103], v[158:161], v[174:177], v[100:103]
	v_mfma_f32_16x16x32_bf16 v[104:107], v[166:169], v[174:177], v[104:107]
	v_mfma_f32_16x16x32_bf16 v[120:123], v[158:161], v[182:185], v[120:123]
	v_mfma_f32_16x16x32_bf16 v[116:119], v[166:169], v[182:185], v[116:119]
	v_mfma_f32_16x16x32_bf16 v[84:87], v[158:161], v[208:211], v[84:87]
	v_mfma_f32_16x16x32_bf16 v[80:83], v[166:169], v[208:211], v[80:83]
	v_mfma_f32_16x16x32_bf16 v[68:71], v[158:161], v[222:225], v[68:71]
	v_mfma_f32_16x16x32_bf16 v[64:67], v[166:169], v[222:225], v[64:67]
	v_mfma_f32_16x16x32_bf16 v[100:103], v[162:165], v[178:181], v[100:103]
	v_mfma_f32_16x16x32_bf16 v[104:107], v[170:173], v[178:181], v[104:107]
	v_mfma_f32_16x16x32_bf16 v[120:123], v[162:165], v[186:189], v[120:123]
	v_mfma_f32_16x16x32_bf16 v[116:119], v[170:173], v[186:189], v[116:119]
	v_mfma_f32_16x16x32_bf16 v[84:87], v[162:165], v[214:217], v[84:87]
	v_mfma_f32_16x16x32_bf16 v[80:83], v[170:173], v[214:217], v[80:83]
	v_mfma_f32_16x16x32_bf16 v[68:71], v[162:165], v[226:229], v[68:71]
	v_mfma_f32_16x16x32_bf16 v[64:67], v[170:173], v[226:229], v[64:67]
	s_setprio 0
	s_barrier
	s_add_i32 s70, s70, s64
	v_lshl_add_u64 v[190:191], s[34:35], 0, v[192:193]
	s_mov_b32 m0, s70
	ds_read_b128 v[174:177], v140 offset:16384
	ds_read_b128 v[178:181], v140 offset:17408
	ds_read_b128 v[182:185], v140 offset:18432
	ds_read_b128 v[186:189], v140 offset:19456
	ds_read_b128 v[208:211], v140 offset:20480
	ds_read_b128 v[214:217], v140 offset:21504
	ds_read_b128 v[222:225], v140 offset:22528
	ds_read_b128 v[226:229], v140 offset:23552
	global_load_lds_dwordx4 v[190:191], off
	s_add_i32 m0, s70, 0x2000
	s_add_u32 s94, s34, 0xb0000
	v_lshl_add_u64 v[218:219], s[34:35], 0, v[128:129]
	s_addc_u32 s95, s35, 0
	s_add_i32 s70, s71, s64
	global_load_lds_dwordx4 v[218:219], off
	s_mov_b32 m0, s70
	v_lshl_add_u64 v[232:233], s[36:37], 0, v[128:129]
	global_load_lds_dwordx4 v192, s[94:95]
	s_add_i32 m0, s70, 0x2000
	s_nop 0
	global_load_lds_dwordx4 v128, s[94:95]
	v_lshl_add_u64 v[230:231], s[36:37], 0, v[192:193]
	s_mov_b32 m0, s44
	s_nop 0
	global_load_lds_dwordx4 v[230:231], off
	s_mov_b32 m0, s46
	s_nop 0
	global_load_lds_dwordx4 v[232:233], off
	s_waitcnt vmcnt(8)
	s_waitcnt lgkmcnt(0)
	s_barrier
	s_setprio 1
	s_waitcnt lgkmcnt(0)
	v_mfma_f32_16x16x32_bf16 v[60:63], v[142:145], v[174:177], v[60:63]
	v_mfma_f32_16x16x32_bf16 v[56:59], v[150:153], v[174:177], v[56:59]
	v_mfma_f32_16x16x32_bf16 v[44:47], v[142:145], v[182:185], v[44:47]
	v_mfma_f32_16x16x32_bf16 v[40:43], v[150:153], v[182:185], v[40:43]
	v_mfma_f32_16x16x32_bf16 v[28:31], v[142:145], v[208:211], v[28:31]
	v_mfma_f32_16x16x32_bf16 v[24:27], v[150:153], v[208:211], v[24:27]
	v_mfma_f32_16x16x32_bf16 v[12:15], v[142:145], v[222:225], v[12:15]
	v_mfma_f32_16x16x32_bf16 v[8:11], v[150:153], v[222:225], v[8:11]
	v_mfma_f32_16x16x32_bf16 v[60:63], v[146:149], v[178:181], v[60:63]
	v_mfma_f32_16x16x32_bf16 v[56:59], v[154:157], v[178:181], v[56:59]
	v_mfma_f32_16x16x32_bf16 v[44:47], v[146:149], v[186:189], v[44:47]
	v_mfma_f32_16x16x32_bf16 v[40:43], v[154:157], v[186:189], v[40:43]
	v_mfma_f32_16x16x32_bf16 v[28:31], v[146:149], v[214:217], v[28:31]
	v_mfma_f32_16x16x32_bf16 v[24:27], v[154:157], v[214:217], v[24:27]
	v_mfma_f32_16x16x32_bf16 v[12:15], v[146:149], v[226:229], v[12:15]
	v_mfma_f32_16x16x32_bf16 v[8:11], v[154:157], v[226:229], v[8:11]
	s_setprio 0
	s_setprio 1
	v_mfma_f32_16x16x32_bf16 v[52:55], v[158:161], v[174:177], v[52:55]
	v_mfma_f32_16x16x32_bf16 v[48:51], v[166:169], v[174:177], v[48:51]
	v_mfma_f32_16x16x32_bf16 v[36:39], v[158:161], v[182:185], v[36:39]
	v_mfma_f32_16x16x32_bf16 v[32:35], v[166:169], v[182:185], v[32:35]
	v_mfma_f32_16x16x32_bf16 v[20:23], v[158:161], v[208:211], v[20:23]
	v_mfma_f32_16x16x32_bf16 v[16:19], v[166:169], v[208:211], v[16:19]
	v_mfma_f32_16x16x32_bf16 v[4:7], v[158:161], v[222:225], v[4:7]
	v_mfma_f32_16x16x32_bf16 v[0:3], v[166:169], v[222:225], v[0:3]
	v_mfma_f32_16x16x32_bf16 v[52:55], v[162:165], v[178:181], v[52:55]
	v_mfma_f32_16x16x32_bf16 v[48:51], v[170:173], v[178:181], v[48:51]
	v_mfma_f32_16x16x32_bf16 v[36:39], v[162:165], v[186:189], v[36:39]
	v_mfma_f32_16x16x32_bf16 v[32:35], v[170:173], v[186:189], v[32:35]
	v_mfma_f32_16x16x32_bf16 v[20:23], v[162:165], v[214:217], v[20:23]
	v_mfma_f32_16x16x32_bf16 v[16:19], v[170:173], v[214:217], v[16:19]
	v_mfma_f32_16x16x32_bf16 v[4:7], v[162:165], v[226:229], v[4:7]
	v_mfma_f32_16x16x32_bf16 v[0:3], v[170:173], v[226:229], v[0:3]
	s_setprio 0
	s_barrier
	s_add_i32 s70, 0, 0x18000
	v_add_u32_e32 v141, s70, v139
	s_add_i32 s71, 0, 0x1c000
	ds_read_b128 v[142:145], v141
	ds_read_b128 v[146:149], v141 offset:1024
	ds_read_b128 v[150:153], v141 offset:2048
	ds_read_b128 v[154:157], v141 offset:3072
	v_add_u32_e32 v141, s71, v139
	ds_read_b128 v[158:161], v141
	ds_read_b128 v[162:165], v141 offset:1024
	ds_read_b128 v[166:169], v141 offset:2048
	ds_read_b128 v[170:173], v141 offset:3072
	s_add_u32 s36, s36, 0xb0000
	s_addc_u32 s37, s37, 0
	s_mov_b32 m0, s47
	ds_read_b128 v[174:177], v140 offset:32768
	ds_read_b128 v[178:181], v140 offset:33792
	ds_read_b128 v[182:185], v140 offset:34816
	ds_read_b128 v[186:189], v140 offset:35840
	ds_read_b128 v[208:211], v140 offset:36864
	ds_read_b128 v[214:217], v140 offset:37888
	ds_read_b128 v[222:225], v140 offset:38912
	ds_read_b128 v[226:229], v140 offset:39936
	global_load_lds_dwordx4 v192, s[36:37]
	v_lshl_add_u64 v[234:235], s[36:37], 0, v[128:129]
	s_mov_b32 m0, s52
	s_nop 0
	global_load_lds_dwordx4 v[234:235], off
	s_waitcnt vmcnt(8)
	s_waitcnt lgkmcnt(0)
	s_barrier
	s_setprio 1
	s_waitcnt lgkmcnt(0)
	v_mfma_f32_16x16x32_bf16 v[88:91], v[142:145], v[174:177], v[88:91]
	v_mfma_f32_16x16x32_bf16 v[96:99], v[150:153], v[174:177], v[96:99]
	v_mfma_f32_16x16x32_bf16 v[108:111], v[142:145], v[182:185], v[108:111]
	v_mfma_f32_16x16x32_bf16 v[124:127], v[150:153], v[182:185], v[124:127]
	v_mfma_f32_16x16x32_bf16 v[112:115], v[142:145], v[208:211], v[112:115]
	v_mfma_f32_16x16x32_bf16 v[92:95], v[150:153], v[208:211], v[92:95]
	v_mfma_f32_16x16x32_bf16 v[76:79], v[142:145], v[222:225], v[76:79]
	v_mfma_f32_16x16x32_bf16 v[72:75], v[150:153], v[222:225], v[72:75]
	v_mfma_f32_16x16x32_bf16 v[88:91], v[146:149], v[178:181], v[88:91]
	v_mfma_f32_16x16x32_bf16 v[96:99], v[154:157], v[178:181], v[96:99]
	v_mfma_f32_16x16x32_bf16 v[108:111], v[146:149], v[186:189], v[108:111]
	v_mfma_f32_16x16x32_bf16 v[124:127], v[154:157], v[186:189], v[124:127]
	v_mfma_f32_16x16x32_bf16 v[112:115], v[146:149], v[214:217], v[112:115]
	v_mfma_f32_16x16x32_bf16 v[92:95], v[154:157], v[214:217], v[92:95]
	v_mfma_f32_16x16x32_bf16 v[76:79], v[146:149], v[226:229], v[76:79]
	v_mfma_f32_16x16x32_bf16 v[72:75], v[154:157], v[226:229], v[72:75]
	s_setprio 0
	s_setprio 1
	v_mfma_f32_16x16x32_bf16 v[100:103], v[158:161], v[174:177], v[100:103]
	v_mfma_f32_16x16x32_bf16 v[104:107], v[166:169], v[174:177], v[104:107]
	v_mfma_f32_16x16x32_bf16 v[120:123], v[158:161], v[182:185], v[120:123]
	v_mfma_f32_16x16x32_bf16 v[116:119], v[166:169], v[182:185], v[116:119]
	v_mfma_f32_16x16x32_bf16 v[84:87], v[158:161], v[208:211], v[84:87]
	v_mfma_f32_16x16x32_bf16 v[80:83], v[166:169], v[208:211], v[80:83]
	v_mfma_f32_16x16x32_bf16 v[68:71], v[158:161], v[222:225], v[68:71]
	v_mfma_f32_16x16x32_bf16 v[64:67], v[166:169], v[222:225], v[64:67]
	v_mfma_f32_16x16x32_bf16 v[100:103], v[162:165], v[178:181], v[100:103]
	v_mfma_f32_16x16x32_bf16 v[104:107], v[170:173], v[178:181], v[104:107]
	v_mfma_f32_16x16x32_bf16 v[120:123], v[162:165], v[186:189], v[120:123]
	v_mfma_f32_16x16x32_bf16 v[116:119], v[170:173], v[186:189], v[116:119]
	v_mfma_f32_16x16x32_bf16 v[84:87], v[162:165], v[214:217], v[84:87]
	v_mfma_f32_16x16x32_bf16 v[80:83], v[170:173], v[214:217], v[80:83]
	v_mfma_f32_16x16x32_bf16 v[68:71], v[162:165], v[226:229], v[68:71]
	v_mfma_f32_16x16x32_bf16 v[64:67], v[170:173], v[226:229], v[64:67]
	s_setprio 0
	s_barrier
	s_add_i32 s36, s70, s64
	v_lshl_add_u64 v[190:191], v[190:191], 0, s[8:9]
	s_mov_b32 m0, s36
	ds_read_b128 v[174:177], v140 offset:49152
	ds_read_b128 v[178:181], v140 offset:50176
	ds_read_b128 v[182:185], v140 offset:51200
	ds_read_b128 v[186:189], v140 offset:52224
	ds_read_b128 v[208:211], v140 offset:53248
	ds_read_b128 v[214:217], v140 offset:54272
	ds_read_b128 v[222:225], v140 offset:55296
	ds_read_b128 v[226:229], v140 offset:56320
	global_load_lds_dwordx4 v[190:191], off
	s_add_i32 m0, s36, 0x2000
	s_add_u32 s34, s34, 0xb0080
	v_lshl_add_u64 v[190:191], v[218:219], 0, s[8:9]
	s_addc_u32 s35, s35, 0
	s_add_i32 s36, s71, s64
	global_load_lds_dwordx4 v[190:191], off
	s_mov_b32 m0, s36
	s_nop 0
	global_load_lds_dwordx4 v192, s[34:35]
	s_add_i32 m0, s36, 0x2000
	s_nop 0
	global_load_lds_dwordx4 v128, s[34:35]
	v_lshl_add_u64 v[190:191], v[230:231], 0, s[8:9]
	s_mov_b32 m0, s58
	s_nop 0
	global_load_lds_dwordx4 v[190:191], off
	v_lshl_add_u64 v[190:191], v[232:233], 0, s[8:9]
	s_mov_b32 m0, s55
	s_nop 0
	global_load_lds_dwordx4 v[190:191], off
	s_waitcnt vmcnt(8)
	s_waitcnt lgkmcnt(0)
	s_barrier
	s_setprio 1
	s_waitcnt lgkmcnt(0)
	v_mfma_f32_16x16x32_bf16 v[60:63], v[142:145], v[174:177], v[60:63]
	v_mfma_f32_16x16x32_bf16 v[56:59], v[150:153], v[174:177], v[56:59]
	v_mfma_f32_16x16x32_bf16 v[44:47], v[142:145], v[182:185], v[44:47]
	v_mfma_f32_16x16x32_bf16 v[40:43], v[150:153], v[182:185], v[40:43]
	v_mfma_f32_16x16x32_bf16 v[28:31], v[142:145], v[208:211], v[28:31]
	v_mfma_f32_16x16x32_bf16 v[24:27], v[150:153], v[208:211], v[24:27]
	v_mfma_f32_16x16x32_bf16 v[12:15], v[142:145], v[222:225], v[12:15]
	v_mfma_f32_16x16x32_bf16 v[8:11], v[150:153], v[222:225], v[8:11]
	v_mfma_f32_16x16x32_bf16 v[60:63], v[146:149], v[178:181], v[60:63]
	v_mfma_f32_16x16x32_bf16 v[56:59], v[154:157], v[178:181], v[56:59]
	v_mfma_f32_16x16x32_bf16 v[44:47], v[146:149], v[186:189], v[44:47]
	v_mfma_f32_16x16x32_bf16 v[40:43], v[154:157], v[186:189], v[40:43]
	v_mfma_f32_16x16x32_bf16 v[28:31], v[146:149], v[214:217], v[28:31]
	v_mfma_f32_16x16x32_bf16 v[24:27], v[154:157], v[214:217], v[24:27]
	v_mfma_f32_16x16x32_bf16 v[12:15], v[146:149], v[226:229], v[12:15]
	v_mfma_f32_16x16x32_bf16 v[8:11], v[154:157], v[226:229], v[8:11]
	s_setprio 0
	s_setprio 1
	v_mfma_f32_16x16x32_bf16 v[52:55], v[158:161], v[174:177], v[52:55]
	v_mfma_f32_16x16x32_bf16 v[48:51], v[166:169], v[174:177], v[48:51]
	v_mfma_f32_16x16x32_bf16 v[36:39], v[158:161], v[182:185], v[36:39]
	v_mfma_f32_16x16x32_bf16 v[32:35], v[166:169], v[182:185], v[32:35]
	v_mfma_f32_16x16x32_bf16 v[20:23], v[158:161], v[208:211], v[20:23]
	v_mfma_f32_16x16x32_bf16 v[16:19], v[166:169], v[208:211], v[16:19]
	v_mfma_f32_16x16x32_bf16 v[4:7], v[158:161], v[222:225], v[4:7]
	v_mfma_f32_16x16x32_bf16 v[0:3], v[166:169], v[222:225], v[0:3]
	v_mfma_f32_16x16x32_bf16 v[52:55], v[162:165], v[178:181], v[52:55]
	v_mfma_f32_16x16x32_bf16 v[48:51], v[170:173], v[178:181], v[48:51]
	v_mfma_f32_16x16x32_bf16 v[36:39], v[162:165], v[186:189], v[36:39]
	v_mfma_f32_16x16x32_bf16 v[32:35], v[170:173], v[186:189], v[32:35]
	v_mfma_f32_16x16x32_bf16 v[20:23], v[162:165], v[214:217], v[20:23]
	v_mfma_f32_16x16x32_bf16 v[16:19], v[170:173], v[214:217], v[16:19]
	v_mfma_f32_16x16x32_bf16 v[4:7], v[162:165], v[226:229], v[4:7]
	v_mfma_f32_16x16x32_bf16 v[0:3], v[170:173], v[226:229], v[0:3]
	s_setprio 0
	s_barrier
	s_add_i32 s69, s69, 2
	s_add_u32 s4, s4, 0x100
	s_addc_u32 s5, s5, 0
	s_cmp_gt_u32 s69, 41
	s_cbranch_scc0 .LBB0_220
	s_add_u32 s4, s42, 0xffffff00
	s_addc_u32 s5, s43, -1
	s_and_b64 vcc, exec, s[40:41]
	s_cbranch_vccnz .LBB0_223
	v_mov_b32_e32 v0, 0
	s_mov_b32 s10, s92
	s_mov_b32 s1, s93
	s_mov_b64 s[26:27], s[30:31]
	s_mov_b32 s11, s68
	v_mov_b32_e32 v1, v0
	v_mov_b32_e32 v2, v0
	v_mov_b32_e32 v3, v0
	v_mov_b32_e32 v4, v0
	v_mov_b32_e32 v5, v0
	v_mov_b32_e32 v6, v0
	v_mov_b32_e32 v7, v0
	v_mov_b32_e32 v16, v0
	v_mov_b32_e32 v17, v0
	v_mov_b32_e32 v18, v0
	v_mov_b32_e32 v19, v0
	v_mov_b32_e32 v20, v0
	v_mov_b32_e32 v21, v0
	v_mov_b32_e32 v22, v0
	v_mov_b32_e32 v23, v0
	v_mov_b32_e32 v32, v0
	v_mov_b32_e32 v33, v0
	v_mov_b32_e32 v34, v0
	v_mov_b32_e32 v35, v0
	v_mov_b32_e32 v36, v0
	v_mov_b32_e32 v37, v0
	v_mov_b32_e32 v38, v0
	v_mov_b32_e32 v39, v0
	v_mov_b32_e32 v48, v0
	v_mov_b32_e32 v49, v0
	v_mov_b32_e32 v50, v0
	v_mov_b32_e32 v51, v0
	v_mov_b32_e32 v52, v0
	v_mov_b32_e32 v53, v0
	v_mov_b32_e32 v54, v0
	v_mov_b32_e32 v55, v0
	v_mov_b32_e32 v8, v0
	v_mov_b32_e32 v9, v0
	v_mov_b32_e32 v10, v0
	v_mov_b32_e32 v11, v0
	v_mov_b32_e32 v12, v0
	v_mov_b32_e32 v13, v0
	v_mov_b32_e32 v14, v0
	v_mov_b32_e32 v15, v0
	v_mov_b32_e32 v24, v0
	v_mov_b32_e32 v25, v0
	v_mov_b32_e32 v26, v0
	v_mov_b32_e32 v27, v0
	v_mov_b32_e32 v28, v0
	v_mov_b32_e32 v29, v0
	v_mov_b32_e32 v30, v0
	v_mov_b32_e32 v31, v0
	v_mov_b32_e32 v40, v0
	v_mov_b32_e32 v41, v0
	v_mov_b32_e32 v42, v0
	v_mov_b32_e32 v43, v0
	v_mov_b32_e32 v44, v0
	v_mov_b32_e32 v45, v0
	v_mov_b32_e32 v46, v0
	v_mov_b32_e32 v47, v0
	v_mov_b32_e32 v56, v0
	v_mov_b32_e32 v57, v0
	v_mov_b32_e32 v58, v0
	v_mov_b32_e32 v59, v0
	v_mov_b32_e32 v60, v0
	v_mov_b32_e32 v61, v0
	v_mov_b32_e32 v62, v0
	v_mov_b32_e32 v63, v0
	v_mov_b32_e32 v64, v0
	v_mov_b32_e32 v65, v0
	v_mov_b32_e32 v66, v0
	v_mov_b32_e32 v67, v0
	v_mov_b32_e32 v68, v0
	v_mov_b32_e32 v69, v0
	v_mov_b32_e32 v70, v0
	v_mov_b32_e32 v71, v0
	v_mov_b32_e32 v80, v0
	v_mov_b32_e32 v81, v0
	v_mov_b32_e32 v82, v0
	v_mov_b32_e32 v83, v0
	v_mov_b32_e32 v84, v0
	v_mov_b32_e32 v85, v0
	v_mov_b32_e32 v86, v0
	v_mov_b32_e32 v87, v0
	v_mov_b32_e32 v116, v0
	v_mov_b32_e32 v117, v0
	v_mov_b32_e32 v118, v0
	v_mov_b32_e32 v119, v0
	v_mov_b32_e32 v120, v0
	v_mov_b32_e32 v121, v0
	v_mov_b32_e32 v122, v0
	v_mov_b32_e32 v123, v0
	v_mov_b32_e32 v104, v0
	v_mov_b32_e32 v105, v0
	v_mov_b32_e32 v106, v0
	v_mov_b32_e32 v107, v0
	v_mov_b32_e32 v100, v0
	v_mov_b32_e32 v101, v0
	v_mov_b32_e32 v102, v0
	v_mov_b32_e32 v103, v0
	v_mov_b32_e32 v72, v0
	v_mov_b32_e32 v73, v0
	v_mov_b32_e32 v74, v0
	v_mov_b32_e32 v75, v0
	v_mov_b32_e32 v76, v0
	v_mov_b32_e32 v77, v0
	v_mov_b32_e32 v78, v0
	v_mov_b32_e32 v79, v0
	v_mov_b32_e32 v92, v0
	v_mov_b32_e32 v93, v0
	v_mov_b32_e32 v94, v0
	v_mov_b32_e32 v95, v0
	v_mov_b32_e32 v112, v0
	v_mov_b32_e32 v113, v0
	v_mov_b32_e32 v114, v0
	v_mov_b32_e32 v115, v0
	v_mov_b32_e32 v124, v0
	v_mov_b32_e32 v125, v0
	v_mov_b32_e32 v126, v0
	v_mov_b32_e32 v127, v0
	v_mov_b32_e32 v108, v0
	v_mov_b32_e32 v109, v0
	v_mov_b32_e32 v110, v0
	v_mov_b32_e32 v111, v0
	v_mov_b32_e32 v96, v0
	v_mov_b32_e32 v97, v0
	v_mov_b32_e32 v98, v0
	v_mov_b32_e32 v99, v0
	v_mov_b32_e32 v88, v0
	v_mov_b32_e32 v89, v0
	v_mov_b32_e32 v90, v0
	v_mov_b32_e32 v91, v0
	s_andn2_b64 vcc, exec, s[38:39]
	s_cbranch_vccnz .LBB0_224
	s_branch .LBB0_225

.LBB0_349:
	s_waitcnt lgkmcnt(0)
	s_add_u32 s10, s14, 0x5720000
	s_addc_u32 s11, s15, 0
	v_bfe_u32 v16, v14, 4, 2
	s_add_u32 s12, s12, 0x7720000
	v_and_b32_e32 v15, 15, v14
	v_lshlrev_b32_e32 v17, 3, v16
	v_lshlrev_b32_e32 v16, 4, v16
	v_lshlrev_b32_e32 v14, 2, v14
	s_addc_u32 s13, s13, 0
	s_and_b32 s26, s26, 3
	v_lshl_or_b32 v150, s17, 6, v15
	v_lshl_or_b32 v15, v15, 6, v16
	s_lshl_b32 s14, s17, 13
	v_and_b32_e32 v14, 32, v14
	s_add_i32 m0, s35, 0x18000
	v_lshl_add_u64 v[6:7], v[6:7], 0, s[8:9]
	v_bitop3_b32 v16, v15, s14, v14 bitop3:0xde
	s_lshl_b32 s14, s26, 12
	s_sext_i32_i8 s52, s2
	s_waitcnt vmcnt(2)
	s_barrier
	global_load_lds_dwordx4 v[6:7], off
	v_lshl_add_u64 v[4:5], v[4:5], 0, s[8:9]
	s_add_i32 m0, s35, 0x1a000
	s_add_i32 s2, s35, 0x8000
	s_add_i32 s50, s35, 0xa000
	v_bitop3_b32 v151, v15, s14, v14 bitop3:0xde
	global_load_lds_dwordx4 v[4:5], off
	v_lshl_add_u64 v[0:1], v[0:1], 0, s[8:9]
	s_mov_b32 m0, s2
	s_add_u32 s14, s4, 0x40080
	global_load_lds_dwordx4 v[0:1], off
	v_lshl_add_u64 v[0:1], v[2:3], 0, s[8:9]
	s_mov_b32 m0, s50
	s_addc_u32 s15, s5, 0
	global_load_lds_dwordx4 v[0:1], off
	s_add_i32 m0, s35, 0x1c000
	s_nop 0
	global_load_lds_dwordx4 v132, s[14:15]
	s_add_i32 m0, s35, 0x1e000
	s_cmpk_lt_u32 s16, 0x100
	global_load_lds_dwordx4 v128, s[14:15]
	v_lshlrev_b32_e32 v0, 14, v12
	v_and_b32_e32 v0, 0xffff8000, v0
	v_lshl_add_u32 v0, v11, 11, v0
	v_and_b32_e32 v1, 1, v12
	v_lshl_or_b32 v0, v1, 6, v0
	v_lshl_add_u32 v136, v13, 1, v0
	v_lshlrev_b32_e32 v0, 14, v8
	v_and_b32_e32 v0, 0xffff8000, v0
	s_waitcnt vmcnt(6)
	v_lshl_add_u32 v0, v9, 11, v0
	v_and_b32_e32 v1, 1, v8
	v_lshl_or_b32 v152, s26, 5, v17
	v_lshl_or_b32 v0, v1, 6, v0
	s_cselect_b64 s[14:15], -1, 0
	v_or_b32_e32 v153, 0xfffff800, v152
	v_mov_b32_e32 v137, v193
	v_lshl_add_u32 v138, v10, 1, v0
	v_mov_b32_e32 v139, v193
	s_mov_b32 s51, 0
	v_add_u32_e32 v154, 0, v16
	s_barrier
	s_branch .LBB0_352

.LBB0_355:
	s_add_u32 s4, s36, 0xfffc0080
	s_addc_u32 s5, s37, -1
	s_add_i32 s60, 0, 0x10000
	s_cmp_eq_u32 s59, 12
	s_cselect_b32 s41, s27, s5
	s_cselect_b32 s40, s53, s4
	v_add_u32_e32 v148, s60, v151
	s_cselect_b32 s5, s17, s58
	s_cselect_b32 s4, s54, s55
	s_add_i32 s62, 0, 0x14000
	ds_read_b128 v[140:143], v148
	ds_read_b128 v[144:147], v148 offset:1024
	ds_read_b128 v[156:159], v148 offset:2048
	ds_read_b128 v[160:163], v148 offset:3072
	v_add_u32_e32 v148, s62, v151
	ds_read_b128 v[164:167], v148
	ds_read_b128 v[168:171], v148 offset:1024
	ds_read_b128 v[172:175], v148 offset:2048
	ds_read_b128 v[176:179], v148 offset:3072
	s_add_i32 m0, s35, 0xc000
	ds_read_b128 v[180:183], v154
	ds_read_b128 v[184:187], v154 offset:1024
	ds_read_b128 v[188:191], v154 offset:2048
	ds_read_b128 v[208:211], v154 offset:3072
	ds_read_b128 v[212:215], v154 offset:4096
	ds_read_b128 v[216:219], v154 offset:5120
	ds_read_b128 v[220:223], v154 offset:6144
	ds_read_b128 v[224:227], v154 offset:7168
	global_load_lds_dwordx4 v136, s[36:37]
	s_add_i32 m0, s35, 0xe000
	s_nop 0
	global_load_lds_dwordx4 v138, s[36:37]
	s_waitcnt vmcnt(8)
	s_waitcnt lgkmcnt(0)
	s_barrier
	s_setprio 1
	s_waitcnt lgkmcnt(0)
	v_mfma_f32_16x16x32_bf16 v[124:127], v[140:143], v[180:183], v[124:127]
	v_mfma_f32_16x16x32_bf16 v[120:123], v[156:159], v[180:183], v[120:123]
	v_mfma_f32_16x16x32_bf16 v[112:115], v[140:143], v[188:191], v[112:115]
	v_mfma_f32_16x16x32_bf16 v[104:107], v[156:159], v[188:191], v[104:107]
	v_mfma_f32_16x16x32_bf16 v[96:99], v[140:143], v[212:215], v[96:99]
	v_mfma_f32_16x16x32_bf16 v[88:91], v[156:159], v[212:215], v[88:91]
	v_mfma_f32_16x16x32_bf16 v[80:83], v[140:143], v[220:223], v[80:83]
	v_mfma_f32_16x16x32_bf16 v[72:75], v[156:159], v[220:223], v[72:75]
	v_mfma_f32_16x16x32_bf16 v[124:127], v[144:147], v[184:187], v[124:127]
	v_mfma_f32_16x16x32_bf16 v[120:123], v[160:163], v[184:187], v[120:123]
	v_mfma_f32_16x16x32_bf16 v[112:115], v[144:147], v[208:211], v[112:115]
	v_mfma_f32_16x16x32_bf16 v[104:107], v[160:163], v[208:211], v[104:107]
	v_mfma_f32_16x16x32_bf16 v[96:99], v[144:147], v[216:219], v[96:99]
	v_mfma_f32_16x16x32_bf16 v[88:91], v[160:163], v[216:219], v[88:91]
	v_mfma_f32_16x16x32_bf16 v[80:83], v[144:147], v[224:227], v[80:83]
	v_mfma_f32_16x16x32_bf16 v[72:75], v[160:163], v[224:227], v[72:75]
	s_setprio 0
	s_setprio 1
	v_mfma_f32_16x16x32_bf16 v[116:119], v[164:167], v[180:183], v[116:119]
	v_mfma_f32_16x16x32_bf16 v[108:111], v[172:175], v[180:183], v[108:111]
	v_mfma_f32_16x16x32_bf16 v[100:103], v[164:167], v[188:191], v[100:103]
	v_mfma_f32_16x16x32_bf16 v[92:95], v[172:175], v[188:191], v[92:95]
	v_mfma_f32_16x16x32_bf16 v[84:87], v[164:167], v[212:215], v[84:87]
	v_mfma_f32_16x16x32_bf16 v[76:79], v[172:175], v[212:215], v[76:79]
	v_mfma_f32_16x16x32_bf16 v[68:71], v[164:167], v[220:223], v[68:71]
	v_mfma_f32_16x16x32_bf16 v[64:67], v[172:175], v[220:223], v[64:67]
	v_mfma_f32_16x16x32_bf16 v[116:119], v[168:171], v[184:187], v[116:119]
	v_mfma_f32_16x16x32_bf16 v[108:111], v[176:179], v[184:187], v[108:111]
	v_mfma_f32_16x16x32_bf16 v[100:103], v[168:171], v[208:211], v[100:103]
	v_mfma_f32_16x16x32_bf16 v[92:95], v[176:179], v[208:211], v[92:95]
	v_mfma_f32_16x16x32_bf16 v[84:87], v[168:171], v[216:219], v[84:87]
	v_mfma_f32_16x16x32_bf16 v[76:79], v[176:179], v[216:219], v[76:79]
	v_mfma_f32_16x16x32_bf16 v[68:71], v[168:171], v[224:227], v[68:71]
	v_mfma_f32_16x16x32_bf16 v[64:67], v[176:179], v[224:227], v[64:67]
	s_setprio 0
	s_barrier
	s_add_i32 s60, s60, s46
	v_lshl_add_u64 v[148:149], s[4:5], 0, v[132:133]
	s_mov_b32 m0, s60
	ds_read_b128 v[180:183], v154 offset:16384
	ds_read_b128 v[184:187], v154 offset:17408
	ds_read_b128 v[188:191], v154 offset:18432
	ds_read_b128 v[208:211], v154 offset:19456
	ds_read_b128 v[212:215], v154 offset:20480
	ds_read_b128 v[216:219], v154 offset:21504
	ds_read_b128 v[220:223], v154 offset:22528
	ds_read_b128 v[224:227], v154 offset:23552
	global_load_lds_dwordx4 v[148:149], off
	s_add_i32 m0, s60, 0x2000
	s_add_u32 s60, s4, 0x40000
	v_lshl_add_u64 v[228:229], s[4:5], 0, v[128:129]
	s_addc_u32 s61, s5, 0
	s_add_i32 s62, s62, s46
	global_load_lds_dwordx4 v[228:229], off
	s_mov_b32 m0, s62
	v_lshl_add_u64 v[232:233], s[40:41], 0, v[130:131]
	global_load_lds_dwordx4 v132, s[60:61]
	s_add_i32 m0, s62, 0x2000
	s_nop 0
	global_load_lds_dwordx4 v128, s[60:61]
	v_lshl_add_u64 v[230:231], s[40:41], 0, v[134:135]
	s_mov_b32 m0, s35
	s_nop 0
	global_load_lds_dwordx4 v[230:231], off
	s_mov_b32 m0, s47
	s_nop 0
	global_load_lds_dwordx4 v[232:233], off
	s_waitcnt vmcnt(8)
	s_waitcnt lgkmcnt(0)
	s_barrier
	s_setprio 1
	s_waitcnt lgkmcnt(0)
	v_mfma_f32_16x16x32_bf16 v[60:63], v[140:143], v[180:183], v[60:63]
	v_mfma_f32_16x16x32_bf16 v[56:59], v[156:159], v[180:183], v[56:59]
	v_mfma_f32_16x16x32_bf16 v[48:51], v[140:143], v[188:191], v[48:51]
	v_mfma_f32_16x16x32_bf16 v[40:43], v[156:159], v[188:191], v[40:43]
	v_mfma_f32_16x16x32_bf16 v[32:35], v[140:143], v[212:215], v[32:35]
	v_mfma_f32_16x16x32_bf16 v[24:27], v[156:159], v[212:215], v[24:27]
	v_mfma_f32_16x16x32_bf16 v[16:19], v[140:143], v[220:223], v[16:19]
	v_mfma_f32_16x16x32_bf16 v[8:11], v[156:159], v[220:223], v[8:11]
	v_mfma_f32_16x16x32_bf16 v[60:63], v[144:147], v[184:187], v[60:63]
	v_mfma_f32_16x16x32_bf16 v[56:59], v[160:163], v[184:187], v[56:59]
	v_mfma_f32_16x16x32_bf16 v[48:51], v[144:147], v[208:211], v[48:51]
	v_mfma_f32_16x16x32_bf16 v[40:43], v[160:163], v[208:211], v[40:43]
	v_mfma_f32_16x16x32_bf16 v[32:35], v[144:147], v[216:219], v[32:35]
	v_mfma_f32_16x16x32_bf16 v[24:27], v[160:163], v[216:219], v[24:27]
	v_mfma_f32_16x16x32_bf16 v[16:19], v[144:147], v[224:227], v[16:19]
	v_mfma_f32_16x16x32_bf16 v[8:11], v[160:163], v[224:227], v[8:11]
	s_setprio 0
	s_setprio 1
	v_mfma_f32_16x16x32_bf16 v[52:55], v[164:167], v[180:183], v[52:55]
	v_mfma_f32_16x16x32_bf16 v[44:47], v[172:175], v[180:183], v[44:47]
	v_mfma_f32_16x16x32_bf16 v[36:39], v[164:167], v[188:191], v[36:39]
	v_mfma_f32_16x16x32_bf16 v[28:31], v[172:175], v[188:191], v[28:31]
	v_mfma_f32_16x16x32_bf16 v[20:23], v[164:167], v[212:215], v[20:23]
	v_mfma_f32_16x16x32_bf16 v[12:15], v[172:175], v[212:215], v[12:15]
	v_mfma_f32_16x16x32_bf16 v[4:7], v[164:167], v[220:223], v[4:7]
	v_mfma_f32_16x16x32_bf16 v[0:3], v[172:175], v[220:223], v[0:3]
	v_mfma_f32_16x16x32_bf16 v[52:55], v[168:171], v[184:187], v[52:55]
	v_mfma_f32_16x16x32_bf16 v[44:47], v[176:179], v[184:187], v[44:47]
	v_mfma_f32_16x16x32_bf16 v[36:39], v[168:171], v[208:211], v[36:39]
	v_mfma_f32_16x16x32_bf16 v[28:31], v[176:179], v[208:211], v[28:31]
	v_mfma_f32_16x16x32_bf16 v[20:23], v[168:171], v[216:219], v[20:23]
	v_mfma_f32_16x16x32_bf16 v[12:15], v[176:179], v[216:219], v[12:15]
	v_mfma_f32_16x16x32_bf16 v[4:7], v[168:171], v[224:227], v[4:7]
	v_mfma_f32_16x16x32_bf16 v[0:3], v[176:179], v[224:227], v[0:3]
	s_setprio 0
	s_barrier
	s_add_i32 s60, 0, 0x18000
	v_add_u32_e32 v155, s60, v151
	s_add_i32 s61, 0, 0x1c000
	ds_read_b128 v[140:143], v155
	ds_read_b128 v[144:147], v155 offset:1024
	ds_read_b128 v[156:159], v155 offset:2048
	ds_read_b128 v[160:163], v155 offset:3072
	v_add_u32_e32 v155, s61, v151
	ds_read_b128 v[164:167], v155
	ds_read_b128 v[168:171], v155 offset:1024
	ds_read_b128 v[172:175], v155 offset:2048
	ds_read_b128 v[176:179], v155 offset:3072
	s_add_u32 s40, s40, 0x40000
	s_addc_u32 s41, s41, 0
	s_mov_b32 m0, s48
	ds_read_b128 v[180:183], v154 offset:32768
	ds_read_b128 v[184:187], v154 offset:33792
	ds_read_b128 v[188:191], v154 offset:34816
	ds_read_b128 v[208:211], v154 offset:35840
	ds_read_b128 v[212:215], v154 offset:36864
	ds_read_b128 v[216:219], v154 offset:37888
	ds_read_b128 v[220:223], v154 offset:38912
	ds_read_b128 v[224:227], v154 offset:39936
	global_load_lds_dwordx4 v134, s[40:41]
	v_lshl_add_u64 v[234:235], s[40:41], 0, v[130:131]
	s_mov_b32 m0, s49
	s_nop 0
	global_load_lds_dwordx4 v[234:235], off
	s_waitcnt vmcnt(8)
	s_waitcnt lgkmcnt(0)
	s_barrier
	s_setprio 1
	s_waitcnt lgkmcnt(0)
	v_mfma_f32_16x16x32_bf16 v[124:127], v[140:143], v[180:183], v[124:127]
	v_mfma_f32_16x16x32_bf16 v[120:123], v[156:159], v[180:183], v[120:123]
	v_mfma_f32_16x16x32_bf16 v[112:115], v[140:143], v[188:191], v[112:115]
	v_mfma_f32_16x16x32_bf16 v[104:107], v[156:159], v[188:191], v[104:107]
	v_mfma_f32_16x16x32_bf16 v[96:99], v[140:143], v[212:215], v[96:99]
	v_mfma_f32_16x16x32_bf16 v[88:91], v[156:159], v[212:215], v[88:91]
	v_mfma_f32_16x16x32_bf16 v[80:83], v[140:143], v[220:223], v[80:83]
	v_mfma_f32_16x16x32_bf16 v[72:75], v[156:159], v[220:223], v[72:75]
	v_mfma_f32_16x16x32_bf16 v[124:127], v[144:147], v[184:187], v[124:127]
	v_mfma_f32_16x16x32_bf16 v[120:123], v[160:163], v[184:187], v[120:123]
	v_mfma_f32_16x16x32_bf16 v[112:115], v[144:147], v[208:211], v[112:115]
	v_mfma_f32_16x16x32_bf16 v[104:107], v[160:163], v[208:211], v[104:107]
	v_mfma_f32_16x16x32_bf16 v[96:99], v[144:147], v[216:219], v[96:99]
	v_mfma_f32_16x16x32_bf16 v[88:91], v[160:163], v[216:219], v[88:91]
	v_mfma_f32_16x16x32_bf16 v[80:83], v[144:147], v[224:227], v[80:83]
	v_mfma_f32_16x16x32_bf16 v[72:75], v[160:163], v[224:227], v[72:75]
	s_setprio 0
	s_setprio 1
	v_mfma_f32_16x16x32_bf16 v[116:119], v[164:167], v[180:183], v[116:119]
	v_mfma_f32_16x16x32_bf16 v[108:111], v[172:175], v[180:183], v[108:111]
	v_mfma_f32_16x16x32_bf16 v[100:103], v[164:167], v[188:191], v[100:103]
	v_mfma_f32_16x16x32_bf16 v[92:95], v[172:175], v[188:191], v[92:95]
	v_mfma_f32_16x16x32_bf16 v[84:87], v[164:167], v[212:215], v[84:87]
	v_mfma_f32_16x16x32_bf16 v[76:79], v[172:175], v[212:215], v[76:79]
	v_mfma_f32_16x16x32_bf16 v[68:71], v[164:167], v[220:223], v[68:71]
	v_mfma_f32_16x16x32_bf16 v[64:67], v[172:175], v[220:223], v[64:67]
	v_mfma_f32_16x16x32_bf16 v[116:119], v[168:171], v[184:187], v[116:119]
	v_mfma_f32_16x16x32_bf16 v[108:111], v[176:179], v[184:187], v[108:111]
	v_mfma_f32_16x16x32_bf16 v[100:103], v[168:171], v[208:211], v[100:103]
	v_mfma_f32_16x16x32_bf16 v[92:95], v[176:179], v[208:211], v[92:95]
	v_mfma_f32_16x16x32_bf16 v[84:87], v[168:171], v[216:219], v[84:87]
	v_mfma_f32_16x16x32_bf16 v[76:79], v[176:179], v[216:219], v[76:79]
	v_mfma_f32_16x16x32_bf16 v[68:71], v[168:171], v[224:227], v[68:71]
	v_mfma_f32_16x16x32_bf16 v[64:67], v[176:179], v[224:227], v[64:67]
	s_setprio 0
	s_barrier
	s_add_i32 s40, s60, s46
	v_lshl_add_u64 v[148:149], v[148:149], 0, s[8:9]
	s_mov_b32 m0, s40
	ds_read_b128 v[180:183], v154 offset:49152
	ds_read_b128 v[184:187], v154 offset:50176
	ds_read_b128 v[188:191], v154 offset:51200
	ds_read_b128 v[208:211], v154 offset:52224
	ds_read_b128 v[212:215], v154 offset:53248
	ds_read_b128 v[216:219], v154 offset:54272
	ds_read_b128 v[220:223], v154 offset:55296
	ds_read_b128 v[224:227], v154 offset:56320
	global_load_lds_dwordx4 v[148:149], off
	s_add_i32 m0, s40, 0x2000
	s_add_u32 s4, s4, 0x40080
	v_lshl_add_u64 v[148:149], v[228:229], 0, s[8:9]
	s_addc_u32 s5, s5, 0
	s_add_i32 s40, s61, s46
	global_load_lds_dwordx4 v[148:149], off
	s_mov_b32 m0, s40
	s_nop 0
	global_load_lds_dwordx4 v132, s[4:5]
	s_add_i32 m0, s40, 0x2000
	s_nop 0
	global_load_lds_dwordx4 v128, s[4:5]
	v_lshl_add_u64 v[148:149], v[230:231], 0, s[8:9]
	s_mov_b32 m0, s2
	s_nop 0
	global_load_lds_dwordx4 v[148:149], off
	v_lshl_add_u64 v[148:149], v[232:233], 0, s[8:9]
	s_mov_b32 m0, s50
	s_nop 0
	global_load_lds_dwordx4 v[148:149], off
	s_waitcnt vmcnt(8)
	s_waitcnt lgkmcnt(0)
	s_barrier
	s_setprio 1
	s_waitcnt lgkmcnt(0)
	v_mfma_f32_16x16x32_bf16 v[60:63], v[140:143], v[180:183], v[60:63]
	v_mfma_f32_16x16x32_bf16 v[56:59], v[156:159], v[180:183], v[56:59]
	v_mfma_f32_16x16x32_bf16 v[48:51], v[140:143], v[188:191], v[48:51]
	v_mfma_f32_16x16x32_bf16 v[40:43], v[156:159], v[188:191], v[40:43]
	v_mfma_f32_16x16x32_bf16 v[32:35], v[140:143], v[212:215], v[32:35]
	v_mfma_f32_16x16x32_bf16 v[24:27], v[156:159], v[212:215], v[24:27]
	v_mfma_f32_16x16x32_bf16 v[16:19], v[140:143], v[220:223], v[16:19]
	v_mfma_f32_16x16x32_bf16 v[8:11], v[156:159], v[220:223], v[8:11]
	v_mfma_f32_16x16x32_bf16 v[60:63], v[144:147], v[184:187], v[60:63]
	v_mfma_f32_16x16x32_bf16 v[56:59], v[160:163], v[184:187], v[56:59]
	v_mfma_f32_16x16x32_bf16 v[48:51], v[144:147], v[208:211], v[48:51]
	v_mfma_f32_16x16x32_bf16 v[40:43], v[160:163], v[208:211], v[40:43]
	v_mfma_f32_16x16x32_bf16 v[32:35], v[144:147], v[216:219], v[32:35]
	v_mfma_f32_16x16x32_bf16 v[24:27], v[160:163], v[216:219], v[24:27]
	v_mfma_f32_16x16x32_bf16 v[16:19], v[144:147], v[224:227], v[16:19]
	v_mfma_f32_16x16x32_bf16 v[8:11], v[160:163], v[224:227], v[8:11]
	s_setprio 0
	s_setprio 1
	v_mfma_f32_16x16x32_bf16 v[52:55], v[164:167], v[180:183], v[52:55]
	v_mfma_f32_16x16x32_bf16 v[44:47], v[172:175], v[180:183], v[44:47]
	v_mfma_f32_16x16x32_bf16 v[36:39], v[164:167], v[188:191], v[36:39]
	v_mfma_f32_16x16x32_bf16 v[28:31], v[172:175], v[188:191], v[28:31]
	v_mfma_f32_16x16x32_bf16 v[20:23], v[164:167], v[212:215], v[20:23]
	v_mfma_f32_16x16x32_bf16 v[12:15], v[172:175], v[212:215], v[12:15]
	v_mfma_f32_16x16x32_bf16 v[4:7], v[164:167], v[220:223], v[4:7]
	v_mfma_f32_16x16x32_bf16 v[0:3], v[172:175], v[220:223], v[0:3]
	v_mfma_f32_16x16x32_bf16 v[52:55], v[168:171], v[184:187], v[52:55]
	v_mfma_f32_16x16x32_bf16 v[44:47], v[176:179], v[184:187], v[44:47]
	v_mfma_f32_16x16x32_bf16 v[36:39], v[168:171], v[208:211], v[36:39]
	v_mfma_f32_16x16x32_bf16 v[28:31], v[176:179], v[208:211], v[28:31]
	v_mfma_f32_16x16x32_bf16 v[20:23], v[168:171], v[216:219], v[20:23]
	v_mfma_f32_16x16x32_bf16 v[12:15], v[176:179], v[216:219], v[12:15]
	v_mfma_f32_16x16x32_bf16 v[4:7], v[168:171], v[224:227], v[4:7]
	v_mfma_f32_16x16x32_bf16 v[0:3], v[176:179], v[224:227], v[0:3]
	s_setprio 0
	s_barrier
	s_add_i32 s59, s59, 2
	s_add_u32 s36, s36, 0x100
	s_addc_u32 s37, s37, 0
	s_add_u32 s55, s55, 0x100
	s_addc_u32 s58, s58, 0
	s_cmp_gt_u32 s59, 13
	s_cbranch_scc0 .LBB0_355
	s_and_b64 vcc, exec, s[14:15]
	s_cbranch_vccz .LBB0_358
	s_barrier

.LBB0_485:
	s_add_u32 s97, s10, 0x5720000
	s_addc_u32 s60, s11, 0
	s_add_u32 s61, s12, 0xbb60000
	s_addc_u32 s62, s13, 0
	s_add_u32 s10, s26, 0x5700000
	s_addc_u32 s11, s27, 0
	s_add_u32 s12, s16, 0x5710000
	s_addc_u32 s13, s17, 0
	v_bfe_u32 v16, v8, 4, 2
	s_add_u32 s14, s14, 0x9b20000
	v_and_b32_e32 v15, 15, v8
	v_lshlrev_b32_e32 v18, 4, v16
	v_lshlrev_b32_e32 v8, 2, v8
	s_addc_u32 s15, s15, 0
	s_and_b32 s26, s28, 3
	v_lshl_or_b32 v158, s29, 6, v15
	v_lshl_or_b32 v15, v15, 6, v18
	s_lshl_b32 s16, s29, 13
	v_and_b32_e32 v8, 32, v8
	s_add_i32 m0, s51, 0x18000
	v_lshl_add_u64 v[6:7], v[6:7], 0, s[8:9]
	v_bitop3_b32 v18, v15, s16, v8 bitop3:0xde
	s_lshl_b32 s16, s26, 12
	s_waitcnt vmcnt(2)
	s_barrier
	global_load_lds_dwordx4 v[6:7], off
	v_lshl_add_u64 v[4:5], v[4:5], 0, s[8:9]
	s_add_i32 m0, s51, 0x1a000
	s_add_i32 s63, s51, 0x8000
	s_add_i32 s64, s51, 0xa000
	v_bitop3_b32 v159, v15, s16, v8 bitop3:0xde
	global_load_lds_dwordx4 v[4:5], off
	v_lshl_add_u64 v[0:1], v[0:1], 0, s[8:9]
	s_mov_b32 m0, s63
	s_add_u32 s16, s46, 0x40080
	global_load_lds_dwordx4 v[0:1], off
	v_lshl_add_u64 v[0:1], v[2:3], 0, s[8:9]
	s_mov_b32 m0, s64
	s_addc_u32 s17, s47, 0
	global_load_lds_dwordx4 v[0:1], off
	s_add_i32 m0, s51, 0x1c000
	s_nop 0
	global_load_lds_dwordx4 v192, s[16:17]
	s_add_i32 m0, s51, 0x1e000
	s_cmpk_lt_u32 s40, 0x100
	global_load_lds_dwordx4 v140, s[16:17]
	v_lshlrev_b32_e32 v0, 14, v9
	v_and_b32_e32 v0, 0xffff8000, v0
	v_lshl_add_u32 v0, v10, 11, v0
	v_and_b32_e32 v1, 1, v9
	v_lshl_or_b32 v0, v1, 6, v0
	v_lshl_add_u32 v142, v11, 1, v0
	v_lshlrev_b32_e32 v0, 14, v12
	v_and_b32_e32 v0, 0xffff8000, v0
	s_waitcnt vmcnt(6)
	v_lshl_add_u32 v0, v13, 11, v0
	v_and_b32_e32 v1, 1, v12
	v_lshlrev_b32_e32 v17, 3, v16
	s_cselect_b64 s[16:17], -1, 0
	s_bitcmp0_b32 s40, 6
	v_lshl_or_b32 v0, v1, 6, v0
	s_mov_b32 s65, 0
	s_cselect_b64 s[28:29], -1, 0
	v_cmp_eq_u32_e64 s[38:39], 0, v16
	v_cmp_lt_u32_e64 s[40:41], 1, v16
	v_lshl_or_b32 v160, s26, 5, v17
	v_mov_b32_e32 v143, v193
	v_lshl_add_u32 v144, v14, 1, v0
	v_mov_b32_e32 v145, v193
	v_add_u32_e32 v161, 0, v18
	s_barrier
	s_branch .LBB0_488

.LBB0_498:
	s_add_u32 s4, s26, 0xfffc0080
	s_addc_u32 s5, s27, -1
	s_add_i32 s70, 0, 0x10000
	s_cmp_eq_u32 s69, 12
	s_cselect_b32 s47, s35, s5
	s_cselect_b32 s46, s43, s4
	s_cselect_b32 s5, s31, s68
	s_cselect_b32 s4, vcc_lo, vcc_hi
	s_add_i32 s72, 0, 0x14000
	v_add_u32_e32 v150, s70, v159
	v_add_u32_e32 v170, s72, v159
	ds_read_b128 v[128:131], v150
	ds_read_b128 v[132:135], v150 offset:1024
	ds_read_b128 v[146:149], v150 offset:2048
	ds_read_b128 v[150:153], v150 offset:3072
	ds_read_b128 v[154:157], v170
	ds_read_b128 v[162:165], v170 offset:1024
	ds_read_b128 v[166:169], v170 offset:2048
	ds_read_b128 v[170:173], v170 offset:3072
	s_add_i32 m0, s51, 0xc000
	ds_read_b128 v[174:177], v161
	ds_read_b128 v[178:181], v161 offset:1024
	ds_read_b128 v[182:185], v161 offset:2048
	ds_read_b128 v[186:189], v161 offset:3072
	ds_read_b128 v[208:211], v161 offset:4096
	ds_read_b128 v[212:215], v161 offset:5120
	ds_read_b128 v[216:219], v161 offset:6144
	ds_read_b128 v[220:223], v161 offset:7168
	global_load_lds_dwordx4 v142, s[26:27]
	s_add_i32 m0, s51, 0xe000
	s_nop 0
	global_load_lds_dwordx4 v144, s[26:27]
	s_waitcnt vmcnt(8)
	s_waitcnt lgkmcnt(0)
	s_barrier
	s_setprio 1
	s_waitcnt lgkmcnt(0)
	v_mfma_f32_16x16x32_bf16 v[124:127], v[128:131], v[174:177], v[124:127]
	v_mfma_f32_16x16x32_bf16 v[120:123], v[146:149], v[174:177], v[120:123]
	v_mfma_f32_16x16x32_bf16 v[108:111], v[128:131], v[182:185], v[108:111]
	v_mfma_f32_16x16x32_bf16 v[104:107], v[146:149], v[182:185], v[104:107]
	v_mfma_f32_16x16x32_bf16 v[92:95], v[128:131], v[208:211], v[92:95]
	v_mfma_f32_16x16x32_bf16 v[88:91], v[146:149], v[208:211], v[88:91]
	v_mfma_f32_16x16x32_bf16 v[76:79], v[128:131], v[216:219], v[76:79]
	v_mfma_f32_16x16x32_bf16 v[72:75], v[146:149], v[216:219], v[72:75]
	v_mfma_f32_16x16x32_bf16 v[124:127], v[132:135], v[178:181], v[124:127]
	v_mfma_f32_16x16x32_bf16 v[120:123], v[150:153], v[178:181], v[120:123]
	v_mfma_f32_16x16x32_bf16 v[108:111], v[132:135], v[186:189], v[108:111]
	v_mfma_f32_16x16x32_bf16 v[104:107], v[150:153], v[186:189], v[104:107]
	v_mfma_f32_16x16x32_bf16 v[92:95], v[132:135], v[212:215], v[92:95]
	v_mfma_f32_16x16x32_bf16 v[88:91], v[150:153], v[212:215], v[88:91]
	v_mfma_f32_16x16x32_bf16 v[76:79], v[132:135], v[220:223], v[76:79]
	v_mfma_f32_16x16x32_bf16 v[72:75], v[150:153], v[220:223], v[72:75]
	s_setprio 0
	s_setprio 1
	v_mfma_f32_16x16x32_bf16 v[116:119], v[154:157], v[174:177], v[116:119]
	v_mfma_f32_16x16x32_bf16 v[112:115], v[166:169], v[174:177], v[112:115]
	v_mfma_f32_16x16x32_bf16 v[100:103], v[154:157], v[182:185], v[100:103]
	v_mfma_f32_16x16x32_bf16 v[96:99], v[166:169], v[182:185], v[96:99]
	v_mfma_f32_16x16x32_bf16 v[84:87], v[154:157], v[208:211], v[84:87]
	v_mfma_f32_16x16x32_bf16 v[80:83], v[166:169], v[208:211], v[80:83]
	v_mfma_f32_16x16x32_bf16 v[68:71], v[154:157], v[216:219], v[68:71]
	v_mfma_f32_16x16x32_bf16 v[64:67], v[166:169], v[216:219], v[64:67]
	v_mfma_f32_16x16x32_bf16 v[116:119], v[162:165], v[178:181], v[116:119]
	v_mfma_f32_16x16x32_bf16 v[112:115], v[170:173], v[178:181], v[112:115]
	v_mfma_f32_16x16x32_bf16 v[100:103], v[162:165], v[186:189], v[100:103]
	v_mfma_f32_16x16x32_bf16 v[96:99], v[170:173], v[186:189], v[96:99]
	v_mfma_f32_16x16x32_bf16 v[84:87], v[162:165], v[212:215], v[84:87]
	v_mfma_f32_16x16x32_bf16 v[80:83], v[170:173], v[212:215], v[80:83]
	v_mfma_f32_16x16x32_bf16 v[68:71], v[162:165], v[220:223], v[68:71]
	v_mfma_f32_16x16x32_bf16 v[64:67], v[170:173], v[220:223], v[64:67]
	s_setprio 0
	s_barrier
	s_add_i32 s70, s70, s93
	v_lshl_add_u64 v[190:191], s[4:5], 0, v[192:193]
	s_mov_b32 m0, s70
	ds_read_b128 v[174:177], v161 offset:16384
	ds_read_b128 v[178:181], v161 offset:17408
	ds_read_b128 v[182:185], v161 offset:18432
	ds_read_b128 v[186:189], v161 offset:19456
	ds_read_b128 v[208:211], v161 offset:20480
	ds_read_b128 v[212:215], v161 offset:21504
	ds_read_b128 v[216:219], v161 offset:22528
	ds_read_b128 v[220:223], v161 offset:23552
	global_load_lds_dwordx4 v[190:191], off
	s_add_i32 m0, s70, 0x2000
	s_add_u32 s70, s4, 0x40000
	v_lshl_add_u64 v[224:225], s[4:5], 0, v[140:141]
	s_addc_u32 s71, s5, 0
	s_add_i32 s72, s72, s93
	global_load_lds_dwordx4 v[224:225], off
	s_mov_b32 m0, s72
	v_lshl_add_u64 v[228:229], s[46:47], 0, v[138:139]
	global_load_lds_dwordx4 v192, s[70:71]
	s_add_i32 m0, s72, 0x2000
	s_nop 0
	global_load_lds_dwordx4 v140, s[70:71]
	v_lshl_add_u64 v[226:227], s[46:47], 0, v[136:137]
	s_mov_b32 m0, s51
	s_nop 0
	global_load_lds_dwordx4 v[226:227], off
	s_mov_b32 m0, s94
	s_nop 0
	global_load_lds_dwordx4 v[228:229], off
	s_waitcnt vmcnt(8)
	s_waitcnt lgkmcnt(0)
	s_barrier
	s_setprio 1
	s_waitcnt lgkmcnt(0)
	v_mfma_f32_16x16x32_bf16 v[60:63], v[128:131], v[174:177], v[60:63]
	v_mfma_f32_16x16x32_bf16 v[56:59], v[146:149], v[174:177], v[56:59]
	v_mfma_f32_16x16x32_bf16 v[44:47], v[128:131], v[182:185], v[44:47]
	v_mfma_f32_16x16x32_bf16 v[40:43], v[146:149], v[182:185], v[40:43]
	v_mfma_f32_16x16x32_bf16 v[28:31], v[128:131], v[208:211], v[28:31]
	v_mfma_f32_16x16x32_bf16 v[24:27], v[146:149], v[208:211], v[24:27]
	v_mfma_f32_16x16x32_bf16 v[12:15], v[128:131], v[216:219], v[12:15]
	v_mfma_f32_16x16x32_bf16 v[8:11], v[146:149], v[216:219], v[8:11]
	v_mfma_f32_16x16x32_bf16 v[60:63], v[132:135], v[178:181], v[60:63]
	v_mfma_f32_16x16x32_bf16 v[56:59], v[150:153], v[178:181], v[56:59]
	v_mfma_f32_16x16x32_bf16 v[44:47], v[132:135], v[186:189], v[44:47]
	v_mfma_f32_16x16x32_bf16 v[40:43], v[150:153], v[186:189], v[40:43]
	v_mfma_f32_16x16x32_bf16 v[28:31], v[132:135], v[212:215], v[28:31]
	v_mfma_f32_16x16x32_bf16 v[24:27], v[150:153], v[212:215], v[24:27]
	v_mfma_f32_16x16x32_bf16 v[12:15], v[132:135], v[220:223], v[12:15]
	v_mfma_f32_16x16x32_bf16 v[8:11], v[150:153], v[220:223], v[8:11]
	s_setprio 0
	s_setprio 1
	v_mfma_f32_16x16x32_bf16 v[52:55], v[154:157], v[174:177], v[52:55]
	v_mfma_f32_16x16x32_bf16 v[48:51], v[166:169], v[174:177], v[48:51]
	v_mfma_f32_16x16x32_bf16 v[36:39], v[154:157], v[182:185], v[36:39]
	v_mfma_f32_16x16x32_bf16 v[32:35], v[166:169], v[182:185], v[32:35]
	v_mfma_f32_16x16x32_bf16 v[20:23], v[154:157], v[208:211], v[20:23]
	v_mfma_f32_16x16x32_bf16 v[16:19], v[166:169], v[208:211], v[16:19]
	v_mfma_f32_16x16x32_bf16 v[4:7], v[154:157], v[216:219], v[4:7]
	v_mfma_f32_16x16x32_bf16 v[0:3], v[166:169], v[216:219], v[0:3]
	v_mfma_f32_16x16x32_bf16 v[52:55], v[162:165], v[178:181], v[52:55]
	v_mfma_f32_16x16x32_bf16 v[48:51], v[170:173], v[178:181], v[48:51]
	v_mfma_f32_16x16x32_bf16 v[36:39], v[162:165], v[186:189], v[36:39]
	v_mfma_f32_16x16x32_bf16 v[32:35], v[170:173], v[186:189], v[32:35]
	v_mfma_f32_16x16x32_bf16 v[20:23], v[162:165], v[212:215], v[20:23]
	v_mfma_f32_16x16x32_bf16 v[16:19], v[170:173], v[212:215], v[16:19]
	v_mfma_f32_16x16x32_bf16 v[4:7], v[162:165], v[220:223], v[4:7]
	v_mfma_f32_16x16x32_bf16 v[0:3], v[170:173], v[220:223], v[0:3]
	s_setprio 0
	s_barrier
	s_add_i32 s70, 0, 0x18000
	s_add_i32 s71, 0, 0x1c000
	v_add_u32_e32 v150, s70, v159
	v_add_u32_e32 v170, s71, v159
	ds_read_b128 v[128:131], v150
	ds_read_b128 v[132:135], v150 offset:1024
	ds_read_b128 v[146:149], v150 offset:2048
	ds_read_b128 v[150:153], v150 offset:3072
	ds_read_b128 v[154:157], v170
	ds_read_b128 v[162:165], v170 offset:1024
	ds_read_b128 v[166:169], v170 offset:2048
	ds_read_b128 v[170:173], v170 offset:3072
	s_add_u32 s46, s46, 0x40000
	s_addc_u32 s47, s47, 0
	s_mov_b32 m0, s95
	ds_read_b128 v[174:177], v161 offset:32768
	ds_read_b128 v[178:181], v161 offset:33792
	ds_read_b128 v[182:185], v161 offset:34816
	ds_read_b128 v[186:189], v161 offset:35840
	ds_read_b128 v[208:211], v161 offset:36864
	ds_read_b128 v[212:215], v161 offset:37888
	ds_read_b128 v[216:219], v161 offset:38912
	ds_read_b128 v[220:223], v161 offset:39936
	global_load_lds_dwordx4 v136, s[46:47]
	v_lshl_add_u64 v[230:231], s[46:47], 0, v[138:139]
	s_mov_b32 m0, s96
	s_nop 0
	global_load_lds_dwordx4 v[230:231], off
	s_waitcnt vmcnt(8)
	s_waitcnt lgkmcnt(0)
	s_barrier
	s_setprio 1
	s_waitcnt lgkmcnt(0)
	v_mfma_f32_16x16x32_bf16 v[124:127], v[128:131], v[174:177], v[124:127]
	v_mfma_f32_16x16x32_bf16 v[120:123], v[146:149], v[174:177], v[120:123]
	v_mfma_f32_16x16x32_bf16 v[108:111], v[128:131], v[182:185], v[108:111]
	v_mfma_f32_16x16x32_bf16 v[104:107], v[146:149], v[182:185], v[104:107]
	v_mfma_f32_16x16x32_bf16 v[92:95], v[128:131], v[208:211], v[92:95]
	v_mfma_f32_16x16x32_bf16 v[88:91], v[146:149], v[208:211], v[88:91]
	v_mfma_f32_16x16x32_bf16 v[76:79], v[128:131], v[216:219], v[76:79]
	v_mfma_f32_16x16x32_bf16 v[72:75], v[146:149], v[216:219], v[72:75]
	v_mfma_f32_16x16x32_bf16 v[124:127], v[132:135], v[178:181], v[124:127]
	v_mfma_f32_16x16x32_bf16 v[120:123], v[150:153], v[178:181], v[120:123]
	v_mfma_f32_16x16x32_bf16 v[108:111], v[132:135], v[186:189], v[108:111]
	v_mfma_f32_16x16x32_bf16 v[104:107], v[150:153], v[186:189], v[104:107]
	v_mfma_f32_16x16x32_bf16 v[92:95], v[132:135], v[212:215], v[92:95]
	v_mfma_f32_16x16x32_bf16 v[88:91], v[150:153], v[212:215], v[88:91]
	v_mfma_f32_16x16x32_bf16 v[76:79], v[132:135], v[220:223], v[76:79]
	v_mfma_f32_16x16x32_bf16 v[72:75], v[150:153], v[220:223], v[72:75]
	s_setprio 0
	s_setprio 1
	v_mfma_f32_16x16x32_bf16 v[116:119], v[154:157], v[174:177], v[116:119]
	v_mfma_f32_16x16x32_bf16 v[112:115], v[166:169], v[174:177], v[112:115]
	v_mfma_f32_16x16x32_bf16 v[100:103], v[154:157], v[182:185], v[100:103]
	v_mfma_f32_16x16x32_bf16 v[96:99], v[166:169], v[182:185], v[96:99]
	v_mfma_f32_16x16x32_bf16 v[84:87], v[154:157], v[208:211], v[84:87]
	v_mfma_f32_16x16x32_bf16 v[80:83], v[166:169], v[208:211], v[80:83]
	v_mfma_f32_16x16x32_bf16 v[68:71], v[154:157], v[216:219], v[68:71]
	v_mfma_f32_16x16x32_bf16 v[64:67], v[166:169], v[216:219], v[64:67]
	v_mfma_f32_16x16x32_bf16 v[116:119], v[162:165], v[178:181], v[116:119]
	v_mfma_f32_16x16x32_bf16 v[112:115], v[170:173], v[178:181], v[112:115]
	v_mfma_f32_16x16x32_bf16 v[100:103], v[162:165], v[186:189], v[100:103]
	v_mfma_f32_16x16x32_bf16 v[96:99], v[170:173], v[186:189], v[96:99]
	v_mfma_f32_16x16x32_bf16 v[84:87], v[162:165], v[212:215], v[84:87]
	v_mfma_f32_16x16x32_bf16 v[80:83], v[170:173], v[212:215], v[80:83]
	v_mfma_f32_16x16x32_bf16 v[68:71], v[162:165], v[220:223], v[68:71]
	v_mfma_f32_16x16x32_bf16 v[64:67], v[170:173], v[220:223], v[64:67]
	s_setprio 0
	s_barrier
	s_add_i32 s46, s70, s93
	v_lshl_add_u64 v[190:191], v[190:191], 0, s[8:9]
	s_mov_b32 m0, s46
	ds_read_b128 v[174:177], v161 offset:49152
	ds_read_b128 v[178:181], v161 offset:50176
	ds_read_b128 v[182:185], v161 offset:51200
	ds_read_b128 v[186:189], v161 offset:52224
	ds_read_b128 v[208:211], v161 offset:53248
	ds_read_b128 v[212:215], v161 offset:54272
	ds_read_b128 v[216:219], v161 offset:55296
	ds_read_b128 v[220:223], v161 offset:56320
	global_load_lds_dwordx4 v[190:191], off
	s_add_i32 m0, s46, 0x2000
	s_add_u32 s4, s4, 0x40080
	v_lshl_add_u64 v[190:191], v[224:225], 0, s[8:9]
	s_addc_u32 s5, s5, 0
	s_add_i32 s46, s71, s93
	global_load_lds_dwordx4 v[190:191], off
	s_mov_b32 m0, s46
	s_nop 0
	global_load_lds_dwordx4 v192, s[4:5]
	s_add_i32 m0, s46, 0x2000
	s_nop 0
	global_load_lds_dwordx4 v140, s[4:5]
	v_lshl_add_u64 v[190:191], v[226:227], 0, s[8:9]
	s_mov_b32 m0, s63
	s_nop 0
	global_load_lds_dwordx4 v[190:191], off
	v_lshl_add_u64 v[190:191], v[228:229], 0, s[8:9]
	s_mov_b32 m0, s64
	s_nop 0
	global_load_lds_dwordx4 v[190:191], off
	s_waitcnt vmcnt(8)
	s_waitcnt lgkmcnt(0)
	s_barrier
	s_setprio 1
	s_waitcnt lgkmcnt(0)
	v_mfma_f32_16x16x32_bf16 v[60:63], v[128:131], v[174:177], v[60:63]
	v_mfma_f32_16x16x32_bf16 v[56:59], v[146:149], v[174:177], v[56:59]
	v_mfma_f32_16x16x32_bf16 v[44:47], v[128:131], v[182:185], v[44:47]
	v_mfma_f32_16x16x32_bf16 v[40:43], v[146:149], v[182:185], v[40:43]
	v_mfma_f32_16x16x32_bf16 v[28:31], v[128:131], v[208:211], v[28:31]
	v_mfma_f32_16x16x32_bf16 v[24:27], v[146:149], v[208:211], v[24:27]
	v_mfma_f32_16x16x32_bf16 v[12:15], v[128:131], v[216:219], v[12:15]
	v_mfma_f32_16x16x32_bf16 v[8:11], v[146:149], v[216:219], v[8:11]
	v_mfma_f32_16x16x32_bf16 v[60:63], v[132:135], v[178:181], v[60:63]
	v_mfma_f32_16x16x32_bf16 v[56:59], v[150:153], v[178:181], v[56:59]
	v_mfma_f32_16x16x32_bf16 v[44:47], v[132:135], v[186:189], v[44:47]
	v_mfma_f32_16x16x32_bf16 v[40:43], v[150:153], v[186:189], v[40:43]
	v_mfma_f32_16x16x32_bf16 v[28:31], v[132:135], v[212:215], v[28:31]
	v_mfma_f32_16x16x32_bf16 v[24:27], v[150:153], v[212:215], v[24:27]
	v_mfma_f32_16x16x32_bf16 v[12:15], v[132:135], v[220:223], v[12:15]
	v_mfma_f32_16x16x32_bf16 v[8:11], v[150:153], v[220:223], v[8:11]
	s_setprio 0
	s_setprio 1
	v_mfma_f32_16x16x32_bf16 v[52:55], v[154:157], v[174:177], v[52:55]
	v_mfma_f32_16x16x32_bf16 v[48:51], v[166:169], v[174:177], v[48:51]
	v_mfma_f32_16x16x32_bf16 v[36:39], v[154:157], v[182:185], v[36:39]
	v_mfma_f32_16x16x32_bf16 v[32:35], v[166:169], v[182:185], v[32:35]
	v_mfma_f32_16x16x32_bf16 v[20:23], v[154:157], v[208:211], v[20:23]
	v_mfma_f32_16x16x32_bf16 v[16:19], v[166:169], v[208:211], v[16:19]
	v_mfma_f32_16x16x32_bf16 v[4:7], v[154:157], v[216:219], v[4:7]
	v_mfma_f32_16x16x32_bf16 v[0:3], v[166:169], v[216:219], v[0:3]
	v_mfma_f32_16x16x32_bf16 v[52:55], v[162:165], v[178:181], v[52:55]
	v_mfma_f32_16x16x32_bf16 v[48:51], v[170:173], v[178:181], v[48:51]
	v_mfma_f32_16x16x32_bf16 v[36:39], v[162:165], v[186:189], v[36:39]
	v_mfma_f32_16x16x32_bf16 v[32:35], v[170:173], v[186:189], v[32:35]
	v_mfma_f32_16x16x32_bf16 v[20:23], v[162:165], v[212:215], v[20:23]
	v_mfma_f32_16x16x32_bf16 v[16:19], v[170:173], v[212:215], v[16:19]
	v_mfma_f32_16x16x32_bf16 v[4:7], v[162:165], v[220:223], v[4:7]
	v_mfma_f32_16x16x32_bf16 v[0:3], v[170:173], v[220:223], v[0:3]
	s_setprio 0
	s_barrier
	s_add_i32 s69, s69, 2
	s_add_u32 s26, s26, 0x100
	s_addc_u32 s27, s27, 0
	s_add_u32 vcc_hi, vcc_hi, 0x100
	s_addc_u32 s68, s68, 0
	s_cmp_gt_u32 s69, 13
	s_cbranch_scc0 .LBB0_498
	s_and_b64 vcc, exec, s[16:17]
	s_cbranch_vccz .LBB0_501
	s_barrier

.LBB0_714:
	v_readlane_b32 s30, v252, 1
	v_readlane_b32 s31, v252, 2
	s_lshl_b64 s[30:31], s[30:31], 13
	s_add_u32 s70, s28, s30
	s_addc_u32 s71, s29, s31
	s_add_u32 s28, s26, 0xbb60000
	s_addc_u32 s29, s27, 0
	s_add_u32 s30, s12, 0x5720000
	s_addc_u32 s31, s13, 0
	s_add_u32 s34, s34, 0xbb60800
	s_addc_u32 s35, s35, 0
	s_add_u32 s36, s70, 0x1000
	s_addc_u32 s37, s71, 0
	s_add_u32 s10, s10, 0x5720000
	v_lshrrev_b32_e32 v16, 1, v8
	s_addc_u32 s11, s11, 0
	v_and_b32_e32 v16, 24, v16
	s_add_u32 s12, s4, 0x9b20000
	v_and_b32_e32 v15, 15, v8
	v_lshlrev_b32_e32 v17, 1, v16
	v_lshlrev_b32_e32 v8, 2, v8
	s_addc_u32 s13, s5, 0
	v_lshl_or_b32 v244, s44, 6, v15
	v_lshl_or_b32 v15, v15, 6, v17
	s_lshl_b32 s4, s44, 13
	v_and_b32_e32 v8, 32, v8
	v_bitop3_b32 v17, v15, s4, v8 bitop3:0xde
	s_lshl_b32 s4, s45, 5
	s_and_b32 s7, s4, 0x60
	s_add_i32 m0, s51, 0x18000
	v_lshl_add_u64 v[6:7], v[6:7], 0, s[8:9]
	s_lshl_b32 s4, s7, 7
	s_waitcnt vmcnt(2)
	s_barrier
	global_load_lds_dwordx4 v[6:7], off
	v_lshl_add_u64 v[4:5], v[4:5], 0, s[8:9]
	s_add_i32 m0, s51, 0x1a000
	s_add_i32 s58, s51, 0x8000
	s_add_i32 s92, s51, 0xa000
	v_bitop3_b32 v245, v15, s4, v8 bitop3:0xde
	global_load_lds_dwordx4 v[4:5], off
	v_lshl_add_u64 v[0:1], v[0:1], 0, s[8:9]
	s_mov_b32 m0, s58
	s_add_u32 s4, s16, 0x40080
	global_load_lds_dwordx4 v[0:1], off
	v_lshl_add_u64 v[0:1], v[2:3], 0, s[8:9]
	s_mov_b32 m0, s92
	s_addc_u32 s5, s17, 0
	global_load_lds_dwordx4 v[0:1], off
	s_add_i32 m0, s51, 0x1c000
	s_nop 0
	global_load_lds_dwordx4 v192, s[4:5]
	s_add_i32 m0, s51, 0x1e000
	s_cmpk_lt_u32 s0, 0x100
	global_load_lds_dwordx4 v140, s[4:5]
	v_lshlrev_b32_e32 v0, 14, v9
	v_and_b32_e32 v0, 0xffff8000, v0
	v_lshl_add_u32 v0, v10, 11, v0
	v_and_b32_e32 v1, 1, v9
	v_lshl_or_b32 v0, v1, 6, v0
	v_lshl_add_u32 v142, v11, 1, v0
	v_lshlrev_b32_e32 v0, 14, v12
	v_and_b32_e32 v0, 0xffff8000, v0
	s_waitcnt vmcnt(6)
	v_lshl_add_u32 v0, v13, 11, v0
	v_and_b32_e32 v1, 1, v12
	s_cselect_b64 s[4:5], -1, 0
	v_lshl_or_b32 v0, v1, 6, v0
	v_writelane_b32 v252, s4, 15
	v_or_b32_e32 v246, s7, v16
	v_mov_b32_e32 v143, v193
	v_lshl_add_u32 v144, v14, 1, v0
	v_mov_b32_e32 v145, v193
	s_mov_b32 s93, 0
	v_add_u32_e32 v247, 0, v17
	s_barrier
	v_writelane_b32 v252, s5, 16
	s_branch .LBB0_717

.LBB0_727:
	s_add_u32 s14, vcc_lo, 0xfffc0080
	s_addc_u32 s15, vcc_hi, -1
	s_add_i32 s64, 0, 0x10000
	s_cmp_eq_u32 s63, 12
	s_cselect_b32 s17, s7, s15
	s_cselect_b32 s16, s27, s14
	s_cselect_b32 s15, s47, s62
	s_cselect_b32 s14, s60, s61
	s_add_i32 s66, 0, 0x14000
	v_add_u32_e32 v150, s64, v245
	v_add_u32_e32 v166, s66, v245
	ds_read_b128 v[128:131], v150
	ds_read_b128 v[132:135], v150 offset:1024
	ds_read_b128 v[146:149], v150 offset:2048
	ds_read_b128 v[150:153], v150 offset:3072
	ds_read_b128 v[154:157], v166
	ds_read_b128 v[158:161], v166 offset:1024
	ds_read_b128 v[162:165], v166 offset:2048
	ds_read_b128 v[166:169], v166 offset:3072
	v_lshl_add_u64 v[190:191], vcc, 0, v[142:143]
	s_add_i32 m0, s51, 0xc000
	ds_read_b128 v[170:173], v247
	ds_read_b128 v[174:177], v247 offset:1024
	ds_read_b128 v[178:181], v247 offset:2048
	ds_read_b128 v[182:185], v247 offset:3072
	ds_read_b128 v[186:189], v247 offset:4096
	ds_read_b128 v[208:211], v247 offset:5120
	ds_read_b128 v[212:215], v247 offset:6144
	ds_read_b128 v[216:219], v247 offset:7168
	global_load_lds_dwordx4 v[190:191], off
	v_lshl_add_u64 v[190:191], vcc, 0, v[144:145]
	s_add_i32 m0, s51, 0xe000
	s_nop 0
	global_load_lds_dwordx4 v[190:191], off
	s_waitcnt vmcnt(8)
	s_waitcnt lgkmcnt(0)
	s_barrier
	s_setprio 1
	s_waitcnt lgkmcnt(0)
	v_mfma_f32_16x16x32_bf16 v[124:127], v[128:131], v[170:173], v[124:127]
	v_mfma_f32_16x16x32_bf16 v[120:123], v[146:149], v[170:173], v[120:123]
	v_mfma_f32_16x16x32_bf16 v[116:119], v[128:131], v[178:181], v[116:119]
	v_mfma_f32_16x16x32_bf16 v[112:115], v[146:149], v[178:181], v[112:115]
	v_mfma_f32_16x16x32_bf16 v[108:111], v[128:131], v[186:189], v[108:111]
	v_mfma_f32_16x16x32_bf16 v[104:107], v[146:149], v[186:189], v[104:107]
	v_mfma_f32_16x16x32_bf16 v[100:103], v[128:131], v[212:215], v[100:103]
	v_mfma_f32_16x16x32_bf16 v[96:99], v[146:149], v[212:215], v[96:99]
	v_mfma_f32_16x16x32_bf16 v[124:127], v[132:135], v[174:177], v[124:127]
	v_mfma_f32_16x16x32_bf16 v[120:123], v[150:153], v[174:177], v[120:123]
	v_mfma_f32_16x16x32_bf16 v[116:119], v[132:135], v[182:185], v[116:119]
	v_mfma_f32_16x16x32_bf16 v[112:115], v[150:153], v[182:185], v[112:115]
	v_mfma_f32_16x16x32_bf16 v[108:111], v[132:135], v[208:211], v[108:111]
	v_mfma_f32_16x16x32_bf16 v[104:107], v[150:153], v[208:211], v[104:107]
	v_mfma_f32_16x16x32_bf16 v[100:103], v[132:135], v[216:219], v[100:103]
	v_mfma_f32_16x16x32_bf16 v[96:99], v[150:153], v[216:219], v[96:99]
	s_setprio 0
	s_setprio 1
	v_mfma_f32_16x16x32_bf16 v[60:63], v[154:157], v[170:173], v[60:63]
	v_mfma_f32_16x16x32_bf16 v[56:59], v[162:165], v[170:173], v[56:59]
	v_mfma_f32_16x16x32_bf16 v[52:55], v[154:157], v[178:181], v[52:55]
	v_mfma_f32_16x16x32_bf16 v[48:51], v[162:165], v[178:181], v[48:51]
	v_mfma_f32_16x16x32_bf16 v[44:47], v[154:157], v[186:189], v[44:47]
	v_mfma_f32_16x16x32_bf16 v[40:43], v[162:165], v[186:189], v[40:43]
	v_mfma_f32_16x16x32_bf16 v[36:39], v[154:157], v[212:215], v[36:39]
	v_mfma_f32_16x16x32_bf16 v[32:35], v[162:165], v[212:215], v[32:35]
	v_mfma_f32_16x16x32_bf16 v[60:63], v[158:161], v[174:177], v[60:63]
	v_mfma_f32_16x16x32_bf16 v[56:59], v[166:169], v[174:177], v[56:59]
	v_mfma_f32_16x16x32_bf16 v[52:55], v[158:161], v[182:185], v[52:55]
	v_mfma_f32_16x16x32_bf16 v[48:51], v[166:169], v[182:185], v[48:51]
	v_mfma_f32_16x16x32_bf16 v[44:47], v[158:161], v[208:211], v[44:47]
	v_mfma_f32_16x16x32_bf16 v[40:43], v[166:169], v[208:211], v[40:43]
	v_mfma_f32_16x16x32_bf16 v[36:39], v[158:161], v[216:219], v[36:39]
	v_mfma_f32_16x16x32_bf16 v[32:35], v[166:169], v[216:219], v[32:35]
	s_setprio 0
	s_barrier
	s_add_i32 s64, s64, s50
	v_lshl_add_u64 v[190:191], s[14:15], 0, v[192:193]
	s_mov_b32 m0, s64
	ds_read_b128 v[170:173], v247 offset:16384
	ds_read_b128 v[174:177], v247 offset:17408
	ds_read_b128 v[178:181], v247 offset:18432
	ds_read_b128 v[182:185], v247 offset:19456
	ds_read_b128 v[186:189], v247 offset:20480
	ds_read_b128 v[208:211], v247 offset:21504
	ds_read_b128 v[212:215], v247 offset:22528
	ds_read_b128 v[216:219], v247 offset:23552
	global_load_lds_dwordx4 v[190:191], off
	s_add_i32 m0, s64, 0x2000
	s_add_u32 s64, s14, 0x40000
	v_lshl_add_u64 v[220:221], s[14:15], 0, v[140:141]
	s_addc_u32 s65, s15, 0
	s_add_i32 s66, s66, s50
	global_load_lds_dwordx4 v[220:221], off
	s_mov_b32 m0, s66
	v_lshl_add_u64 v[224:225], s[16:17], 0, v[138:139]
	global_load_lds_dwordx4 v192, s[64:65]
	s_add_i32 m0, s66, 0x2000
	s_nop 0
	global_load_lds_dwordx4 v140, s[64:65]
	v_lshl_add_u64 v[222:223], s[16:17], 0, v[136:137]
	s_mov_b32 m0, s51
	s_nop 0
	global_load_lds_dwordx4 v[222:223], off
	s_mov_b32 m0, s53
	s_nop 0
	global_load_lds_dwordx4 v[224:225], off
	s_waitcnt vmcnt(8)
	s_waitcnt lgkmcnt(0)
	s_barrier
	s_setprio 1
	s_waitcnt lgkmcnt(0)
	v_mfma_f32_16x16x32_bf16 v[92:95], v[128:131], v[170:173], v[92:95]
	v_mfma_f32_16x16x32_bf16 v[88:91], v[146:149], v[170:173], v[88:91]
	v_mfma_f32_16x16x32_bf16 v[84:87], v[128:131], v[178:181], v[84:87]
	v_mfma_f32_16x16x32_bf16 v[80:83], v[146:149], v[178:181], v[80:83]
	v_mfma_f32_16x16x32_bf16 v[76:79], v[128:131], v[186:189], v[76:79]
	v_mfma_f32_16x16x32_bf16 v[72:75], v[146:149], v[186:189], v[72:75]
	v_mfma_f32_16x16x32_bf16 v[68:71], v[128:131], v[212:215], v[68:71]
	v_mfma_f32_16x16x32_bf16 v[64:67], v[146:149], v[212:215], v[64:67]
	v_mfma_f32_16x16x32_bf16 v[92:95], v[132:135], v[174:177], v[92:95]
	v_mfma_f32_16x16x32_bf16 v[88:91], v[150:153], v[174:177], v[88:91]
	v_mfma_f32_16x16x32_bf16 v[84:87], v[132:135], v[182:185], v[84:87]
	v_mfma_f32_16x16x32_bf16 v[80:83], v[150:153], v[182:185], v[80:83]
	v_mfma_f32_16x16x32_bf16 v[76:79], v[132:135], v[208:211], v[76:79]
	v_mfma_f32_16x16x32_bf16 v[72:75], v[150:153], v[208:211], v[72:75]
	v_mfma_f32_16x16x32_bf16 v[68:71], v[132:135], v[216:219], v[68:71]
	v_mfma_f32_16x16x32_bf16 v[64:67], v[150:153], v[216:219], v[64:67]
	s_setprio 0
	s_setprio 1
	v_mfma_f32_16x16x32_bf16 v[28:31], v[154:157], v[170:173], v[28:31]
	v_mfma_f32_16x16x32_bf16 v[24:27], v[162:165], v[170:173], v[24:27]
	v_mfma_f32_16x16x32_bf16 v[20:23], v[154:157], v[178:181], v[20:23]
	v_mfma_f32_16x16x32_bf16 v[16:19], v[162:165], v[178:181], v[16:19]
	v_mfma_f32_16x16x32_bf16 v[12:15], v[154:157], v[186:189], v[12:15]
	v_mfma_f32_16x16x32_bf16 v[8:11], v[162:165], v[186:189], v[8:11]
	v_mfma_f32_16x16x32_bf16 v[4:7], v[154:157], v[212:215], v[4:7]
	v_mfma_f32_16x16x32_bf16 v[0:3], v[162:165], v[212:215], v[0:3]
	v_mfma_f32_16x16x32_bf16 v[28:31], v[158:161], v[174:177], v[28:31]
	v_mfma_f32_16x16x32_bf16 v[24:27], v[166:169], v[174:177], v[24:27]
	v_mfma_f32_16x16x32_bf16 v[20:23], v[158:161], v[182:185], v[20:23]
	v_mfma_f32_16x16x32_bf16 v[16:19], v[166:169], v[182:185], v[16:19]
	v_mfma_f32_16x16x32_bf16 v[12:15], v[158:161], v[208:211], v[12:15]
	v_mfma_f32_16x16x32_bf16 v[8:11], v[166:169], v[208:211], v[8:11]
	v_mfma_f32_16x16x32_bf16 v[4:7], v[158:161], v[216:219], v[4:7]
	v_mfma_f32_16x16x32_bf16 v[0:3], v[166:169], v[216:219], v[0:3]
	s_setprio 0
	s_barrier
	s_add_i32 s64, 0, 0x18000
	s_add_i32 s65, 0, 0x1c000
	v_add_u32_e32 v150, s64, v245
	v_add_u32_e32 v166, s65, v245
	ds_read_b128 v[128:131], v150
	ds_read_b128 v[132:135], v150 offset:1024
	ds_read_b128 v[146:149], v150 offset:2048
	ds_read_b128 v[150:153], v150 offset:3072
	ds_read_b128 v[154:157], v166
	ds_read_b128 v[158:161], v166 offset:1024
	ds_read_b128 v[162:165], v166 offset:2048
	ds_read_b128 v[166:169], v166 offset:3072
	s_add_u32 s16, s16, 0x40000
	s_addc_u32 s17, s17, 0
	s_mov_b32 m0, s54
	ds_read_b128 v[170:173], v247 offset:32768
	ds_read_b128 v[174:177], v247 offset:33792
	ds_read_b128 v[178:181], v247 offset:34816
	ds_read_b128 v[182:185], v247 offset:35840
	ds_read_b128 v[186:189], v247 offset:36864
	ds_read_b128 v[208:211], v247 offset:37888
	ds_read_b128 v[212:215], v247 offset:38912
	ds_read_b128 v[216:219], v247 offset:39936
	global_load_lds_dwordx4 v136, s[16:17]
	v_lshl_add_u64 v[226:227], s[16:17], 0, v[138:139]
	s_mov_b32 m0, s55
	s_nop 0
	global_load_lds_dwordx4 v[226:227], off
	s_waitcnt vmcnt(8)
	s_waitcnt lgkmcnt(0)
	s_barrier
	s_setprio 1
	s_waitcnt lgkmcnt(0)
	v_mfma_f32_16x16x32_bf16 v[124:127], v[128:131], v[170:173], v[124:127]
	v_mfma_f32_16x16x32_bf16 v[120:123], v[146:149], v[170:173], v[120:123]
	v_mfma_f32_16x16x32_bf16 v[116:119], v[128:131], v[178:181], v[116:119]
	v_mfma_f32_16x16x32_bf16 v[112:115], v[146:149], v[178:181], v[112:115]
	v_mfma_f32_16x16x32_bf16 v[108:111], v[128:131], v[186:189], v[108:111]
	v_mfma_f32_16x16x32_bf16 v[104:107], v[146:149], v[186:189], v[104:107]
	v_mfma_f32_16x16x32_bf16 v[100:103], v[128:131], v[212:215], v[100:103]
	v_mfma_f32_16x16x32_bf16 v[96:99], v[146:149], v[212:215], v[96:99]
	v_mfma_f32_16x16x32_bf16 v[124:127], v[132:135], v[174:177], v[124:127]
	v_mfma_f32_16x16x32_bf16 v[120:123], v[150:153], v[174:177], v[120:123]
	v_mfma_f32_16x16x32_bf16 v[116:119], v[132:135], v[182:185], v[116:119]
	v_mfma_f32_16x16x32_bf16 v[112:115], v[150:153], v[182:185], v[112:115]
	v_mfma_f32_16x16x32_bf16 v[108:111], v[132:135], v[208:211], v[108:111]
	v_mfma_f32_16x16x32_bf16 v[104:107], v[150:153], v[208:211], v[104:107]
	v_mfma_f32_16x16x32_bf16 v[100:103], v[132:135], v[216:219], v[100:103]
	v_mfma_f32_16x16x32_bf16 v[96:99], v[150:153], v[216:219], v[96:99]
	s_setprio 0
	s_setprio 1
	v_mfma_f32_16x16x32_bf16 v[60:63], v[154:157], v[170:173], v[60:63]
	v_mfma_f32_16x16x32_bf16 v[56:59], v[162:165], v[170:173], v[56:59]
	v_mfma_f32_16x16x32_bf16 v[52:55], v[154:157], v[178:181], v[52:55]
	v_mfma_f32_16x16x32_bf16 v[48:51], v[162:165], v[178:181], v[48:51]
	v_mfma_f32_16x16x32_bf16 v[44:47], v[154:157], v[186:189], v[44:47]
	v_mfma_f32_16x16x32_bf16 v[40:43], v[162:165], v[186:189], v[40:43]
	v_mfma_f32_16x16x32_bf16 v[36:39], v[154:157], v[212:215], v[36:39]
	v_mfma_f32_16x16x32_bf16 v[32:35], v[162:165], v[212:215], v[32:35]
	v_mfma_f32_16x16x32_bf16 v[60:63], v[158:161], v[174:177], v[60:63]
	v_mfma_f32_16x16x32_bf16 v[56:59], v[166:169], v[174:177], v[56:59]
	v_mfma_f32_16x16x32_bf16 v[52:55], v[158:161], v[182:185], v[52:55]
	v_mfma_f32_16x16x32_bf16 v[48:51], v[166:169], v[182:185], v[48:51]
	v_mfma_f32_16x16x32_bf16 v[44:47], v[158:161], v[208:211], v[44:47]
	v_mfma_f32_16x16x32_bf16 v[40:43], v[166:169], v[208:211], v[40:43]
	v_mfma_f32_16x16x32_bf16 v[36:39], v[158:161], v[216:219], v[36:39]
	v_mfma_f32_16x16x32_bf16 v[32:35], v[166:169], v[216:219], v[32:35]
	s_setprio 0
	s_barrier
	s_add_i32 s16, s64, s50
	v_lshl_add_u64 v[190:191], v[190:191], 0, s[8:9]
	s_mov_b32 m0, s16
	ds_read_b128 v[170:173], v247 offset:49152
	ds_read_b128 v[174:177], v247 offset:50176
	ds_read_b128 v[178:181], v247 offset:51200
	ds_read_b128 v[182:185], v247 offset:52224
	ds_read_b128 v[186:189], v247 offset:53248
	ds_read_b128 v[208:211], v247 offset:54272
	ds_read_b128 v[212:215], v247 offset:55296
	ds_read_b128 v[216:219], v247 offset:56320
	global_load_lds_dwordx4 v[190:191], off
	s_add_i32 m0, s16, 0x2000
	s_add_u32 s14, s14, 0x40080
	v_lshl_add_u64 v[190:191], v[220:221], 0, s[8:9]
	s_addc_u32 s15, s15, 0
	s_add_i32 s16, s65, s50
	global_load_lds_dwordx4 v[190:191], off
	s_mov_b32 m0, s16
	s_nop 0
	global_load_lds_dwordx4 v192, s[14:15]
	s_add_i32 m0, s16, 0x2000
	s_nop 0
	global_load_lds_dwordx4 v140, s[14:15]
	v_lshl_add_u64 v[190:191], v[222:223], 0, s[8:9]
	s_mov_b32 m0, s58
	s_nop 0
	global_load_lds_dwordx4 v[190:191], off
	v_lshl_add_u64 v[190:191], v[224:225], 0, s[8:9]
	s_mov_b32 m0, s92
	s_nop 0
	global_load_lds_dwordx4 v[190:191], off
	s_waitcnt vmcnt(8)
	s_waitcnt lgkmcnt(0)
	s_barrier
	s_setprio 1
	s_waitcnt lgkmcnt(0)
	v_mfma_f32_16x16x32_bf16 v[92:95], v[128:131], v[170:173], v[92:95]
	v_mfma_f32_16x16x32_bf16 v[88:91], v[146:149], v[170:173], v[88:91]
	v_mfma_f32_16x16x32_bf16 v[84:87], v[128:131], v[178:181], v[84:87]
	v_mfma_f32_16x16x32_bf16 v[80:83], v[146:149], v[178:181], v[80:83]
	v_mfma_f32_16x16x32_bf16 v[76:79], v[128:131], v[186:189], v[76:79]
	v_mfma_f32_16x16x32_bf16 v[72:75], v[146:149], v[186:189], v[72:75]
	v_mfma_f32_16x16x32_bf16 v[68:71], v[128:131], v[212:215], v[68:71]
	v_mfma_f32_16x16x32_bf16 v[64:67], v[146:149], v[212:215], v[64:67]
	v_mfma_f32_16x16x32_bf16 v[92:95], v[132:135], v[174:177], v[92:95]
	v_mfma_f32_16x16x32_bf16 v[88:91], v[150:153], v[174:177], v[88:91]
	v_mfma_f32_16x16x32_bf16 v[84:87], v[132:135], v[182:185], v[84:87]
	v_mfma_f32_16x16x32_bf16 v[80:83], v[150:153], v[182:185], v[80:83]
	v_mfma_f32_16x16x32_bf16 v[76:79], v[132:135], v[208:211], v[76:79]
	v_mfma_f32_16x16x32_bf16 v[72:75], v[150:153], v[208:211], v[72:75]
	v_mfma_f32_16x16x32_bf16 v[68:71], v[132:135], v[216:219], v[68:71]
	v_mfma_f32_16x16x32_bf16 v[64:67], v[150:153], v[216:219], v[64:67]
	s_setprio 0
	s_setprio 1
	v_mfma_f32_16x16x32_bf16 v[28:31], v[154:157], v[170:173], v[28:31]
	v_mfma_f32_16x16x32_bf16 v[24:27], v[162:165], v[170:173], v[24:27]
	v_mfma_f32_16x16x32_bf16 v[20:23], v[154:157], v[178:181], v[20:23]
	v_mfma_f32_16x16x32_bf16 v[16:19], v[162:165], v[178:181], v[16:19]
	v_mfma_f32_16x16x32_bf16 v[12:15], v[154:157], v[186:189], v[12:15]
	v_mfma_f32_16x16x32_bf16 v[8:11], v[162:165], v[186:189], v[8:11]
	v_mfma_f32_16x16x32_bf16 v[4:7], v[154:157], v[212:215], v[4:7]
	v_mfma_f32_16x16x32_bf16 v[0:3], v[162:165], v[212:215], v[0:3]
	v_mfma_f32_16x16x32_bf16 v[28:31], v[158:161], v[174:177], v[28:31]
	v_mfma_f32_16x16x32_bf16 v[24:27], v[166:169], v[174:177], v[24:27]
	v_mfma_f32_16x16x32_bf16 v[20:23], v[158:161], v[182:185], v[20:23]
	v_mfma_f32_16x16x32_bf16 v[16:19], v[166:169], v[182:185], v[16:19]
	v_mfma_f32_16x16x32_bf16 v[12:15], v[158:161], v[208:211], v[12:15]
	v_mfma_f32_16x16x32_bf16 v[8:11], v[166:169], v[208:211], v[8:11]
	v_mfma_f32_16x16x32_bf16 v[4:7], v[158:161], v[216:219], v[4:7]
	v_mfma_f32_16x16x32_bf16 v[0:3], v[166:169], v[216:219], v[0:3]
	s_setprio 0
	s_barrier
	s_add_i32 s63, s63, 2
	s_add_u32 vcc_lo, vcc_lo, 0x100
	s_addc_u32 vcc_hi, vcc_hi, 0
	s_add_u32 s61, s61, 0x100
	s_addc_u32 s62, s62, 0
	s_cmp_gt_u32 s63, 13
	s_cbranch_scc0 .LBB0_727
	v_readlane_b32 s14, v252, 15
	v_readlane_b32 s15, v252, 16
	s_and_b64 vcc, exec, s[14:15]
	s_cbranch_vccz .LBB0_730
	s_barrier

.LBB0_793:
	v_lshl_add_u64 v[8:9], s[4:5], 0, v[192:193]
	v_mov_b32_e32 v129, v193
	v_and_b32_e32 v220, 15, v138
	v_and_b32_e32 v16, 48, v138
	v_lshlrev_b32_e32 v17, 2, v138
	v_lshl_add_u64 v[10:11], s[4:5], 0, v[128:129]
	s_and_b32 s61, s55, 3
	s_lshl_b32 s11, s0, 13
	v_lshl_or_b32 v16, v220, 6, v16
	v_and_b32_e32 v17, 32, v17
	s_add_i32 m0, s46, 0x18000
	v_lshl_add_u64 v[8:9], v[8:9], 0, s[8:9]
	v_lshl_add_u64 v[12:13], s[26:27], 0, v[192:193]
	s_lshl_b32 s58, s0, 6
	v_bitop3_b32 v18, v16, s11, v17 bitop3:0xde
	s_lshl_b32 s11, s61, 12
	s_waitcnt vmcnt(2)
	s_barrier
	global_load_lds_dwordx4 v[8:9], off
	v_lshl_add_u64 v[8:9], v[10:11], 0, s[8:9]
	s_add_i32 m0, s46, 0x1a000
	s_add_i32 s60, s46, 0x8000
	s_add_i32 s59, s46, 0xa000
	v_lshl_add_u64 v[14:15], s[26:27], 0, v[128:129]
	global_load_lds_dwordx4 v[8:9], off
	v_lshl_add_u64 v[8:9], v[12:13], 0, s[8:9]
	s_mov_b32 m0, s60
	s_add_u32 s28, s4, 0x40080
	global_load_lds_dwordx4 v[8:9], off
	v_lshl_add_u64 v[8:9], v[14:15], 0, s[8:9]
	s_mov_b32 m0, s59
	s_addc_u32 s29, s5, 0
	global_load_lds_dwordx4 v[8:9], off
	s_add_i32 m0, s46, 0x1c000
	s_nop 0
	global_load_lds_dwordx4 v192, s[28:29]
	s_add_i32 m0, s46, 0x1e000
	v_lshlrev_b32_e32 v0, 13, v0
	global_load_lds_dwordx4 v128, s[28:29]
	v_lshlrev_b32_e32 v5, 13, v5
	v_and_b32_e32 v0, 0x7fffc000, v0
	v_and_b32_e32 v5, 0x7fffc000, v5
	v_lshl_add_u32 v0, v1, 10, v0
	v_lshl_add_u32 v4, v4, 10, v5
	v_or_b32_e32 v0, v0, v2
	s_waitcnt vmcnt(6)
	v_or_b32_e32 v4, v4, v6
	v_add_lshl_u32 v132, v0, v3, 1
	v_mov_b32_e32 v2, v193
	v_mov_b32_e32 v3, v193
	v_bitop3_b32 v139, v16, s11, v17 bitop3:0xde
	v_add_lshl_u32 v130, v4, v7, 1
	v_mov_b32_e32 v0, v193
	v_mov_b32_e32 v1, v193
	v_add_u32_e32 v140, 0, v18
	v_mov_b64_e32 v[6:7], v[2:3]
	v_mov_b64_e32 v[18:19], v[2:3]
	v_mov_b64_e32 v[22:23], v[2:3]
	v_mov_b64_e32 v[34:35], v[2:3]
	v_mov_b64_e32 v[38:39], v[2:3]
	v_mov_b64_e32 v[50:51], v[2:3]
	v_mov_b64_e32 v[54:55], v[2:3]
	v_mov_b64_e32 v[10:11], v[2:3]
	v_mov_b64_e32 v[14:15], v[2:3]
	v_mov_b64_e32 v[26:27], v[2:3]
	v_mov_b64_e32 v[30:31], v[2:3]
	v_mov_b64_e32 v[42:43], v[2:3]
	v_mov_b64_e32 v[46:47], v[2:3]
	v_mov_b64_e32 v[58:59], v[2:3]
	v_mov_b64_e32 v[62:63], v[2:3]
	v_mov_b64_e32 v[66:67], v[2:3]
	v_mov_b64_e32 v[70:71], v[2:3]
	v_mov_b64_e32 v[82:83], v[2:3]
	v_mov_b64_e32 v[86:87], v[2:3]
	v_mov_b64_e32 v[102:103], v[2:3]
	v_mov_b64_e32 v[118:119], v[2:3]
	v_mov_b64_e32 v[114:115], v[2:3]
	v_mov_b64_e32 v[110:111], v[2:3]
	v_mov_b64_e32 v[74:75], v[2:3]
	v_mov_b64_e32 v[78:79], v[2:3]
	v_mov_b64_e32 v[90:91], v[2:3]
	v_mov_b64_e32 v[98:99], v[2:3]
	v_mov_b64_e32 v[126:127], v[2:3]
	v_mov_b64_e32 v[122:123], v[2:3]
	v_mov_b64_e32 v[106:107], v[2:3]
	v_mov_b64_e32 v[94:95], v[2:3]
	v_or_b32_e32 v212, s58, v220
	s_sext_i32_i8 s12, s2
	v_mov_b32_e32 v131, v193
	v_mov_b32_e32 v133, v193
	s_mov_b32 s2, 0
	v_mov_b64_e32 v[4:5], v[0:1]
	v_mov_b64_e32 v[16:17], v[0:1]
	v_mov_b64_e32 v[20:21], v[0:1]
	v_mov_b64_e32 v[32:33], v[0:1]
	v_mov_b64_e32 v[36:37], v[0:1]
	v_mov_b64_e32 v[48:49], v[0:1]
	v_mov_b64_e32 v[52:53], v[0:1]
	v_mov_b64_e32 v[8:9], v[0:1]
	v_mov_b64_e32 v[12:13], v[0:1]
	v_mov_b64_e32 v[24:25], v[0:1]
	v_mov_b64_e32 v[28:29], v[0:1]
	v_mov_b64_e32 v[40:41], v[0:1]
	v_mov_b64_e32 v[44:45], v[0:1]
	v_mov_b64_e32 v[56:57], v[0:1]
	v_mov_b64_e32 v[60:61], v[0:1]
	v_mov_b64_e32 v[64:65], v[0:1]
	v_mov_b64_e32 v[68:69], v[0:1]
	v_mov_b64_e32 v[80:81], v[0:1]
	v_mov_b64_e32 v[84:85], v[0:1]
	v_mov_b64_e32 v[100:101], v[0:1]
	v_mov_b64_e32 v[116:117], v[0:1]
	v_mov_b64_e32 v[112:113], v[0:1]
	v_mov_b64_e32 v[108:109], v[0:1]
	v_mov_b64_e32 v[72:73], v[0:1]
	v_mov_b64_e32 v[76:77], v[0:1]
	v_mov_b64_e32 v[88:89], v[0:1]
	v_mov_b64_e32 v[96:97], v[0:1]
	v_mov_b64_e32 v[124:125], v[0:1]
	v_mov_b64_e32 v[120:121], v[0:1]
	v_mov_b64_e32 v[104:105], v[0:1]
	v_mov_b64_e32 v[92:93], v[0:1]
	s_barrier

.LBB0_801:
	s_add_u32 s29, s26, s4
	s_addc_u32 s31, s27, s5
	s_add_u32 s29, s29, 0x100
	s_addc_u32 s31, s31, 0
	s_add_u32 s42, s13, s4
	s_addc_u32 s43, s68, s5
	s_add_i32 s70, 0, 0x10000
	s_cmpk_eq_i32 s4, 0x700
	s_cselect_b32 s45, s69, s31
	s_cselect_b32 s44, s92, s29
	v_add_u32_e32 v141, s70, v139
	s_cselect_b32 s43, s93, s43
	s_cselect_b32 s42, s94, s42
	s_add_i32 s72, 0, 0x14000
	ds_read_b128 v[142:145], v141
	ds_read_b128 v[146:149], v141 offset:1024
	ds_read_b128 v[150:153], v141 offset:2048
	ds_read_b128 v[154:157], v141 offset:3072
	v_add_u32_e32 v141, s72, v139
	ds_read_b128 v[158:161], v141
	ds_read_b128 v[162:165], v141 offset:1024
	ds_read_b128 v[166:169], v141 offset:2048
	ds_read_b128 v[170:173], v141 offset:3072
	s_add_i32 s29, s46, 0xc000
	v_lshl_add_u64 v[190:191], v[134:135], 0, s[4:5]
	s_mov_b32 m0, s29
	s_add_i32 s31, s46, 0xe000
	ds_read_b128 v[174:177], v140
	ds_read_b128 v[178:181], v140 offset:1024
	ds_read_b128 v[182:185], v140 offset:2048
	ds_read_b128 v[186:189], v140 offset:3072
	ds_read_b128 v[208:211], v140 offset:4096
	ds_read_b128 v[214:217], v140 offset:5120
	ds_read_b128 v[222:225], v140 offset:6144
	ds_read_b128 v[226:229], v140 offset:7168
	global_load_lds_dwordx4 v[190:191], off
	v_lshl_add_u64 v[190:191], v[136:137], 0, s[4:5]
	s_mov_b32 m0, s31
	s_nop 0
	global_load_lds_dwordx4 v[190:191], off
	s_waitcnt vmcnt(8)
	s_waitcnt lgkmcnt(0)
	s_barrier
	s_setprio 1
	s_waitcnt lgkmcnt(0)
	v_mfma_f32_16x16x32_bf16 v[92:95], v[142:145], v[174:177], v[92:95]
	v_mfma_f32_16x16x32_bf16 v[104:107], v[150:153], v[174:177], v[104:107]
	v_mfma_f32_16x16x32_bf16 v[120:123], v[142:145], v[182:185], v[120:123]
	v_mfma_f32_16x16x32_bf16 v[124:127], v[150:153], v[182:185], v[124:127]
	v_mfma_f32_16x16x32_bf16 v[96:99], v[142:145], v[208:211], v[96:99]
	v_mfma_f32_16x16x32_bf16 v[88:91], v[150:153], v[208:211], v[88:91]
	v_mfma_f32_16x16x32_bf16 v[76:79], v[142:145], v[222:225], v[76:79]
	v_mfma_f32_16x16x32_bf16 v[72:75], v[150:153], v[222:225], v[72:75]
	v_mfma_f32_16x16x32_bf16 v[92:95], v[146:149], v[178:181], v[92:95]
	v_mfma_f32_16x16x32_bf16 v[104:107], v[154:157], v[178:181], v[104:107]
	v_mfma_f32_16x16x32_bf16 v[120:123], v[146:149], v[186:189], v[120:123]
	v_mfma_f32_16x16x32_bf16 v[124:127], v[154:157], v[186:189], v[124:127]
	v_mfma_f32_16x16x32_bf16 v[96:99], v[146:149], v[214:217], v[96:99]
	v_mfma_f32_16x16x32_bf16 v[88:91], v[154:157], v[214:217], v[88:91]
	v_mfma_f32_16x16x32_bf16 v[76:79], v[146:149], v[226:229], v[76:79]
	v_mfma_f32_16x16x32_bf16 v[72:75], v[154:157], v[226:229], v[72:75]
	s_setprio 0
	s_setprio 1
	v_mfma_f32_16x16x32_bf16 v[108:111], v[158:161], v[174:177], v[108:111]
	v_mfma_f32_16x16x32_bf16 v[112:115], v[166:169], v[174:177], v[112:115]
	v_mfma_f32_16x16x32_bf16 v[116:119], v[158:161], v[182:185], v[116:119]
	v_mfma_f32_16x16x32_bf16 v[100:103], v[166:169], v[182:185], v[100:103]
	v_mfma_f32_16x16x32_bf16 v[84:87], v[158:161], v[208:211], v[84:87]
	v_mfma_f32_16x16x32_bf16 v[80:83], v[166:169], v[208:211], v[80:83]
	v_mfma_f32_16x16x32_bf16 v[68:71], v[158:161], v[222:225], v[68:71]
	v_mfma_f32_16x16x32_bf16 v[64:67], v[166:169], v[222:225], v[64:67]
	v_mfma_f32_16x16x32_bf16 v[108:111], v[162:165], v[178:181], v[108:111]
	v_mfma_f32_16x16x32_bf16 v[112:115], v[170:173], v[178:181], v[112:115]
	v_mfma_f32_16x16x32_bf16 v[116:119], v[162:165], v[186:189], v[116:119]
	v_mfma_f32_16x16x32_bf16 v[100:103], v[170:173], v[186:189], v[100:103]
	v_mfma_f32_16x16x32_bf16 v[84:87], v[162:165], v[214:217], v[84:87]
	v_mfma_f32_16x16x32_bf16 v[80:83], v[170:173], v[214:217], v[80:83]
	v_mfma_f32_16x16x32_bf16 v[68:71], v[162:165], v[226:229], v[68:71]
	v_mfma_f32_16x16x32_bf16 v[64:67], v[170:173], v[226:229], v[64:67]
	s_setprio 0
	s_barrier
	s_add_i32 s70, s70, s66
	v_lshl_add_u64 v[190:191], s[42:43], 0, v[192:193]
	s_mov_b32 m0, s70
	ds_read_b128 v[174:177], v140 offset:16384
	ds_read_b128 v[178:181], v140 offset:17408
	ds_read_b128 v[182:185], v140 offset:18432
	ds_read_b128 v[186:189], v140 offset:19456
	ds_read_b128 v[208:211], v140 offset:20480
	ds_read_b128 v[214:217], v140 offset:21504
	ds_read_b128 v[222:225], v140 offset:22528
	ds_read_b128 v[226:229], v140 offset:23552
	global_load_lds_dwordx4 v[190:191], off
	s_add_i32 m0, s70, 0x2000
	s_add_u32 s70, s42, 0x40000
	v_lshl_add_u64 v[218:219], s[42:43], 0, v[128:129]
	s_addc_u32 s71, s43, 0
	s_add_i32 s72, s72, s66
	global_load_lds_dwordx4 v[218:219], off
	s_mov_b32 m0, s72
	v_lshl_add_u64 v[232:233], s[44:45], 0, v[128:129]
	global_load_lds_dwordx4 v192, s[70:71]
	s_add_i32 m0, s72, 0x2000
	s_nop 0
	global_load_lds_dwordx4 v128, s[70:71]
	v_lshl_add_u64 v[230:231], s[44:45], 0, v[192:193]
	s_mov_b32 m0, s46
	s_nop 0
	global_load_lds_dwordx4 v[230:231], off
	s_mov_b32 m0, s52
	s_nop 0
	global_load_lds_dwordx4 v[232:233], off
	s_waitcnt vmcnt(8)
	s_waitcnt lgkmcnt(0)
	s_barrier
	s_setprio 1
	s_waitcnt lgkmcnt(0)
	v_mfma_f32_16x16x32_bf16 v[60:63], v[142:145], v[174:177], v[60:63]
	v_mfma_f32_16x16x32_bf16 v[56:59], v[150:153], v[174:177], v[56:59]
	v_mfma_f32_16x16x32_bf16 v[44:47], v[142:145], v[182:185], v[44:47]
	v_mfma_f32_16x16x32_bf16 v[40:43], v[150:153], v[182:185], v[40:43]
	v_mfma_f32_16x16x32_bf16 v[28:31], v[142:145], v[208:211], v[28:31]
	v_mfma_f32_16x16x32_bf16 v[24:27], v[150:153], v[208:211], v[24:27]
	v_mfma_f32_16x16x32_bf16 v[12:15], v[142:145], v[222:225], v[12:15]
	v_mfma_f32_16x16x32_bf16 v[8:11], v[150:153], v[222:225], v[8:11]
	v_mfma_f32_16x16x32_bf16 v[60:63], v[146:149], v[178:181], v[60:63]
	v_mfma_f32_16x16x32_bf16 v[56:59], v[154:157], v[178:181], v[56:59]
	v_mfma_f32_16x16x32_bf16 v[44:47], v[146:149], v[186:189], v[44:47]
	v_mfma_f32_16x16x32_bf16 v[40:43], v[154:157], v[186:189], v[40:43]
	v_mfma_f32_16x16x32_bf16 v[28:31], v[146:149], v[214:217], v[28:31]
	v_mfma_f32_16x16x32_bf16 v[24:27], v[154:157], v[214:217], v[24:27]
	v_mfma_f32_16x16x32_bf16 v[12:15], v[146:149], v[226:229], v[12:15]
	v_mfma_f32_16x16x32_bf16 v[8:11], v[154:157], v[226:229], v[8:11]
	s_setprio 0
	s_setprio 1
	v_mfma_f32_16x16x32_bf16 v[52:55], v[158:161], v[174:177], v[52:55]
	v_mfma_f32_16x16x32_bf16 v[48:51], v[166:169], v[174:177], v[48:51]
	v_mfma_f32_16x16x32_bf16 v[36:39], v[158:161], v[182:185], v[36:39]
	v_mfma_f32_16x16x32_bf16 v[32:35], v[166:169], v[182:185], v[32:35]
	v_mfma_f32_16x16x32_bf16 v[20:23], v[158:161], v[208:211], v[20:23]
	v_mfma_f32_16x16x32_bf16 v[16:19], v[166:169], v[208:211], v[16:19]
	v_mfma_f32_16x16x32_bf16 v[4:7], v[158:161], v[222:225], v[4:7]
	v_mfma_f32_16x16x32_bf16 v[0:3], v[166:169], v[222:225], v[0:3]
	v_mfma_f32_16x16x32_bf16 v[52:55], v[162:165], v[178:181], v[52:55]
	v_mfma_f32_16x16x32_bf16 v[48:51], v[170:173], v[178:181], v[48:51]
	v_mfma_f32_16x16x32_bf16 v[36:39], v[162:165], v[186:189], v[36:39]
	v_mfma_f32_16x16x32_bf16 v[32:35], v[170:173], v[186:189], v[32:35]
	v_mfma_f32_16x16x32_bf16 v[20:23], v[162:165], v[214:217], v[20:23]
	v_mfma_f32_16x16x32_bf16 v[16:19], v[170:173], v[214:217], v[16:19]
	v_mfma_f32_16x16x32_bf16 v[4:7], v[162:165], v[226:229], v[4:7]
	v_mfma_f32_16x16x32_bf16 v[0:3], v[170:173], v[226:229], v[0:3]
	s_setprio 0
	s_barrier
	s_add_i32 s70, 0, 0x18000
	v_add_u32_e32 v141, s70, v139
	s_add_i32 s71, 0, 0x1c000
	ds_read_b128 v[142:145], v141
	ds_read_b128 v[146:149], v141 offset:1024
	ds_read_b128 v[150:153], v141 offset:2048
	ds_read_b128 v[154:157], v141 offset:3072
	v_add_u32_e32 v141, s71, v139
	ds_read_b128 v[158:161], v141
	ds_read_b128 v[162:165], v141 offset:1024
	ds_read_b128 v[166:169], v141 offset:2048
	ds_read_b128 v[170:173], v141 offset:3072
	s_add_u32 s44, s44, 0x40000
	s_addc_u32 s45, s45, 0
	s_mov_b32 m0, s53
	ds_read_b128 v[174:177], v140 offset:32768
	ds_read_b128 v[178:181], v140 offset:33792
	ds_read_b128 v[182:185], v140 offset:34816
	ds_read_b128 v[186:189], v140 offset:35840
	ds_read_b128 v[208:211], v140 offset:36864
	ds_read_b128 v[214:217], v140 offset:37888
	ds_read_b128 v[222:225], v140 offset:38912
	ds_read_b128 v[226:229], v140 offset:39936
	global_load_lds_dwordx4 v192, s[44:45]
	v_lshl_add_u64 v[234:235], s[44:45], 0, v[128:129]
	s_mov_b32 m0, s54
	s_nop 0
	global_load_lds_dwordx4 v[234:235], off
	s_waitcnt vmcnt(8)
	s_waitcnt lgkmcnt(0)
	s_barrier
	s_setprio 1
	s_waitcnt lgkmcnt(0)
	v_mfma_f32_16x16x32_bf16 v[92:95], v[142:145], v[174:177], v[92:95]
	v_mfma_f32_16x16x32_bf16 v[104:107], v[150:153], v[174:177], v[104:107]
	v_mfma_f32_16x16x32_bf16 v[120:123], v[142:145], v[182:185], v[120:123]
	v_mfma_f32_16x16x32_bf16 v[124:127], v[150:153], v[182:185], v[124:127]
	v_mfma_f32_16x16x32_bf16 v[96:99], v[142:145], v[208:211], v[96:99]
	v_mfma_f32_16x16x32_bf16 v[88:91], v[150:153], v[208:211], v[88:91]
	v_mfma_f32_16x16x32_bf16 v[76:79], v[142:145], v[222:225], v[76:79]
	v_mfma_f32_16x16x32_bf16 v[72:75], v[150:153], v[222:225], v[72:75]
	v_mfma_f32_16x16x32_bf16 v[92:95], v[146:149], v[178:181], v[92:95]
	v_mfma_f32_16x16x32_bf16 v[104:107], v[154:157], v[178:181], v[104:107]
	v_mfma_f32_16x16x32_bf16 v[120:123], v[146:149], v[186:189], v[120:123]
	v_mfma_f32_16x16x32_bf16 v[124:127], v[154:157], v[186:189], v[124:127]
	v_mfma_f32_16x16x32_bf16 v[96:99], v[146:149], v[214:217], v[96:99]
	v_mfma_f32_16x16x32_bf16 v[88:91], v[154:157], v[214:217], v[88:91]
	v_mfma_f32_16x16x32_bf16 v[76:79], v[146:149], v[226:229], v[76:79]
	v_mfma_f32_16x16x32_bf16 v[72:75], v[154:157], v[226:229], v[72:75]
	s_setprio 0
	s_setprio 1
	v_mfma_f32_16x16x32_bf16 v[108:111], v[158:161], v[174:177], v[108:111]
	v_mfma_f32_16x16x32_bf16 v[112:115], v[166:169], v[174:177], v[112:115]
	v_mfma_f32_16x16x32_bf16 v[116:119], v[158:161], v[182:185], v[116:119]
	v_mfma_f32_16x16x32_bf16 v[100:103], v[166:169], v[182:185], v[100:103]
	v_mfma_f32_16x16x32_bf16 v[84:87], v[158:161], v[208:211], v[84:87]
	v_mfma_f32_16x16x32_bf16 v[80:83], v[166:169], v[208:211], v[80:83]
	v_mfma_f32_16x16x32_bf16 v[68:71], v[158:161], v[222:225], v[68:71]
	v_mfma_f32_16x16x32_bf16 v[64:67], v[166:169], v[222:225], v[64:67]
	v_mfma_f32_16x16x32_bf16 v[108:111], v[162:165], v[178:181], v[108:111]
	v_mfma_f32_16x16x32_bf16 v[112:115], v[170:173], v[178:181], v[112:115]
	v_mfma_f32_16x16x32_bf16 v[116:119], v[162:165], v[186:189], v[116:119]
	v_mfma_f32_16x16x32_bf16 v[100:103], v[170:173], v[186:189], v[100:103]
	v_mfma_f32_16x16x32_bf16 v[84:87], v[162:165], v[214:217], v[84:87]
	v_mfma_f32_16x16x32_bf16 v[80:83], v[170:173], v[214:217], v[80:83]
	v_mfma_f32_16x16x32_bf16 v[68:71], v[162:165], v[226:229], v[68:71]
	v_mfma_f32_16x16x32_bf16 v[64:67], v[170:173], v[226:229], v[64:67]
	s_setprio 0
	s_barrier
	s_add_i32 s44, s70, s66
	v_lshl_add_u64 v[190:191], v[190:191], 0, s[8:9]
	s_mov_b32 m0, s44
	ds_read_b128 v[174:177], v140 offset:49152
	ds_read_b128 v[178:181], v140 offset:50176
	ds_read_b128 v[182:185], v140 offset:51200
	ds_read_b128 v[186:189], v140 offset:52224
	ds_read_b128 v[208:211], v140 offset:53248
	ds_read_b128 v[214:217], v140 offset:54272
	ds_read_b128 v[222:225], v140 offset:55296
	ds_read_b128 v[226:229], v140 offset:56320
	global_load_lds_dwordx4 v[190:191], off
	s_add_i32 m0, s44, 0x2000
	s_add_u32 s42, s42, 0x40080
	v_lshl_add_u64 v[190:191], v[218:219], 0, s[8:9]
	s_addc_u32 s43, s43, 0
	s_add_i32 s44, s71, s66
	global_load_lds_dwordx4 v[190:191], off
	s_mov_b32 m0, s44
	s_nop 0
	global_load_lds_dwordx4 v192, s[42:43]
	s_add_i32 m0, s44, 0x2000
	s_nop 0
	global_load_lds_dwordx4 v128, s[42:43]
	v_lshl_add_u64 v[190:191], v[230:231], 0, s[8:9]
	s_mov_b32 m0, s60
	s_nop 0
	global_load_lds_dwordx4 v[190:191], off
	v_lshl_add_u64 v[190:191], v[232:233], 0, s[8:9]
	s_mov_b32 m0, s59
	s_nop 0
	global_load_lds_dwordx4 v[190:191], off
	s_waitcnt vmcnt(8)
	s_waitcnt lgkmcnt(0)
	s_barrier
	s_setprio 1
	s_waitcnt lgkmcnt(0)
	v_mfma_f32_16x16x32_bf16 v[60:63], v[142:145], v[174:177], v[60:63]
	v_mfma_f32_16x16x32_bf16 v[56:59], v[150:153], v[174:177], v[56:59]
	v_mfma_f32_16x16x32_bf16 v[44:47], v[142:145], v[182:185], v[44:47]
	v_mfma_f32_16x16x32_bf16 v[40:43], v[150:153], v[182:185], v[40:43]
	v_mfma_f32_16x16x32_bf16 v[28:31], v[142:145], v[208:211], v[28:31]
	v_mfma_f32_16x16x32_bf16 v[24:27], v[150:153], v[208:211], v[24:27]
	v_mfma_f32_16x16x32_bf16 v[12:15], v[142:145], v[222:225], v[12:15]
	v_mfma_f32_16x16x32_bf16 v[8:11], v[150:153], v[222:225], v[8:11]
	v_mfma_f32_16x16x32_bf16 v[60:63], v[146:149], v[178:181], v[60:63]
	v_mfma_f32_16x16x32_bf16 v[56:59], v[154:157], v[178:181], v[56:59]
	v_mfma_f32_16x16x32_bf16 v[44:47], v[146:149], v[186:189], v[44:47]
	v_mfma_f32_16x16x32_bf16 v[40:43], v[154:157], v[186:189], v[40:43]
	v_mfma_f32_16x16x32_bf16 v[28:31], v[146:149], v[214:217], v[28:31]
	v_mfma_f32_16x16x32_bf16 v[24:27], v[154:157], v[214:217], v[24:27]
	v_mfma_f32_16x16x32_bf16 v[12:15], v[146:149], v[226:229], v[12:15]
	v_mfma_f32_16x16x32_bf16 v[8:11], v[154:157], v[226:229], v[8:11]
	s_setprio 0
	s_setprio 1
	v_mfma_f32_16x16x32_bf16 v[52:55], v[158:161], v[174:177], v[52:55]
	v_mfma_f32_16x16x32_bf16 v[48:51], v[166:169], v[174:177], v[48:51]
	v_mfma_f32_16x16x32_bf16 v[36:39], v[158:161], v[182:185], v[36:39]
	v_mfma_f32_16x16x32_bf16 v[32:35], v[166:169], v[182:185], v[32:35]
	v_mfma_f32_16x16x32_bf16 v[20:23], v[158:161], v[208:211], v[20:23]
	v_mfma_f32_16x16x32_bf16 v[16:19], v[166:169], v[208:211], v[16:19]
	v_mfma_f32_16x16x32_bf16 v[4:7], v[158:161], v[222:225], v[4:7]
	v_mfma_f32_16x16x32_bf16 v[0:3], v[166:169], v[222:225], v[0:3]
	v_mfma_f32_16x16x32_bf16 v[52:55], v[162:165], v[178:181], v[52:55]
	v_mfma_f32_16x16x32_bf16 v[48:51], v[170:173], v[178:181], v[48:51]
	v_mfma_f32_16x16x32_bf16 v[36:39], v[162:165], v[186:189], v[36:39]
	v_mfma_f32_16x16x32_bf16 v[32:35], v[170:173], v[186:189], v[32:35]
	v_mfma_f32_16x16x32_bf16 v[20:23], v[162:165], v[214:217], v[20:23]
	v_mfma_f32_16x16x32_bf16 v[16:19], v[170:173], v[214:217], v[16:19]
	v_mfma_f32_16x16x32_bf16 v[4:7], v[162:165], v[226:229], v[4:7]
	v_mfma_f32_16x16x32_bf16 v[0:3], v[170:173], v[226:229], v[0:3]
	s_setprio 0
	s_barrier
	s_add_i32 s95, s95, 2
	s_add_u32 s4, s4, 0x100
	s_addc_u32 s5, s5, 0
	s_cmp_gt_u32 s95, 13
	s_cbranch_scc0 .LBB0_801
	s_add_u32 s4, s13, 0xffffff00
	s_addc_u32 s5, s68, -1
	s_andn2_b64 vcc, exec, s[40:41]
	s_cbranch_vccnz .LBB0_804
	v_mov_b32_e32 v0, 0
	s_mov_b32 s12, s28
	s_mov_b32 s10, s30
	s_mov_b64 s[26:27], s[36:37]
	s_mov_b32 s2, s11
	v_mov_b32_e32 v1, v0
	v_mov_b32_e32 v2, v0
	v_mov_b32_e32 v3, v0
	v_mov_b32_e32 v4, v0
	v_mov_b32_e32 v5, v0
	v_mov_b32_e32 v6, v0
	v_mov_b32_e32 v7, v0
	v_mov_b32_e32 v16, v0
	v_mov_b32_e32 v17, v0
	v_mov_b32_e32 v18, v0
	v_mov_b32_e32 v19, v0
	v_mov_b32_e32 v20, v0
	v_mov_b32_e32 v21, v0
	v_mov_b32_e32 v22, v0
	v_mov_b32_e32 v23, v0
	v_mov_b32_e32 v32, v0
	v_mov_b32_e32 v33, v0
	v_mov_b32_e32 v34, v0
	v_mov_b32_e32 v35, v0
	v_mov_b32_e32 v36, v0
	v_mov_b32_e32 v37, v0
	v_mov_b32_e32 v38, v0
	v_mov_b32_e32 v39, v0
	v_mov_b32_e32 v48, v0
	v_mov_b32_e32 v49, v0
	v_mov_b32_e32 v50, v0
	v_mov_b32_e32 v51, v0
	v_mov_b32_e32 v52, v0
	v_mov_b32_e32 v53, v0
	v_mov_b32_e32 v54, v0
	v_mov_b32_e32 v55, v0
	v_mov_b32_e32 v8, v0
	v_mov_b32_e32 v9, v0
	v_mov_b32_e32 v10, v0
	v_mov_b32_e32 v11, v0
	v_mov_b32_e32 v12, v0
	v_mov_b32_e32 v13, v0
	v_mov_b32_e32 v14, v0
	v_mov_b32_e32 v15, v0
	v_mov_b32_e32 v24, v0
	v_mov_b32_e32 v25, v0
	v_mov_b32_e32 v26, v0
	v_mov_b32_e32 v27, v0
	v_mov_b32_e32 v28, v0
	v_mov_b32_e32 v29, v0
	v_mov_b32_e32 v30, v0
	v_mov_b32_e32 v31, v0
	v_mov_b32_e32 v40, v0
	v_mov_b32_e32 v41, v0
	v_mov_b32_e32 v42, v0
	v_mov_b32_e32 v43, v0
	v_mov_b32_e32 v44, v0
	v_mov_b32_e32 v45, v0
	v_mov_b32_e32 v46, v0
	v_mov_b32_e32 v47, v0
	v_mov_b32_e32 v56, v0
	v_mov_b32_e32 v57, v0
	v_mov_b32_e32 v58, v0
	v_mov_b32_e32 v59, v0
	v_mov_b32_e32 v60, v0
	v_mov_b32_e32 v61, v0
	v_mov_b32_e32 v62, v0
	v_mov_b32_e32 v63, v0
	v_mov_b32_e32 v64, v0
	v_mov_b32_e32 v65, v0
	v_mov_b32_e32 v66, v0
	v_mov_b32_e32 v67, v0
	v_mov_b32_e32 v68, v0
	v_mov_b32_e32 v69, v0
	v_mov_b32_e32 v70, v0
	v_mov_b32_e32 v71, v0
	v_mov_b32_e32 v80, v0
	v_mov_b32_e32 v81, v0
	v_mov_b32_e32 v82, v0
	v_mov_b32_e32 v83, v0
	v_mov_b32_e32 v84, v0
	v_mov_b32_e32 v85, v0
	v_mov_b32_e32 v86, v0
	v_mov_b32_e32 v87, v0
	v_mov_b32_e32 v100, v0
	v_mov_b32_e32 v101, v0
	v_mov_b32_e32 v102, v0
	v_mov_b32_e32 v103, v0
	v_mov_b32_e32 v116, v0
	v_mov_b32_e32 v117, v0
	v_mov_b32_e32 v118, v0
	v_mov_b32_e32 v119, v0
	v_mov_b32_e32 v112, v0
	v_mov_b32_e32 v113, v0
	v_mov_b32_e32 v114, v0
	v_mov_b32_e32 v115, v0
	v_mov_b32_e32 v108, v0
	v_mov_b32_e32 v109, v0
	v_mov_b32_e32 v110, v0
	v_mov_b32_e32 v111, v0
	v_mov_b32_e32 v72, v0
	v_mov_b32_e32 v73, v0
	v_mov_b32_e32 v74, v0
	v_mov_b32_e32 v75, v0
	v_mov_b32_e32 v76, v0
	v_mov_b32_e32 v77, v0
	v_mov_b32_e32 v78, v0
	v_mov_b32_e32 v79, v0
	v_mov_b32_e32 v88, v0
	v_mov_b32_e32 v89, v0
	v_mov_b32_e32 v90, v0
	v_mov_b32_e32 v91, v0
	v_mov_b32_e32 v96, v0
	v_mov_b32_e32 v97, v0
	v_mov_b32_e32 v98, v0
	v_mov_b32_e32 v99, v0
	v_mov_b32_e32 v124, v0
	v_mov_b32_e32 v125, v0
	v_mov_b32_e32 v126, v0
	v_mov_b32_e32 v127, v0
	v_mov_b32_e32 v120, v0
	v_mov_b32_e32 v121, v0
	v_mov_b32_e32 v122, v0
	v_mov_b32_e32 v123, v0
	v_mov_b32_e32 v104, v0
	v_mov_b32_e32 v105, v0
	v_mov_b32_e32 v106, v0
	v_mov_b32_e32 v107, v0
	v_mov_b32_e32 v92, v0
	v_mov_b32_e32 v93, v0
	v_mov_b32_e32 v94, v0
	v_mov_b32_e32 v95, v0
	s_branch .LBB0_805

.LBB0_931:
	s_waitcnt lgkmcnt(0)
	s_add_u32 s10, s10, 0x5720000
	v_lshrrev_b32_e32 v16, 1, v14
	s_addc_u32 s11, s11, 0
	v_and_b32_e32 v16, 24, v16
	s_lshl_b32 s13, s13, 5
	v_and_b32_e32 v15, 15, v14
	v_lshlrev_b32_e32 v17, 1, v16
	v_lshlrev_b32_e32 v14, 2, v14
	s_and_b32 s16, s13, 0x60
	s_add_i32 m0, s27, 0x18000
	v_lshl_add_u64 v[6:7], v[6:7], 0, s[8:9]
	v_lshl_or_b32 v140, s14, 6, v15
	v_lshl_or_b32 v15, v15, 6, v17
	s_lshl_b32 s14, s14, 13
	v_and_b32_e32 v14, 32, v14
	s_lshl_b32 s13, s16, 7
	s_sext_i32_i16 s50, s2
	s_waitcnt vmcnt(2)
	s_barrier
	global_load_lds_dwordx4 v[6:7], off
	v_lshl_add_u64 v[4:5], v[4:5], 0, s[8:9]
	s_add_i32 m0, s27, 0x1a000
	s_add_i32 s2, s27, 0x8000
	s_add_i32 s48, s27, 0xa000
	v_bitop3_b32 v17, v15, s14, v14 bitop3:0xde
	global_load_lds_dwordx4 v[4:5], off
	v_lshl_add_u64 v[0:1], v[0:1], 0, s[8:9]
	s_mov_b32 m0, s2
	s_add_u32 s14, s4, 0x40080
	global_load_lds_dwordx4 v[0:1], off
	v_lshl_add_u64 v[0:1], v[2:3], 0, s[8:9]
	s_mov_b32 m0, s48
	s_addc_u32 s15, s5, 0
	global_load_lds_dwordx4 v[0:1], off
	s_add_i32 m0, s27, 0x1c000
	s_nop 0
	global_load_lds_dwordx4 v192, s[14:15]
	s_add_i32 m0, s27, 0x1e000
	s_cmpk_lt_u32 s12, 0x100
	global_load_lds_dwordx4 v128, s[14:15]
	v_lshlrev_b32_e32 v0, 14, v12
	v_and_b32_e32 v0, 0xffff8000, v0
	v_lshl_add_u32 v0, v11, 11, v0
	v_and_b32_e32 v1, 1, v12
	v_lshl_or_b32 v0, v1, 6, v0
	v_lshl_add_u32 v134, v13, 1, v0
	v_lshlrev_b32_e32 v0, 14, v8
	v_and_b32_e32 v0, 0xffff8000, v0
	s_waitcnt vmcnt(6)
	v_lshl_add_u32 v0, v9, 11, v0
	v_and_b32_e32 v1, 1, v8
	v_lshl_or_b32 v0, v1, 6, v0
	v_bitop3_b32 v141, v15, s13, v14 bitop3:0xde
	s_cselect_b64 s[12:13], -1, 0
	v_or_b32_e32 v142, s16, v16
	v_mov_b32_e32 v135, v193
	v_lshl_add_u32 v136, v10, 1, v0
	v_mov_b32_e32 v137, v193
	s_mov_b32 s49, 0
	v_add_u32_e32 v143, 0, v17
	s_barrier
	s_branch .LBB0_934

.LBB0_937:
	s_add_u32 s4, s34, 0xfffc0080
	s_addc_u32 s5, s35, -1
	s_add_i32 s58, 0, 0x10000
	s_cmp_eq_u32 s55, 12
	s_cselect_b32 s37, s17, s5
	s_cselect_b32 s36, s51, s4
	v_add_u32_e32 v138, s58, v141
	s_cselect_b32 s5, s15, s54
	s_cselect_b32 s4, s52, s53
	s_add_i32 s60, 0, 0x14000
	ds_read_b128 v[144:147], v138
	ds_read_b128 v[148:151], v138 offset:1024
	ds_read_b128 v[152:155], v138 offset:2048
	ds_read_b128 v[156:159], v138 offset:3072
	v_add_u32_e32 v138, s60, v141
	ds_read_b128 v[160:163], v138
	ds_read_b128 v[164:167], v138 offset:1024
	ds_read_b128 v[168:171], v138 offset:2048
	ds_read_b128 v[172:175], v138 offset:3072
	s_add_i32 m0, s27, 0xc000
	ds_read_b128 v[176:179], v143
	ds_read_b128 v[180:183], v143 offset:1024
	ds_read_b128 v[184:187], v143 offset:2048
	ds_read_b128 v[188:191], v143 offset:3072
	ds_read_b128 v[208:211], v143 offset:4096
	ds_read_b128 v[212:215], v143 offset:5120
	ds_read_b128 v[216:219], v143 offset:6144
	ds_read_b128 v[220:223], v143 offset:7168
	global_load_lds_dwordx4 v134, s[34:35]
	s_add_i32 m0, s27, 0xe000
	s_nop 0
	global_load_lds_dwordx4 v136, s[34:35]
	s_waitcnt vmcnt(8)
	s_waitcnt lgkmcnt(0)
	s_barrier
	s_setprio 1
	s_waitcnt lgkmcnt(0)
	v_mfma_f32_16x16x32_bf16 v[124:127], v[144:147], v[176:179], v[124:127]
	v_mfma_f32_16x16x32_bf16 v[120:123], v[152:155], v[176:179], v[120:123]
	v_mfma_f32_16x16x32_bf16 v[108:111], v[144:147], v[184:187], v[108:111]
	v_mfma_f32_16x16x32_bf16 v[104:107], v[152:155], v[184:187], v[104:107]
	v_mfma_f32_16x16x32_bf16 v[92:95], v[144:147], v[208:211], v[92:95]
	v_mfma_f32_16x16x32_bf16 v[88:91], v[152:155], v[208:211], v[88:91]
	v_mfma_f32_16x16x32_bf16 v[76:79], v[144:147], v[216:219], v[76:79]
	v_mfma_f32_16x16x32_bf16 v[72:75], v[152:155], v[216:219], v[72:75]
	v_mfma_f32_16x16x32_bf16 v[124:127], v[148:151], v[180:183], v[124:127]
	v_mfma_f32_16x16x32_bf16 v[120:123], v[156:159], v[180:183], v[120:123]
	v_mfma_f32_16x16x32_bf16 v[108:111], v[148:151], v[188:191], v[108:111]
	v_mfma_f32_16x16x32_bf16 v[104:107], v[156:159], v[188:191], v[104:107]
	v_mfma_f32_16x16x32_bf16 v[92:95], v[148:151], v[212:215], v[92:95]
	v_mfma_f32_16x16x32_bf16 v[88:91], v[156:159], v[212:215], v[88:91]
	v_mfma_f32_16x16x32_bf16 v[76:79], v[148:151], v[220:223], v[76:79]
	v_mfma_f32_16x16x32_bf16 v[72:75], v[156:159], v[220:223], v[72:75]
	s_setprio 0
	s_setprio 1
	v_mfma_f32_16x16x32_bf16 v[116:119], v[160:163], v[176:179], v[116:119]
	v_mfma_f32_16x16x32_bf16 v[112:115], v[168:171], v[176:179], v[112:115]
	v_mfma_f32_16x16x32_bf16 v[100:103], v[160:163], v[184:187], v[100:103]
	v_mfma_f32_16x16x32_bf16 v[96:99], v[168:171], v[184:187], v[96:99]
	v_mfma_f32_16x16x32_bf16 v[84:87], v[160:163], v[208:211], v[84:87]
	v_mfma_f32_16x16x32_bf16 v[80:83], v[168:171], v[208:211], v[80:83]
	v_mfma_f32_16x16x32_bf16 v[68:71], v[160:163], v[216:219], v[68:71]
	v_mfma_f32_16x16x32_bf16 v[64:67], v[168:171], v[216:219], v[64:67]
	v_mfma_f32_16x16x32_bf16 v[116:119], v[164:167], v[180:183], v[116:119]
	v_mfma_f32_16x16x32_bf16 v[112:115], v[172:175], v[180:183], v[112:115]
	v_mfma_f32_16x16x32_bf16 v[100:103], v[164:167], v[188:191], v[100:103]
	v_mfma_f32_16x16x32_bf16 v[96:99], v[172:175], v[188:191], v[96:99]
	v_mfma_f32_16x16x32_bf16 v[84:87], v[164:167], v[212:215], v[84:87]
	v_mfma_f32_16x16x32_bf16 v[80:83], v[172:175], v[212:215], v[80:83]
	v_mfma_f32_16x16x32_bf16 v[68:71], v[164:167], v[220:223], v[68:71]
	v_mfma_f32_16x16x32_bf16 v[64:67], v[172:175], v[220:223], v[64:67]
	s_setprio 0
	s_barrier
	s_add_i32 s58, s58, s44
	v_lshl_add_u64 v[138:139], s[4:5], 0, v[192:193]
	s_mov_b32 m0, s58
	ds_read_b128 v[176:179], v143 offset:16384
	ds_read_b128 v[180:183], v143 offset:17408
	ds_read_b128 v[184:187], v143 offset:18432
	ds_read_b128 v[188:191], v143 offset:19456
	ds_read_b128 v[208:211], v143 offset:20480
	ds_read_b128 v[212:215], v143 offset:21504
	ds_read_b128 v[216:219], v143 offset:22528
	ds_read_b128 v[220:223], v143 offset:23552
	global_load_lds_dwordx4 v[138:139], off
	s_add_i32 m0, s58, 0x2000
	s_add_u32 s58, s4, 0x40000
	v_lshl_add_u64 v[224:225], s[4:5], 0, v[128:129]
	s_addc_u32 s59, s5, 0
	s_add_i32 s60, s60, s44
	global_load_lds_dwordx4 v[224:225], off
	s_mov_b32 m0, s60
	v_lshl_add_u64 v[228:229], s[36:37], 0, v[130:131]
	global_load_lds_dwordx4 v192, s[58:59]
	s_add_i32 m0, s60, 0x2000
	s_nop 0
	global_load_lds_dwordx4 v128, s[58:59]
	v_lshl_add_u64 v[226:227], s[36:37], 0, v[132:133]
	s_mov_b32 m0, s27
	s_nop 0
	global_load_lds_dwordx4 v[226:227], off
	s_mov_b32 m0, s45
	s_nop 0
	global_load_lds_dwordx4 v[228:229], off
	s_waitcnt vmcnt(8)
	s_waitcnt lgkmcnt(0)
	s_barrier
	s_setprio 1
	s_waitcnt lgkmcnt(0)
	v_mfma_f32_16x16x32_bf16 v[60:63], v[144:147], v[176:179], v[60:63]
	v_mfma_f32_16x16x32_bf16 v[56:59], v[152:155], v[176:179], v[56:59]
	v_mfma_f32_16x16x32_bf16 v[44:47], v[144:147], v[184:187], v[44:47]
	v_mfma_f32_16x16x32_bf16 v[40:43], v[152:155], v[184:187], v[40:43]
	v_mfma_f32_16x16x32_bf16 v[28:31], v[144:147], v[208:211], v[28:31]
	v_mfma_f32_16x16x32_bf16 v[24:27], v[152:155], v[208:211], v[24:27]
	v_mfma_f32_16x16x32_bf16 v[12:15], v[144:147], v[216:219], v[12:15]
	v_mfma_f32_16x16x32_bf16 v[8:11], v[152:155], v[216:219], v[8:11]
	v_mfma_f32_16x16x32_bf16 v[60:63], v[148:151], v[180:183], v[60:63]
	v_mfma_f32_16x16x32_bf16 v[56:59], v[156:159], v[180:183], v[56:59]
	v_mfma_f32_16x16x32_bf16 v[44:47], v[148:151], v[188:191], v[44:47]
	v_mfma_f32_16x16x32_bf16 v[40:43], v[156:159], v[188:191], v[40:43]
	v_mfma_f32_16x16x32_bf16 v[28:31], v[148:151], v[212:215], v[28:31]
	v_mfma_f32_16x16x32_bf16 v[24:27], v[156:159], v[212:215], v[24:27]
	v_mfma_f32_16x16x32_bf16 v[12:15], v[148:151], v[220:223], v[12:15]
	v_mfma_f32_16x16x32_bf16 v[8:11], v[156:159], v[220:223], v[8:11]
	s_setprio 0
	s_setprio 1
	v_mfma_f32_16x16x32_bf16 v[52:55], v[160:163], v[176:179], v[52:55]
	v_mfma_f32_16x16x32_bf16 v[48:51], v[168:171], v[176:179], v[48:51]
	v_mfma_f32_16x16x32_bf16 v[36:39], v[160:163], v[184:187], v[36:39]
	v_mfma_f32_16x16x32_bf16 v[32:35], v[168:171], v[184:187], v[32:35]
	v_mfma_f32_16x16x32_bf16 v[20:23], v[160:163], v[208:211], v[20:23]
	v_mfma_f32_16x16x32_bf16 v[16:19], v[168:171], v[208:211], v[16:19]
	v_mfma_f32_16x16x32_bf16 v[4:7], v[160:163], v[216:219], v[4:7]
	v_mfma_f32_16x16x32_bf16 v[0:3], v[168:171], v[216:219], v[0:3]
	v_mfma_f32_16x16x32_bf16 v[52:55], v[164:167], v[180:183], v[52:55]
	v_mfma_f32_16x16x32_bf16 v[48:51], v[172:175], v[180:183], v[48:51]
	v_mfma_f32_16x16x32_bf16 v[36:39], v[164:167], v[188:191], v[36:39]
	v_mfma_f32_16x16x32_bf16 v[32:35], v[172:175], v[188:191], v[32:35]
	v_mfma_f32_16x16x32_bf16 v[20:23], v[164:167], v[212:215], v[20:23]
	v_mfma_f32_16x16x32_bf16 v[16:19], v[172:175], v[212:215], v[16:19]
	v_mfma_f32_16x16x32_bf16 v[4:7], v[164:167], v[220:223], v[4:7]
	v_mfma_f32_16x16x32_bf16 v[0:3], v[172:175], v[220:223], v[0:3]
	s_setprio 0
	s_barrier
	s_add_i32 s58, 0, 0x18000
	s_add_i32 s59, 0, 0x1c000
	v_add_u32_e32 v156, s58, v141
	v_add_u32_e32 v172, s59, v141
	ds_read_b128 v[144:147], v156
	ds_read_b128 v[148:151], v156 offset:1024
	ds_read_b128 v[152:155], v156 offset:2048
	ds_read_b128 v[156:159], v156 offset:3072
	ds_read_b128 v[160:163], v172
	ds_read_b128 v[164:167], v172 offset:1024
	ds_read_b128 v[168:171], v172 offset:2048
	ds_read_b128 v[172:175], v172 offset:3072
	s_add_u32 s36, s36, 0x40000
	s_addc_u32 s37, s37, 0
	s_mov_b32 m0, s46
	ds_read_b128 v[176:179], v143 offset:32768
	ds_read_b128 v[180:183], v143 offset:33792
	ds_read_b128 v[184:187], v143 offset:34816
	ds_read_b128 v[188:191], v143 offset:35840
	ds_read_b128 v[208:211], v143 offset:36864
	ds_read_b128 v[212:215], v143 offset:37888
	ds_read_b128 v[216:219], v143 offset:38912
	ds_read_b128 v[220:223], v143 offset:39936
	global_load_lds_dwordx4 v132, s[36:37]
	v_lshl_add_u64 v[230:231], s[36:37], 0, v[130:131]
	s_mov_b32 m0, s47
	s_nop 0
	global_load_lds_dwordx4 v[230:231], off
	s_waitcnt vmcnt(8)
	s_waitcnt lgkmcnt(0)
	s_barrier
	s_setprio 1
	s_waitcnt lgkmcnt(0)
	v_mfma_f32_16x16x32_bf16 v[124:127], v[144:147], v[176:179], v[124:127]
	v_mfma_f32_16x16x32_bf16 v[120:123], v[152:155], v[176:179], v[120:123]
	v_mfma_f32_16x16x32_bf16 v[108:111], v[144:147], v[184:187], v[108:111]
	v_mfma_f32_16x16x32_bf16 v[104:107], v[152:155], v[184:187], v[104:107]
	v_mfma_f32_16x16x32_bf16 v[92:95], v[144:147], v[208:211], v[92:95]
	v_mfma_f32_16x16x32_bf16 v[88:91], v[152:155], v[208:211], v[88:91]
	v_mfma_f32_16x16x32_bf16 v[76:79], v[144:147], v[216:219], v[76:79]
	v_mfma_f32_16x16x32_bf16 v[72:75], v[152:155], v[216:219], v[72:75]
	v_mfma_f32_16x16x32_bf16 v[124:127], v[148:151], v[180:183], v[124:127]
	v_mfma_f32_16x16x32_bf16 v[120:123], v[156:159], v[180:183], v[120:123]
	v_mfma_f32_16x16x32_bf16 v[108:111], v[148:151], v[188:191], v[108:111]
	v_mfma_f32_16x16x32_bf16 v[104:107], v[156:159], v[188:191], v[104:107]
	v_mfma_f32_16x16x32_bf16 v[92:95], v[148:151], v[212:215], v[92:95]
	v_mfma_f32_16x16x32_bf16 v[88:91], v[156:159], v[212:215], v[88:91]
	v_mfma_f32_16x16x32_bf16 v[76:79], v[148:151], v[220:223], v[76:79]
	v_mfma_f32_16x16x32_bf16 v[72:75], v[156:159], v[220:223], v[72:75]
	s_setprio 0
	s_setprio 1
	v_mfma_f32_16x16x32_bf16 v[116:119], v[160:163], v[176:179], v[116:119]
	v_mfma_f32_16x16x32_bf16 v[112:115], v[168:171], v[176:179], v[112:115]
	v_mfma_f32_16x16x32_bf16 v[100:103], v[160:163], v[184:187], v[100:103]
	v_mfma_f32_16x16x32_bf16 v[96:99], v[168:171], v[184:187], v[96:99]
	v_mfma_f32_16x16x32_bf16 v[84:87], v[160:163], v[208:211], v[84:87]
	v_mfma_f32_16x16x32_bf16 v[80:83], v[168:171], v[208:211], v[80:83]
	v_mfma_f32_16x16x32_bf16 v[68:71], v[160:163], v[216:219], v[68:71]
	v_mfma_f32_16x16x32_bf16 v[64:67], v[168:171], v[216:219], v[64:67]
	v_mfma_f32_16x16x32_bf16 v[116:119], v[164:167], v[180:183], v[116:119]
	v_mfma_f32_16x16x32_bf16 v[112:115], v[172:175], v[180:183], v[112:115]
	v_mfma_f32_16x16x32_bf16 v[100:103], v[164:167], v[188:191], v[100:103]
	v_mfma_f32_16x16x32_bf16 v[96:99], v[172:175], v[188:191], v[96:99]
	v_mfma_f32_16x16x32_bf16 v[84:87], v[164:167], v[212:215], v[84:87]
	v_mfma_f32_16x16x32_bf16 v[80:83], v[172:175], v[212:215], v[80:83]
	v_mfma_f32_16x16x32_bf16 v[68:71], v[164:167], v[220:223], v[68:71]
	v_mfma_f32_16x16x32_bf16 v[64:67], v[172:175], v[220:223], v[64:67]
	s_setprio 0
	s_barrier
	s_add_i32 s36, s58, s44
	v_lshl_add_u64 v[138:139], v[138:139], 0, s[8:9]
	s_mov_b32 m0, s36
	ds_read_b128 v[176:179], v143 offset:49152
	ds_read_b128 v[180:183], v143 offset:50176
	ds_read_b128 v[184:187], v143 offset:51200
	ds_read_b128 v[188:191], v143 offset:52224
	ds_read_b128 v[208:211], v143 offset:53248
	ds_read_b128 v[212:215], v143 offset:54272
	ds_read_b128 v[216:219], v143 offset:55296
	ds_read_b128 v[220:223], v143 offset:56320
	global_load_lds_dwordx4 v[138:139], off
	s_add_i32 m0, s36, 0x2000
	s_add_u32 s4, s4, 0x40080
	v_lshl_add_u64 v[138:139], v[224:225], 0, s[8:9]
	s_addc_u32 s5, s5, 0
	s_add_i32 s36, s59, s44
	global_load_lds_dwordx4 v[138:139], off
	s_mov_b32 m0, s36
	s_nop 0
	global_load_lds_dwordx4 v192, s[4:5]
	s_add_i32 m0, s36, 0x2000
	s_nop 0
	global_load_lds_dwordx4 v128, s[4:5]
	v_lshl_add_u64 v[138:139], v[226:227], 0, s[8:9]
	s_mov_b32 m0, s2
	s_nop 0
	global_load_lds_dwordx4 v[138:139], off
	v_lshl_add_u64 v[138:139], v[228:229], 0, s[8:9]
	s_mov_b32 m0, s48
	s_nop 0
	global_load_lds_dwordx4 v[138:139], off
	s_waitcnt vmcnt(8)
	s_waitcnt lgkmcnt(0)
	s_barrier
	s_setprio 1
	s_waitcnt lgkmcnt(0)
	v_mfma_f32_16x16x32_bf16 v[60:63], v[144:147], v[176:179], v[60:63]
	v_mfma_f32_16x16x32_bf16 v[56:59], v[152:155], v[176:179], v[56:59]
	v_mfma_f32_16x16x32_bf16 v[44:47], v[144:147], v[184:187], v[44:47]
	v_mfma_f32_16x16x32_bf16 v[40:43], v[152:155], v[184:187], v[40:43]
	v_mfma_f32_16x16x32_bf16 v[28:31], v[144:147], v[208:211], v[28:31]
	v_mfma_f32_16x16x32_bf16 v[24:27], v[152:155], v[208:211], v[24:27]
	v_mfma_f32_16x16x32_bf16 v[12:15], v[144:147], v[216:219], v[12:15]
	v_mfma_f32_16x16x32_bf16 v[8:11], v[152:155], v[216:219], v[8:11]
	v_mfma_f32_16x16x32_bf16 v[60:63], v[148:151], v[180:183], v[60:63]
	v_mfma_f32_16x16x32_bf16 v[56:59], v[156:159], v[180:183], v[56:59]
	v_mfma_f32_16x16x32_bf16 v[44:47], v[148:151], v[188:191], v[44:47]
	v_mfma_f32_16x16x32_bf16 v[40:43], v[156:159], v[188:191], v[40:43]
	v_mfma_f32_16x16x32_bf16 v[28:31], v[148:151], v[212:215], v[28:31]
	v_mfma_f32_16x16x32_bf16 v[24:27], v[156:159], v[212:215], v[24:27]
	v_mfma_f32_16x16x32_bf16 v[12:15], v[148:151], v[220:223], v[12:15]
	v_mfma_f32_16x16x32_bf16 v[8:11], v[156:159], v[220:223], v[8:11]
	s_setprio 0
	s_setprio 1
	v_mfma_f32_16x16x32_bf16 v[52:55], v[160:163], v[176:179], v[52:55]
	v_mfma_f32_16x16x32_bf16 v[48:51], v[168:171], v[176:179], v[48:51]
	v_mfma_f32_16x16x32_bf16 v[36:39], v[160:163], v[184:187], v[36:39]
	v_mfma_f32_16x16x32_bf16 v[32:35], v[168:171], v[184:187], v[32:35]
	v_mfma_f32_16x16x32_bf16 v[20:23], v[160:163], v[208:211], v[20:23]
	v_mfma_f32_16x16x32_bf16 v[16:19], v[168:171], v[208:211], v[16:19]
	v_mfma_f32_16x16x32_bf16 v[4:7], v[160:163], v[216:219], v[4:7]
	v_mfma_f32_16x16x32_bf16 v[0:3], v[168:171], v[216:219], v[0:3]
	v_mfma_f32_16x16x32_bf16 v[52:55], v[164:167], v[180:183], v[52:55]
	v_mfma_f32_16x16x32_bf16 v[48:51], v[172:175], v[180:183], v[48:51]
	v_mfma_f32_16x16x32_bf16 v[36:39], v[164:167], v[188:191], v[36:39]
	v_mfma_f32_16x16x32_bf16 v[32:35], v[172:175], v[188:191], v[32:35]
	v_mfma_f32_16x16x32_bf16 v[20:23], v[164:167], v[212:215], v[20:23]
	v_mfma_f32_16x16x32_bf16 v[16:19], v[172:175], v[212:215], v[16:19]
	v_mfma_f32_16x16x32_bf16 v[4:7], v[164:167], v[220:223], v[4:7]
	v_mfma_f32_16x16x32_bf16 v[0:3], v[172:175], v[220:223], v[0:3]
	s_setprio 0
	s_barrier
	s_add_i32 s55, s55, 2
	s_add_u32 s34, s34, 0x100
	s_addc_u32 s35, s35, 0
	s_add_u32 s53, s53, 0x100
	s_addc_u32 s54, s54, 0
	s_cmp_gt_u32 s55, 13
	s_cbranch_scc0 .LBB0_937
	s_and_b64 vcc, exec, s[12:13]
	s_cbranch_vccz .LBB0_940
	s_barrier

.LBB0_1024:
	v_lshl_add_u64 v[8:9], s[4:5], 0, v[192:193]
	v_mov_b32_e32 v129, v193
	v_and_b32_e32 v220, 15, v138
	v_and_b32_e32 v16, 48, v138
	v_lshlrev_b32_e32 v17, 2, v138
	v_lshl_add_u64 v[10:11], s[4:5], 0, v[128:129]
	s_and_b32 s59, s53, 3
	s_lshl_b32 s11, s0, 13
	v_lshl_or_b32 v16, v220, 6, v16
	v_and_b32_e32 v17, 32, v17
	s_add_i32 m0, s36, 0x18000
	v_lshl_add_u64 v[8:9], v[8:9], 0, s[8:9]
	s_lshr_b32 s10, s26, 3
	v_lshl_add_u64 v[12:13], s[16:17], 0, v[192:193]
	s_lshl_b32 s54, s0, 6
	v_bitop3_b32 v18, v16, s11, v17 bitop3:0xde
	s_lshl_b32 s11, s59, 12
	s_waitcnt vmcnt(2)
	s_barrier
	global_load_lds_dwordx4 v[8:9], off
	v_lshl_add_u64 v[8:9], v[10:11], 0, s[8:9]
	s_add_i32 m0, s36, 0x1a000
	s_add_i32 s58, s36, 0x8000
	s_add_i32 s55, s36, 0xa000
	v_lshl_add_u64 v[14:15], s[16:17], 0, v[128:129]
	global_load_lds_dwordx4 v[8:9], off
	v_lshl_add_u64 v[8:9], v[12:13], 0, s[8:9]
	s_mov_b32 m0, s58
	s_add_u32 s26, s4, 0xb0080
	global_load_lds_dwordx4 v[8:9], off
	v_lshl_add_u64 v[8:9], v[14:15], 0, s[8:9]
	s_mov_b32 m0, s55
	s_addc_u32 s27, s5, 0
	global_load_lds_dwordx4 v[8:9], off
	s_add_i32 m0, s36, 0x1c000
	s_nop 0
	global_load_lds_dwordx4 v192, s[26:27]
	s_add_i32 m0, s36, 0x1e000
	v_bitop3_b32 v139, v16, s11, v17 bitop3:0xde
	global_load_lds_dwordx4 v128, s[26:27]
	s_movk_i32 s11, 0xb00
	v_lshrrev_b32_e32 v5, 1, v5
	v_mul_lo_u32 v4, v4, s11
	s_mov_b32 s28, 0xb000
	v_mad_u64_u32 v[4:5], s[26:27], v5, s28, v[4:5]
	v_or_b32_e32 v4, v4, v6
	v_add_lshl_u32 v130, v4, v7, 1
	v_lshrrev_b32_e32 v4, 1, v0
	v_mul_lo_u32 v0, v1, s11
	v_mad_u64_u32 v[0:1], s[26:27], v4, s28, v[0:1]
	v_or_b32_e32 v0, v0, v2
	s_waitcnt vmcnt(6)
	v_add_lshl_u32 v132, v0, v3, 1
	v_mov_b32_e32 v2, v193
	v_mov_b32_e32 v3, v193
	v_mov_b32_e32 v0, v193
	v_mov_b32_e32 v1, v193
	v_add_u32_e32 v140, 0, v18
	v_mov_b64_e32 v[6:7], v[2:3]
	v_mov_b64_e32 v[18:19], v[2:3]
	v_mov_b64_e32 v[22:23], v[2:3]
	v_mov_b64_e32 v[34:35], v[2:3]
	v_mov_b64_e32 v[38:39], v[2:3]
	v_mov_b64_e32 v[50:51], v[2:3]
	v_mov_b64_e32 v[54:55], v[2:3]
	v_mov_b64_e32 v[10:11], v[2:3]
	v_mov_b64_e32 v[14:15], v[2:3]
	v_mov_b64_e32 v[26:27], v[2:3]
	v_mov_b64_e32 v[30:31], v[2:3]
	v_mov_b64_e32 v[42:43], v[2:3]
	v_mov_b64_e32 v[46:47], v[2:3]
	v_mov_b64_e32 v[58:59], v[2:3]
	v_mov_b64_e32 v[62:63], v[2:3]
	v_mov_b64_e32 v[66:67], v[2:3]
	v_mov_b64_e32 v[70:71], v[2:3]
	v_mov_b64_e32 v[82:83], v[2:3]
	v_mov_b64_e32 v[86:87], v[2:3]
	v_mov_b64_e32 v[102:103], v[2:3]
	v_mov_b64_e32 v[106:107], v[2:3]
	v_mov_b64_e32 v[118:119], v[2:3]
	v_mov_b64_e32 v[114:115], v[2:3]
	v_mov_b64_e32 v[74:75], v[2:3]
	v_mov_b64_e32 v[78:79], v[2:3]
	v_mov_b64_e32 v[90:91], v[2:3]
	v_mov_b64_e32 v[94:95], v[2:3]
	v_mov_b64_e32 v[122:123], v[2:3]
	v_mov_b64_e32 v[126:127], v[2:3]
	v_mov_b64_e32 v[110:111], v[2:3]
	v_mov_b64_e32 v[98:99], v[2:3]
	s_sext_i32_i8 s10, s10
	v_or_b32_e32 v212, s54, v220
	v_mov_b32_e32 v131, v193
	v_mov_b32_e32 v133, v193
	s_mov_b32 s11, 0
	v_mov_b64_e32 v[4:5], v[0:1]
	v_mov_b64_e32 v[16:17], v[0:1]
	v_mov_b64_e32 v[20:21], v[0:1]
	v_mov_b64_e32 v[32:33], v[0:1]
	v_mov_b64_e32 v[36:37], v[0:1]
	v_mov_b64_e32 v[48:49], v[0:1]
	v_mov_b64_e32 v[52:53], v[0:1]
	v_mov_b64_e32 v[8:9], v[0:1]
	v_mov_b64_e32 v[12:13], v[0:1]
	v_mov_b64_e32 v[24:25], v[0:1]
	v_mov_b64_e32 v[28:29], v[0:1]
	v_mov_b64_e32 v[40:41], v[0:1]
	v_mov_b64_e32 v[44:45], v[0:1]
	v_mov_b64_e32 v[56:57], v[0:1]
	v_mov_b64_e32 v[60:61], v[0:1]
	v_mov_b64_e32 v[64:65], v[0:1]
	v_mov_b64_e32 v[68:69], v[0:1]
	v_mov_b64_e32 v[80:81], v[0:1]
	v_mov_b64_e32 v[84:85], v[0:1]
	v_mov_b64_e32 v[100:101], v[0:1]
	v_mov_b64_e32 v[104:105], v[0:1]
	v_mov_b64_e32 v[116:117], v[0:1]
	v_mov_b64_e32 v[112:113], v[0:1]
	v_mov_b64_e32 v[72:73], v[0:1]
	v_mov_b64_e32 v[76:77], v[0:1]
	v_mov_b64_e32 v[88:89], v[0:1]
	v_mov_b64_e32 v[92:93], v[0:1]
	v_mov_b64_e32 v[120:121], v[0:1]
	v_mov_b64_e32 v[124:125], v[0:1]
	v_mov_b64_e32 v[108:109], v[0:1]
	v_mov_b64_e32 v[96:97], v[0:1]
	s_barrier

.LBB0_1036:
	s_add_u32 s30, s16, s4
	s_addc_u32 s31, s17, s5
	s_add_u32 s30, s30, 0x100
	s_addc_u32 s31, s31, 0
	s_add_u32 s66, s44, s4
	s_addc_u32 s67, s45, s5
	s_add_i32 s70, 0, 0x10000
	s_cmpk_eq_i32 s4, 0x1500
	s_cselect_b32 s35, s29, s31
	s_cselect_b32 s34, s28, s30
	v_add_u32_e32 v141, s70, v139
	s_cselect_b32 s31, s27, s67
	s_cselect_b32 s30, s26, s66
	s_add_i32 s72, 0, 0x14000
	ds_read_b128 v[142:145], v141
	ds_read_b128 v[146:149], v141 offset:1024
	ds_read_b128 v[150:153], v141 offset:2048
	ds_read_b128 v[154:157], v141 offset:3072
	v_add_u32_e32 v141, s72, v139
	ds_read_b128 v[158:161], v141
	ds_read_b128 v[162:165], v141 offset:1024
	ds_read_b128 v[166:169], v141 offset:2048
	ds_read_b128 v[170:173], v141 offset:3072
	s_add_i32 s66, s36, 0xc000
	v_lshl_add_u64 v[190:191], v[134:135], 0, s[4:5]
	s_mov_b32 m0, s66
	s_add_i32 s67, s36, 0xe000
	ds_read_b128 v[174:177], v140
	ds_read_b128 v[178:181], v140 offset:1024
	ds_read_b128 v[182:185], v140 offset:2048
	ds_read_b128 v[186:189], v140 offset:3072
	ds_read_b128 v[208:211], v140 offset:4096
	ds_read_b128 v[214:217], v140 offset:5120
	ds_read_b128 v[222:225], v140 offset:6144
	ds_read_b128 v[226:229], v140 offset:7168
	global_load_lds_dwordx4 v[190:191], off
	v_lshl_add_u64 v[190:191], v[136:137], 0, s[4:5]
	s_mov_b32 m0, s67
	s_nop 0
	global_load_lds_dwordx4 v[190:191], off
	s_waitcnt vmcnt(8)
	s_waitcnt lgkmcnt(0)
	s_barrier
	s_setprio 1
	s_waitcnt lgkmcnt(0)
	v_mfma_f32_16x16x32_bf16 v[96:99], v[142:145], v[174:177], v[96:99]
	v_mfma_f32_16x16x32_bf16 v[108:111], v[150:153], v[174:177], v[108:111]
	v_mfma_f32_16x16x32_bf16 v[124:127], v[142:145], v[182:185], v[124:127]
	v_mfma_f32_16x16x32_bf16 v[120:123], v[150:153], v[182:185], v[120:123]
	v_mfma_f32_16x16x32_bf16 v[92:95], v[142:145], v[208:211], v[92:95]
	v_mfma_f32_16x16x32_bf16 v[88:91], v[150:153], v[208:211], v[88:91]
	v_mfma_f32_16x16x32_bf16 v[76:79], v[142:145], v[222:225], v[76:79]
	v_mfma_f32_16x16x32_bf16 v[72:75], v[150:153], v[222:225], v[72:75]
	v_mfma_f32_16x16x32_bf16 v[96:99], v[146:149], v[178:181], v[96:99]
	v_mfma_f32_16x16x32_bf16 v[108:111], v[154:157], v[178:181], v[108:111]
	v_mfma_f32_16x16x32_bf16 v[124:127], v[146:149], v[186:189], v[124:127]
	v_mfma_f32_16x16x32_bf16 v[120:123], v[154:157], v[186:189], v[120:123]
	v_mfma_f32_16x16x32_bf16 v[92:95], v[146:149], v[214:217], v[92:95]
	v_mfma_f32_16x16x32_bf16 v[88:91], v[154:157], v[214:217], v[88:91]
	v_mfma_f32_16x16x32_bf16 v[76:79], v[146:149], v[226:229], v[76:79]
	v_mfma_f32_16x16x32_bf16 v[72:75], v[154:157], v[226:229], v[72:75]
	s_setprio 0
	s_setprio 1
	v_mfma_f32_16x16x32_bf16 v[112:115], v[158:161], v[174:177], v[112:115]
	v_mfma_f32_16x16x32_bf16 v[116:119], v[166:169], v[174:177], v[116:119]
	v_mfma_f32_16x16x32_bf16 v[104:107], v[158:161], v[182:185], v[104:107]
	v_mfma_f32_16x16x32_bf16 v[100:103], v[166:169], v[182:185], v[100:103]
	v_mfma_f32_16x16x32_bf16 v[84:87], v[158:161], v[208:211], v[84:87]
	v_mfma_f32_16x16x32_bf16 v[80:83], v[166:169], v[208:211], v[80:83]
	v_mfma_f32_16x16x32_bf16 v[68:71], v[158:161], v[222:225], v[68:71]
	v_mfma_f32_16x16x32_bf16 v[64:67], v[166:169], v[222:225], v[64:67]
	v_mfma_f32_16x16x32_bf16 v[112:115], v[162:165], v[178:181], v[112:115]
	v_mfma_f32_16x16x32_bf16 v[116:119], v[170:173], v[178:181], v[116:119]
	v_mfma_f32_16x16x32_bf16 v[104:107], v[162:165], v[186:189], v[104:107]
	v_mfma_f32_16x16x32_bf16 v[100:103], v[170:173], v[186:189], v[100:103]
	v_mfma_f32_16x16x32_bf16 v[84:87], v[162:165], v[214:217], v[84:87]
	v_mfma_f32_16x16x32_bf16 v[80:83], v[170:173], v[214:217], v[80:83]
	v_mfma_f32_16x16x32_bf16 v[68:71], v[162:165], v[226:229], v[68:71]
	v_mfma_f32_16x16x32_bf16 v[64:67], v[170:173], v[226:229], v[64:67]
	s_setprio 0
	s_barrier
	s_add_i32 s70, s70, s60
	v_lshl_add_u64 v[190:191], s[30:31], 0, v[192:193]
	s_mov_b32 m0, s70
	ds_read_b128 v[174:177], v140 offset:16384
	ds_read_b128 v[178:181], v140 offset:17408
	ds_read_b128 v[182:185], v140 offset:18432
	ds_read_b128 v[186:189], v140 offset:19456
	ds_read_b128 v[208:211], v140 offset:20480
	ds_read_b128 v[214:217], v140 offset:21504
	ds_read_b128 v[222:225], v140 offset:22528
	ds_read_b128 v[226:229], v140 offset:23552
	global_load_lds_dwordx4 v[190:191], off
	s_add_i32 m0, s70, 0x2000
	s_add_u32 s70, s30, 0xb0000
	v_lshl_add_u64 v[218:219], s[30:31], 0, v[128:129]
	s_addc_u32 s71, s31, 0
	s_add_i32 s72, s72, s60
	global_load_lds_dwordx4 v[218:219], off
	s_mov_b32 m0, s72
	v_lshl_add_u64 v[232:233], s[34:35], 0, v[128:129]
	global_load_lds_dwordx4 v192, s[70:71]
	s_add_i32 m0, s72, 0x2000
	s_nop 0
	global_load_lds_dwordx4 v128, s[70:71]
	v_lshl_add_u64 v[230:231], s[34:35], 0, v[192:193]
	s_mov_b32 m0, s36
	s_nop 0
	global_load_lds_dwordx4 v[230:231], off
	s_mov_b32 m0, s46
	s_nop 0
	global_load_lds_dwordx4 v[232:233], off
	s_waitcnt vmcnt(8)
	s_waitcnt lgkmcnt(0)
	s_barrier
	s_setprio 1
	s_waitcnt lgkmcnt(0)
	v_mfma_f32_16x16x32_bf16 v[60:63], v[142:145], v[174:177], v[60:63]
	v_mfma_f32_16x16x32_bf16 v[56:59], v[150:153], v[174:177], v[56:59]
	v_mfma_f32_16x16x32_bf16 v[44:47], v[142:145], v[182:185], v[44:47]
	v_mfma_f32_16x16x32_bf16 v[40:43], v[150:153], v[182:185], v[40:43]
	v_mfma_f32_16x16x32_bf16 v[28:31], v[142:145], v[208:211], v[28:31]
	v_mfma_f32_16x16x32_bf16 v[24:27], v[150:153], v[208:211], v[24:27]
	v_mfma_f32_16x16x32_bf16 v[12:15], v[142:145], v[222:225], v[12:15]
	v_mfma_f32_16x16x32_bf16 v[8:11], v[150:153], v[222:225], v[8:11]
	v_mfma_f32_16x16x32_bf16 v[60:63], v[146:149], v[178:181], v[60:63]
	v_mfma_f32_16x16x32_bf16 v[56:59], v[154:157], v[178:181], v[56:59]
	v_mfma_f32_16x16x32_bf16 v[44:47], v[146:149], v[186:189], v[44:47]
	v_mfma_f32_16x16x32_bf16 v[40:43], v[154:157], v[186:189], v[40:43]
	v_mfma_f32_16x16x32_bf16 v[28:31], v[146:149], v[214:217], v[28:31]
	v_mfma_f32_16x16x32_bf16 v[24:27], v[154:157], v[214:217], v[24:27]
	v_mfma_f32_16x16x32_bf16 v[12:15], v[146:149], v[226:229], v[12:15]
	v_mfma_f32_16x16x32_bf16 v[8:11], v[154:157], v[226:229], v[8:11]
	s_setprio 0
	s_setprio 1
	v_mfma_f32_16x16x32_bf16 v[52:55], v[158:161], v[174:177], v[52:55]
	v_mfma_f32_16x16x32_bf16 v[48:51], v[166:169], v[174:177], v[48:51]
	v_mfma_f32_16x16x32_bf16 v[36:39], v[158:161], v[182:185], v[36:39]
	v_mfma_f32_16x16x32_bf16 v[32:35], v[166:169], v[182:185], v[32:35]
	v_mfma_f32_16x16x32_bf16 v[20:23], v[158:161], v[208:211], v[20:23]
	v_mfma_f32_16x16x32_bf16 v[16:19], v[166:169], v[208:211], v[16:19]
	v_mfma_f32_16x16x32_bf16 v[4:7], v[158:161], v[222:225], v[4:7]
	v_mfma_f32_16x16x32_bf16 v[0:3], v[166:169], v[222:225], v[0:3]
	v_mfma_f32_16x16x32_bf16 v[52:55], v[162:165], v[178:181], v[52:55]
	v_mfma_f32_16x16x32_bf16 v[48:51], v[170:173], v[178:181], v[48:51]
	v_mfma_f32_16x16x32_bf16 v[36:39], v[162:165], v[186:189], v[36:39]
	v_mfma_f32_16x16x32_bf16 v[32:35], v[170:173], v[186:189], v[32:35]
	v_mfma_f32_16x16x32_bf16 v[20:23], v[162:165], v[214:217], v[20:23]
	v_mfma_f32_16x16x32_bf16 v[16:19], v[170:173], v[214:217], v[16:19]
	v_mfma_f32_16x16x32_bf16 v[4:7], v[162:165], v[226:229], v[4:7]
	v_mfma_f32_16x16x32_bf16 v[0:3], v[170:173], v[226:229], v[0:3]
	s_setprio 0
	s_barrier
	s_add_i32 s70, 0, 0x18000
	v_add_u32_e32 v141, s70, v139
	s_add_i32 s71, 0, 0x1c000
	ds_read_b128 v[142:145], v141
	ds_read_b128 v[146:149], v141 offset:1024
	ds_read_b128 v[150:153], v141 offset:2048
	ds_read_b128 v[154:157], v141 offset:3072
	v_add_u32_e32 v141, s71, v139
	ds_read_b128 v[158:161], v141
	ds_read_b128 v[162:165], v141 offset:1024
	ds_read_b128 v[166:169], v141 offset:2048
	ds_read_b128 v[170:173], v141 offset:3072
	s_add_u32 s34, s34, 0xb0000
	s_addc_u32 s35, s35, 0
	s_mov_b32 m0, s47
	ds_read_b128 v[174:177], v140 offset:32768
	ds_read_b128 v[178:181], v140 offset:33792
	ds_read_b128 v[182:185], v140 offset:34816
	ds_read_b128 v[186:189], v140 offset:35840
	ds_read_b128 v[208:211], v140 offset:36864
	ds_read_b128 v[214:217], v140 offset:37888
	ds_read_b128 v[222:225], v140 offset:38912
	ds_read_b128 v[226:229], v140 offset:39936
	global_load_lds_dwordx4 v192, s[34:35]
	v_lshl_add_u64 v[234:235], s[34:35], 0, v[128:129]
	s_mov_b32 m0, s52
	s_nop 0
	global_load_lds_dwordx4 v[234:235], off
	s_waitcnt vmcnt(8)
	s_waitcnt lgkmcnt(0)
	s_barrier
	s_setprio 1
	s_waitcnt lgkmcnt(0)
	v_mfma_f32_16x16x32_bf16 v[96:99], v[142:145], v[174:177], v[96:99]
	v_mfma_f32_16x16x32_bf16 v[108:111], v[150:153], v[174:177], v[108:111]
	v_mfma_f32_16x16x32_bf16 v[124:127], v[142:145], v[182:185], v[124:127]
	v_mfma_f32_16x16x32_bf16 v[120:123], v[150:153], v[182:185], v[120:123]
	v_mfma_f32_16x16x32_bf16 v[92:95], v[142:145], v[208:211], v[92:95]
	v_mfma_f32_16x16x32_bf16 v[88:91], v[150:153], v[208:211], v[88:91]
	v_mfma_f32_16x16x32_bf16 v[76:79], v[142:145], v[222:225], v[76:79]
	v_mfma_f32_16x16x32_bf16 v[72:75], v[150:153], v[222:225], v[72:75]
	v_mfma_f32_16x16x32_bf16 v[96:99], v[146:149], v[178:181], v[96:99]
	v_mfma_f32_16x16x32_bf16 v[108:111], v[154:157], v[178:181], v[108:111]
	v_mfma_f32_16x16x32_bf16 v[124:127], v[146:149], v[186:189], v[124:127]
	v_mfma_f32_16x16x32_bf16 v[120:123], v[154:157], v[186:189], v[120:123]
	v_mfma_f32_16x16x32_bf16 v[92:95], v[146:149], v[214:217], v[92:95]
	v_mfma_f32_16x16x32_bf16 v[88:91], v[154:157], v[214:217], v[88:91]
	v_mfma_f32_16x16x32_bf16 v[76:79], v[146:149], v[226:229], v[76:79]
	v_mfma_f32_16x16x32_bf16 v[72:75], v[154:157], v[226:229], v[72:75]
	s_setprio 0
	s_setprio 1
	v_mfma_f32_16x16x32_bf16 v[112:115], v[158:161], v[174:177], v[112:115]
	v_mfma_f32_16x16x32_bf16 v[116:119], v[166:169], v[174:177], v[116:119]
	v_mfma_f32_16x16x32_bf16 v[104:107], v[158:161], v[182:185], v[104:107]
	v_mfma_f32_16x16x32_bf16 v[100:103], v[166:169], v[182:185], v[100:103]
	v_mfma_f32_16x16x32_bf16 v[84:87], v[158:161], v[208:211], v[84:87]
	v_mfma_f32_16x16x32_bf16 v[80:83], v[166:169], v[208:211], v[80:83]
	v_mfma_f32_16x16x32_bf16 v[68:71], v[158:161], v[222:225], v[68:71]
	v_mfma_f32_16x16x32_bf16 v[64:67], v[166:169], v[222:225], v[64:67]
	v_mfma_f32_16x16x32_bf16 v[112:115], v[162:165], v[178:181], v[112:115]
	v_mfma_f32_16x16x32_bf16 v[116:119], v[170:173], v[178:181], v[116:119]
	v_mfma_f32_16x16x32_bf16 v[104:107], v[162:165], v[186:189], v[104:107]
	v_mfma_f32_16x16x32_bf16 v[100:103], v[170:173], v[186:189], v[100:103]
	v_mfma_f32_16x16x32_bf16 v[84:87], v[162:165], v[214:217], v[84:87]
	v_mfma_f32_16x16x32_bf16 v[80:83], v[170:173], v[214:217], v[80:83]
	v_mfma_f32_16x16x32_bf16 v[68:71], v[162:165], v[226:229], v[68:71]
	v_mfma_f32_16x16x32_bf16 v[64:67], v[170:173], v[226:229], v[64:67]
	s_setprio 0
	s_barrier
	s_add_i32 s34, s70, s60
	v_lshl_add_u64 v[190:191], v[190:191], 0, s[8:9]
	s_mov_b32 m0, s34
	ds_read_b128 v[174:177], v140 offset:49152
	ds_read_b128 v[178:181], v140 offset:50176
	ds_read_b128 v[182:185], v140 offset:51200
	ds_read_b128 v[186:189], v140 offset:52224
	ds_read_b128 v[208:211], v140 offset:53248
	ds_read_b128 v[214:217], v140 offset:54272
	ds_read_b128 v[222:225], v140 offset:55296
	ds_read_b128 v[226:229], v140 offset:56320
	global_load_lds_dwordx4 v[190:191], off
	s_add_i32 m0, s34, 0x2000
	s_add_u32 s30, s30, 0xb0080
	v_lshl_add_u64 v[190:191], v[218:219], 0, s[8:9]
	s_addc_u32 s31, s31, 0
	s_add_i32 s34, s71, s60
	global_load_lds_dwordx4 v[190:191], off
	s_mov_b32 m0, s34
	s_nop 0
	global_load_lds_dwordx4 v192, s[30:31]
	s_add_i32 m0, s34, 0x2000
	s_nop 0
	global_load_lds_dwordx4 v128, s[30:31]
	v_lshl_add_u64 v[190:191], v[230:231], 0, s[8:9]
	s_mov_b32 m0, s58
	s_nop 0
	global_load_lds_dwordx4 v[190:191], off
	v_lshl_add_u64 v[190:191], v[232:233], 0, s[8:9]
	s_mov_b32 m0, s55
	s_nop 0
	global_load_lds_dwordx4 v[190:191], off
	s_waitcnt vmcnt(8)
	s_waitcnt lgkmcnt(0)
	s_barrier
	s_setprio 1
	s_waitcnt lgkmcnt(0)
	v_mfma_f32_16x16x32_bf16 v[60:63], v[142:145], v[174:177], v[60:63]
	v_mfma_f32_16x16x32_bf16 v[56:59], v[150:153], v[174:177], v[56:59]
	v_mfma_f32_16x16x32_bf16 v[44:47], v[142:145], v[182:185], v[44:47]
	v_mfma_f32_16x16x32_bf16 v[40:43], v[150:153], v[182:185], v[40:43]
	v_mfma_f32_16x16x32_bf16 v[28:31], v[142:145], v[208:211], v[28:31]
	v_mfma_f32_16x16x32_bf16 v[24:27], v[150:153], v[208:211], v[24:27]
	v_mfma_f32_16x16x32_bf16 v[12:15], v[142:145], v[222:225], v[12:15]
	v_mfma_f32_16x16x32_bf16 v[8:11], v[150:153], v[222:225], v[8:11]
	v_mfma_f32_16x16x32_bf16 v[60:63], v[146:149], v[178:181], v[60:63]
	v_mfma_f32_16x16x32_bf16 v[56:59], v[154:157], v[178:181], v[56:59]
	v_mfma_f32_16x16x32_bf16 v[44:47], v[146:149], v[186:189], v[44:47]
	v_mfma_f32_16x16x32_bf16 v[40:43], v[154:157], v[186:189], v[40:43]
	v_mfma_f32_16x16x32_bf16 v[28:31], v[146:149], v[214:217], v[28:31]
	v_mfma_f32_16x16x32_bf16 v[24:27], v[154:157], v[214:217], v[24:27]
	v_mfma_f32_16x16x32_bf16 v[12:15], v[146:149], v[226:229], v[12:15]
	v_mfma_f32_16x16x32_bf16 v[8:11], v[154:157], v[226:229], v[8:11]
	s_setprio 0
	s_setprio 1
	v_mfma_f32_16x16x32_bf16 v[52:55], v[158:161], v[174:177], v[52:55]
	v_mfma_f32_16x16x32_bf16 v[48:51], v[166:169], v[174:177], v[48:51]
	v_mfma_f32_16x16x32_bf16 v[36:39], v[158:161], v[182:185], v[36:39]
	v_mfma_f32_16x16x32_bf16 v[32:35], v[166:169], v[182:185], v[32:35]
	v_mfma_f32_16x16x32_bf16 v[20:23], v[158:161], v[208:211], v[20:23]
	v_mfma_f32_16x16x32_bf16 v[16:19], v[166:169], v[208:211], v[16:19]
	v_mfma_f32_16x16x32_bf16 v[4:7], v[158:161], v[222:225], v[4:7]
	v_mfma_f32_16x16x32_bf16 v[0:3], v[166:169], v[222:225], v[0:3]
	v_mfma_f32_16x16x32_bf16 v[52:55], v[162:165], v[178:181], v[52:55]
	v_mfma_f32_16x16x32_bf16 v[48:51], v[170:173], v[178:181], v[48:51]
	v_mfma_f32_16x16x32_bf16 v[36:39], v[162:165], v[186:189], v[36:39]
	v_mfma_f32_16x16x32_bf16 v[32:35], v[170:173], v[186:189], v[32:35]
	v_mfma_f32_16x16x32_bf16 v[20:23], v[162:165], v[214:217], v[20:23]
	v_mfma_f32_16x16x32_bf16 v[16:19], v[170:173], v[214:217], v[16:19]
	v_mfma_f32_16x16x32_bf16 v[4:7], v[162:165], v[226:229], v[4:7]
	v_mfma_f32_16x16x32_bf16 v[0:3], v[170:173], v[226:229], v[0:3]
	s_setprio 0
	s_barrier
	s_add_i32 s69, s69, 2
	s_add_u32 s4, s4, 0x100
	s_addc_u32 s5, s5, 0
	s_cmp_gt_u32 s69, 41
	s_cbranch_scc0 .LBB0_1036
	s_add_u32 s4, s44, 0xffffff00
	s_addc_u32 s5, s45, -1
	s_and_b64 vcc, exec, s[42:43]
	s_cbranch_vccnz .LBB0_1039
	v_mov_b32_e32 v0, 0
	s_mov_b32 s10, s92
	s_mov_b32 s1, s93
	s_mov_b64 s[16:17], s[28:29]
	s_mov_b32 s11, s68
	v_mov_b32_e32 v1, v0
	v_mov_b32_e32 v2, v0
	v_mov_b32_e32 v3, v0
	v_mov_b32_e32 v4, v0
	v_mov_b32_e32 v5, v0
	v_mov_b32_e32 v6, v0
	v_mov_b32_e32 v7, v0
	v_mov_b32_e32 v16, v0
	v_mov_b32_e32 v17, v0
	v_mov_b32_e32 v18, v0
	v_mov_b32_e32 v19, v0
	v_mov_b32_e32 v20, v0
	v_mov_b32_e32 v21, v0
	v_mov_b32_e32 v22, v0
	v_mov_b32_e32 v23, v0
	v_mov_b32_e32 v32, v0
	v_mov_b32_e32 v33, v0
	v_mov_b32_e32 v34, v0
	v_mov_b32_e32 v35, v0
	v_mov_b32_e32 v36, v0
	v_mov_b32_e32 v37, v0
	v_mov_b32_e32 v38, v0
	v_mov_b32_e32 v39, v0
	v_mov_b32_e32 v48, v0
	v_mov_b32_e32 v49, v0
	v_mov_b32_e32 v50, v0
	v_mov_b32_e32 v51, v0
	v_mov_b32_e32 v52, v0
	v_mov_b32_e32 v53, v0
	v_mov_b32_e32 v54, v0
	v_mov_b32_e32 v55, v0
	v_mov_b32_e32 v8, v0
	v_mov_b32_e32 v9, v0
	v_mov_b32_e32 v10, v0
	v_mov_b32_e32 v11, v0
	v_mov_b32_e32 v12, v0
	v_mov_b32_e32 v13, v0
	v_mov_b32_e32 v14, v0
	v_mov_b32_e32 v15, v0
	v_mov_b32_e32 v24, v0
	v_mov_b32_e32 v25, v0
	v_mov_b32_e32 v26, v0
	v_mov_b32_e32 v27, v0
	v_mov_b32_e32 v28, v0
	v_mov_b32_e32 v29, v0
	v_mov_b32_e32 v30, v0
	v_mov_b32_e32 v31, v0
	v_mov_b32_e32 v40, v0
	v_mov_b32_e32 v41, v0
	v_mov_b32_e32 v42, v0
	v_mov_b32_e32 v43, v0
	v_mov_b32_e32 v44, v0
	v_mov_b32_e32 v45, v0
	v_mov_b32_e32 v46, v0
	v_mov_b32_e32 v47, v0
	v_mov_b32_e32 v56, v0
	v_mov_b32_e32 v57, v0
	v_mov_b32_e32 v58, v0
	v_mov_b32_e32 v59, v0
	v_mov_b32_e32 v60, v0
	v_mov_b32_e32 v61, v0
	v_mov_b32_e32 v62, v0
	v_mov_b32_e32 v63, v0
	v_mov_b32_e32 v64, v0
	v_mov_b32_e32 v65, v0
	v_mov_b32_e32 v66, v0
	v_mov_b32_e32 v67, v0
	v_mov_b32_e32 v68, v0
	v_mov_b32_e32 v69, v0
	v_mov_b32_e32 v70, v0
	v_mov_b32_e32 v71, v0
	v_mov_b32_e32 v80, v0
	v_mov_b32_e32 v81, v0
	v_mov_b32_e32 v82, v0
	v_mov_b32_e32 v83, v0
	v_mov_b32_e32 v84, v0
	v_mov_b32_e32 v85, v0
	v_mov_b32_e32 v86, v0
	v_mov_b32_e32 v87, v0
	v_mov_b32_e32 v100, v0
	v_mov_b32_e32 v101, v0
	v_mov_b32_e32 v102, v0
	v_mov_b32_e32 v103, v0
	v_mov_b32_e32 v104, v0
	v_mov_b32_e32 v105, v0
	v_mov_b32_e32 v106, v0
	v_mov_b32_e32 v107, v0
	v_mov_b32_e32 v116, v0
	v_mov_b32_e32 v117, v0
	v_mov_b32_e32 v118, v0
	v_mov_b32_e32 v119, v0
	v_mov_b32_e32 v112, v0
	v_mov_b32_e32 v113, v0
	v_mov_b32_e32 v114, v0
	v_mov_b32_e32 v115, v0
	v_mov_b32_e32 v72, v0
	v_mov_b32_e32 v73, v0
	v_mov_b32_e32 v74, v0
	v_mov_b32_e32 v75, v0
	v_mov_b32_e32 v76, v0
	v_mov_b32_e32 v77, v0
	v_mov_b32_e32 v78, v0
	v_mov_b32_e32 v79, v0
	v_mov_b32_e32 v88, v0
	v_mov_b32_e32 v89, v0
	v_mov_b32_e32 v90, v0
	v_mov_b32_e32 v91, v0
	v_mov_b32_e32 v92, v0
	v_mov_b32_e32 v93, v0
	v_mov_b32_e32 v94, v0
	v_mov_b32_e32 v95, v0
	v_mov_b32_e32 v120, v0
	v_mov_b32_e32 v121, v0
	v_mov_b32_e32 v122, v0
	v_mov_b32_e32 v123, v0
	v_mov_b32_e32 v124, v0
	v_mov_b32_e32 v125, v0
	v_mov_b32_e32 v126, v0
	v_mov_b32_e32 v127, v0
	v_mov_b32_e32 v108, v0
	v_mov_b32_e32 v109, v0
	v_mov_b32_e32 v110, v0
	v_mov_b32_e32 v111, v0
	v_mov_b32_e32 v96, v0
	v_mov_b32_e32 v97, v0
	v_mov_b32_e32 v98, v0
	v_mov_b32_e32 v99, v0
	s_branch .LBB0_1040
